# v9 + open barrier of each MFMA segment placed before the first MFMA
# speedup vs baseline: 1.0068x; 1.0068x over previous
.LBB0_642:
	ds_read_b128 v[148:151], v139
	ds_read_b128 v[152:155], v139 offset:1024
	ds_read_b128 v[156:159], v139 offset:2048
	ds_read_b128 v[160:163], v139 offset:3072
	ds_read_b128 v[164:167], v140
	ds_read_b128 v[168:171], v140 offset:1024
	ds_read_b128 v[172:175], v140 offset:2048
	ds_read_b128 v[176:179], v140 offset:3072
	s_add_i32 s18, s71, 0xffe80080
	s_cmp_eq_u32 s58, s73
	s_cselect_b32 s74, s69, s18
	s_cselect_b32 s76, s70, s72
	s_or_b32 s75, s74, 0x80
	s_add_i32 s18, s71, 0xfff80000
	s_mov_b32 m0, s59
	ds_read_b128 v[180:183], v141
	ds_read_b128 v[184:187], v141 offset:1024
	ds_read_b128 v[188:191], v141 offset:2048
	ds_read_b128 v[192:195], v141 offset:3072
	ds_read_b128 v[196:199], v141 offset:4096
	ds_read_b128 v[200:203], v141 offset:5120
	ds_read_b128 v[204:207], v141 offset:6144
	ds_read_b128 v[208:211], v141 offset:7168
	buffer_load_dwordx4 v137, s[12:15], s18 offen lds
	s_mov_b32 m0, s60
	s_nop 0
	buffer_load_dwordx4 v137, s[12:15], s71 offen lds
	s_waitcnt vmcnt(8)
	s_waitcnt lgkmcnt(0)
	s_setprio 1
	s_barrier
	v_mfma_f32_16x16x32_bf16 v[118:121], v[148:151], v[180:183], v[118:121]
	v_mfma_f32_16x16x32_bf16 v[118:121], v[152:155], v[184:187], v[118:121]
	v_mfma_f32_16x16x32_bf16 v[114:117], v[156:159], v[180:183], v[114:117]
	v_mfma_f32_16x16x32_bf16 v[114:117], v[160:163], v[184:187], v[114:117]
	v_mfma_f32_16x16x32_bf16 v[110:113], v[148:151], v[188:191], v[110:113]
	v_mfma_f32_16x16x32_bf16 v[110:113], v[152:155], v[192:195], v[110:113]
	v_mfma_f32_16x16x32_bf16 v[102:105], v[156:159], v[188:191], v[102:105]
	v_mfma_f32_16x16x32_bf16 v[102:105], v[160:163], v[192:195], v[102:105]
	v_mfma_f32_16x16x32_bf16 v[94:97], v[148:151], v[196:199], v[94:97]
	v_mfma_f32_16x16x32_bf16 v[94:97], v[152:155], v[200:203], v[94:97]
	v_mfma_f32_16x16x32_bf16 v[86:89], v[156:159], v[196:199], v[86:89]
	v_mfma_f32_16x16x32_bf16 v[86:89], v[160:163], v[200:203], v[86:89]
	v_mfma_f32_16x16x32_bf16 v[78:81], v[148:151], v[204:207], v[78:81]
	v_mfma_f32_16x16x32_bf16 v[78:81], v[152:155], v[208:211], v[78:81]
	v_mfma_f32_16x16x32_bf16 v[66:69], v[156:159], v[204:207], v[66:69]
	v_mfma_f32_16x16x32_bf16 v[66:69], v[160:163], v[208:211], v[66:69]
	v_mfma_f32_16x16x32_bf16 v[126:129], v[164:167], v[180:183], v[126:129]
	v_mfma_f32_16x16x32_bf16 v[126:129], v[168:171], v[184:187], v[126:129]
	v_mfma_f32_16x16x32_bf16 v[122:125], v[172:175], v[180:183], v[122:125]
	v_mfma_f32_16x16x32_bf16 v[122:125], v[176:179], v[184:187], v[122:125]
	v_mfma_f32_16x16x32_bf16 v[106:109], v[164:167], v[188:191], v[106:109]
	v_mfma_f32_16x16x32_bf16 v[106:109], v[168:171], v[192:195], v[106:109]
	v_mfma_f32_16x16x32_bf16 v[98:101], v[172:175], v[188:191], v[98:101]
	v_mfma_f32_16x16x32_bf16 v[98:101], v[176:179], v[192:195], v[98:101]
	v_mfma_f32_16x16x32_bf16 v[90:93], v[164:167], v[196:199], v[90:93]
	v_mfma_f32_16x16x32_bf16 v[90:93], v[168:171], v[200:203], v[90:93]
	v_mfma_f32_16x16x32_bf16 v[82:85], v[172:175], v[196:199], v[82:85]
	v_mfma_f32_16x16x32_bf16 v[82:85], v[176:179], v[200:203], v[82:85]
	v_mfma_f32_16x16x32_bf16 v[74:77], v[164:167], v[204:207], v[74:77]
	v_mfma_f32_16x16x32_bf16 v[74:77], v[168:171], v[208:211], v[74:77]
	v_mfma_f32_16x16x32_bf16 v[70:73], v[172:175], v[204:207], v[70:73]
	v_mfma_f32_16x16x32_bf16 v[70:73], v[176:179], v[208:211], v[70:73]
	s_setprio 0
	s_barrier
	s_mov_b32 m0, s30
	s_mov_b32 s18, s14
	s_mov_b32 s19, s15
	ds_read_b128 v[180:183], v141 offset:16384
	ds_read_b128 v[184:187], v141 offset:17408
	ds_read_b128 v[188:191], v141 offset:18432
	ds_read_b128 v[192:195], v141 offset:19456
	ds_read_b128 v[196:199], v141 offset:20480
	ds_read_b128 v[200:203], v141 offset:21504
	ds_read_b128 v[204:207], v141 offset:22528
	ds_read_b128 v[208:211], v141 offset:23552
	buffer_load_dwordx4 v138, s[16:19], s76 offen lds
	s_add_i32 s77, s76, 0x80000
	s_mov_b32 m0, s31
	s_nop 0
	buffer_load_dwordx4 v138, s[16:19], s77 offen lds
	s_add_i32 s77, s76, 0x100000
	s_mov_b32 m0, s44
	s_nop 0
	buffer_load_dwordx4 v138, s[16:19], s77 offen lds
	s_add_i32 s77, s76, 0x180000
	s_mov_b32 m0, s45
	s_nop 0
	buffer_load_dwordx4 v138, s[16:19], s77 offen lds
	s_mov_b32 m0, s27
	s_add_i32 s77, s74, 0x80000
	buffer_load_dwordx4 v137, s[12:15], s74 offen lds
	s_mov_b32 m0, s46
	s_nop 0
	buffer_load_dwordx4 v137, s[12:15], s77 offen lds
	s_waitcnt vmcnt(8)
	s_waitcnt lgkmcnt(0)
	s_setprio 1
	s_barrier
	v_mfma_f32_16x16x32_bf16 v[62:65], v[148:151], v[180:183], v[62:65]
	v_mfma_f32_16x16x32_bf16 v[62:65], v[152:155], v[184:187], v[62:65]
	v_mfma_f32_16x16x32_bf16 v[54:57], v[156:159], v[180:183], v[54:57]
	v_mfma_f32_16x16x32_bf16 v[54:57], v[160:163], v[184:187], v[54:57]
	v_mfma_f32_16x16x32_bf16 v[46:49], v[148:151], v[188:191], v[46:49]
	v_mfma_f32_16x16x32_bf16 v[46:49], v[152:155], v[192:195], v[46:49]
	v_mfma_f32_16x16x32_bf16 v[38:41], v[156:159], v[188:191], v[38:41]
	v_mfma_f32_16x16x32_bf16 v[38:41], v[160:163], v[192:195], v[38:41]
	v_mfma_f32_16x16x32_bf16 v[30:33], v[148:151], v[196:199], v[30:33]
	v_mfma_f32_16x16x32_bf16 v[30:33], v[152:155], v[200:203], v[30:33]
	v_mfma_f32_16x16x32_bf16 v[22:25], v[156:159], v[196:199], v[22:25]
	v_mfma_f32_16x16x32_bf16 v[22:25], v[160:163], v[200:203], v[22:25]
	v_mfma_f32_16x16x32_bf16 v[14:17], v[148:151], v[204:207], v[14:17]
	v_mfma_f32_16x16x32_bf16 v[14:17], v[152:155], v[208:211], v[14:17]
	v_mfma_f32_16x16x32_bf16 v[6:9], v[156:159], v[204:207], v[6:9]
	v_mfma_f32_16x16x32_bf16 v[6:9], v[160:163], v[208:211], v[6:9]
	v_mfma_f32_16x16x32_bf16 v[58:61], v[164:167], v[180:183], v[58:61]
	v_mfma_f32_16x16x32_bf16 v[58:61], v[168:171], v[184:187], v[58:61]
	v_mfma_f32_16x16x32_bf16 v[50:53], v[172:175], v[180:183], v[50:53]
	v_mfma_f32_16x16x32_bf16 v[50:53], v[176:179], v[184:187], v[50:53]
	v_mfma_f32_16x16x32_bf16 v[42:45], v[164:167], v[188:191], v[42:45]
	v_mfma_f32_16x16x32_bf16 v[42:45], v[168:171], v[192:195], v[42:45]
	v_mfma_f32_16x16x32_bf16 v[34:37], v[172:175], v[188:191], v[34:37]
	v_mfma_f32_16x16x32_bf16 v[34:37], v[176:179], v[192:195], v[34:37]
	v_mfma_f32_16x16x32_bf16 v[26:29], v[164:167], v[196:199], v[26:29]
	v_mfma_f32_16x16x32_bf16 v[26:29], v[168:171], v[200:203], v[26:29]
	v_mfma_f32_16x16x32_bf16 v[18:21], v[172:175], v[196:199], v[18:21]
	v_mfma_f32_16x16x32_bf16 v[18:21], v[176:179], v[200:203], v[18:21]
	v_mfma_f32_16x16x32_bf16 v[10:13], v[164:167], v[204:207], v[10:13]
	v_mfma_f32_16x16x32_bf16 v[10:13], v[168:171], v[208:211], v[10:13]
	v_mfma_f32_16x16x32_bf16 v[2:5], v[172:175], v[204:207], v[2:5]
	v_mfma_f32_16x16x32_bf16 v[2:5], v[176:179], v[208:211], v[2:5]
	s_setprio 0
	s_barrier
	ds_read_b128 v[148:151], v142
	ds_read_b128 v[152:155], v142 offset:1024
	ds_read_b128 v[156:159], v142 offset:2048
	ds_read_b128 v[160:163], v142 offset:3072
	ds_read_b128 v[164:167], v143
	ds_read_b128 v[168:171], v143 offset:1024
	ds_read_b128 v[172:175], v143 offset:2048
	ds_read_b128 v[176:179], v143 offset:3072
	s_mov_b32 m0, s47
	s_add_i32 s77, s74, 0x100000
	ds_read_b128 v[180:183], v141 offset:32768
	ds_read_b128 v[184:187], v141 offset:33792
	ds_read_b128 v[188:191], v141 offset:34816
	ds_read_b128 v[192:195], v141 offset:35840
	ds_read_b128 v[196:199], v141 offset:36864
	ds_read_b128 v[200:203], v141 offset:37888
	ds_read_b128 v[204:207], v141 offset:38912
	ds_read_b128 v[208:211], v141 offset:39936
	buffer_load_dwordx4 v137, s[12:15], s77 offen lds
	s_add_i32 s77, s74, 0x180000
	s_mov_b32 m0, s48
	s_nop 0
	buffer_load_dwordx4 v137, s[12:15], s77 offen lds
	s_waitcnt vmcnt(8)
	s_waitcnt lgkmcnt(0)
	s_setprio 1
	s_barrier
	v_mfma_f32_16x16x32_bf16 v[118:121], v[148:151], v[180:183], v[118:121]
	v_mfma_f32_16x16x32_bf16 v[118:121], v[152:155], v[184:187], v[118:121]
	v_mfma_f32_16x16x32_bf16 v[114:117], v[156:159], v[180:183], v[114:117]
	v_mfma_f32_16x16x32_bf16 v[114:117], v[160:163], v[184:187], v[114:117]
	v_mfma_f32_16x16x32_bf16 v[110:113], v[148:151], v[188:191], v[110:113]
	v_mfma_f32_16x16x32_bf16 v[110:113], v[152:155], v[192:195], v[110:113]
	v_mfma_f32_16x16x32_bf16 v[102:105], v[156:159], v[188:191], v[102:105]
	v_mfma_f32_16x16x32_bf16 v[102:105], v[160:163], v[192:195], v[102:105]
	v_mfma_f32_16x16x32_bf16 v[94:97], v[148:151], v[196:199], v[94:97]
	v_mfma_f32_16x16x32_bf16 v[94:97], v[152:155], v[200:203], v[94:97]
	v_mfma_f32_16x16x32_bf16 v[86:89], v[156:159], v[196:199], v[86:89]
	v_mfma_f32_16x16x32_bf16 v[86:89], v[160:163], v[200:203], v[86:89]
	v_mfma_f32_16x16x32_bf16 v[78:81], v[148:151], v[204:207], v[78:81]
	v_mfma_f32_16x16x32_bf16 v[78:81], v[152:155], v[208:211], v[78:81]
	v_mfma_f32_16x16x32_bf16 v[66:69], v[156:159], v[204:207], v[66:69]
	v_mfma_f32_16x16x32_bf16 v[66:69], v[160:163], v[208:211], v[66:69]
	v_mfma_f32_16x16x32_bf16 v[126:129], v[164:167], v[180:183], v[126:129]
	v_mfma_f32_16x16x32_bf16 v[126:129], v[168:171], v[184:187], v[126:129]
	v_mfma_f32_16x16x32_bf16 v[122:125], v[172:175], v[180:183], v[122:125]
	v_mfma_f32_16x16x32_bf16 v[122:125], v[176:179], v[184:187], v[122:125]
	v_mfma_f32_16x16x32_bf16 v[106:109], v[164:167], v[188:191], v[106:109]
	v_mfma_f32_16x16x32_bf16 v[106:109], v[168:171], v[192:195], v[106:109]
	v_mfma_f32_16x16x32_bf16 v[98:101], v[172:175], v[188:191], v[98:101]
	v_mfma_f32_16x16x32_bf16 v[98:101], v[176:179], v[192:195], v[98:101]
	v_mfma_f32_16x16x32_bf16 v[90:93], v[164:167], v[196:199], v[90:93]
	v_mfma_f32_16x16x32_bf16 v[90:93], v[168:171], v[200:203], v[90:93]
	v_mfma_f32_16x16x32_bf16 v[82:85], v[172:175], v[196:199], v[82:85]
	v_mfma_f32_16x16x32_bf16 v[82:85], v[176:179], v[200:203], v[82:85]
	v_mfma_f32_16x16x32_bf16 v[74:77], v[164:167], v[204:207], v[74:77]
	v_mfma_f32_16x16x32_bf16 v[74:77], v[168:171], v[208:211], v[74:77]
	v_mfma_f32_16x16x32_bf16 v[70:73], v[172:175], v[204:207], v[70:73]
	v_mfma_f32_16x16x32_bf16 v[70:73], v[176:179], v[208:211], v[70:73]
	s_setprio 0
	s_barrier
	s_mov_b32 m0, s50
	s_or_b32 s77, s76, 0x80
	ds_read_b128 v[180:183], v141 offset:49152
	ds_read_b128 v[184:187], v141 offset:50176
	ds_read_b128 v[188:191], v141 offset:51200
	ds_read_b128 v[192:195], v141 offset:52224
	ds_read_b128 v[196:199], v141 offset:53248
	ds_read_b128 v[200:203], v141 offset:54272
	ds_read_b128 v[204:207], v141 offset:55296
	ds_read_b128 v[208:211], v141 offset:56320
	buffer_load_dwordx4 v138, s[16:19], s77 offen lds
	s_add_i32 s77, s76, 0x80080
	s_mov_b32 m0, s51
	s_add_i32 s74, s74, 0x80080
	buffer_load_dwordx4 v138, s[16:19], s77 offen lds
	s_add_i32 s77, s76, 0x100080
	s_mov_b32 m0, s54
	s_add_i32 s76, s76, 0x180080
	buffer_load_dwordx4 v138, s[16:19], s77 offen lds
	s_mov_b32 m0, s55
	s_nop 0
	buffer_load_dwordx4 v138, s[16:19], s76 offen lds
	s_mov_b32 m0, s52
	s_nop 0
	buffer_load_dwordx4 v137, s[12:15], s75 offen lds
	s_mov_b32 m0, s53
	s_nop 0
	buffer_load_dwordx4 v137, s[12:15], s74 offen lds
	s_waitcnt vmcnt(8)
	s_waitcnt lgkmcnt(0)
	s_setprio 1
	s_barrier
	v_mfma_f32_16x16x32_bf16 v[62:65], v[148:151], v[180:183], v[62:65]
	v_mfma_f32_16x16x32_bf16 v[62:65], v[152:155], v[184:187], v[62:65]
	v_mfma_f32_16x16x32_bf16 v[54:57], v[156:159], v[180:183], v[54:57]
	v_mfma_f32_16x16x32_bf16 v[54:57], v[160:163], v[184:187], v[54:57]
	v_mfma_f32_16x16x32_bf16 v[46:49], v[148:151], v[188:191], v[46:49]
	v_mfma_f32_16x16x32_bf16 v[46:49], v[152:155], v[192:195], v[46:49]
	v_mfma_f32_16x16x32_bf16 v[38:41], v[156:159], v[188:191], v[38:41]
	v_mfma_f32_16x16x32_bf16 v[38:41], v[160:163], v[192:195], v[38:41]
	v_mfma_f32_16x16x32_bf16 v[30:33], v[148:151], v[196:199], v[30:33]
	v_mfma_f32_16x16x32_bf16 v[30:33], v[152:155], v[200:203], v[30:33]
	v_mfma_f32_16x16x32_bf16 v[22:25], v[156:159], v[196:199], v[22:25]
	v_mfma_f32_16x16x32_bf16 v[22:25], v[160:163], v[200:203], v[22:25]
	v_mfma_f32_16x16x32_bf16 v[14:17], v[148:151], v[204:207], v[14:17]
	v_mfma_f32_16x16x32_bf16 v[14:17], v[152:155], v[208:211], v[14:17]
	v_mfma_f32_16x16x32_bf16 v[6:9], v[156:159], v[204:207], v[6:9]
	v_mfma_f32_16x16x32_bf16 v[6:9], v[160:163], v[208:211], v[6:9]
	v_mfma_f32_16x16x32_bf16 v[58:61], v[164:167], v[180:183], v[58:61]
	v_mfma_f32_16x16x32_bf16 v[58:61], v[168:171], v[184:187], v[58:61]
	v_mfma_f32_16x16x32_bf16 v[50:53], v[172:175], v[180:183], v[50:53]
	v_mfma_f32_16x16x32_bf16 v[50:53], v[176:179], v[184:187], v[50:53]
	v_mfma_f32_16x16x32_bf16 v[42:45], v[164:167], v[188:191], v[42:45]
	v_mfma_f32_16x16x32_bf16 v[42:45], v[168:171], v[192:195], v[42:45]
	v_mfma_f32_16x16x32_bf16 v[34:37], v[172:175], v[188:191], v[34:37]
	v_mfma_f32_16x16x32_bf16 v[34:37], v[176:179], v[192:195], v[34:37]
	v_mfma_f32_16x16x32_bf16 v[26:29], v[164:167], v[196:199], v[26:29]
	v_mfma_f32_16x16x32_bf16 v[26:29], v[168:171], v[200:203], v[26:29]
	v_mfma_f32_16x16x32_bf16 v[18:21], v[172:175], v[196:199], v[18:21]
	v_mfma_f32_16x16x32_bf16 v[18:21], v[176:179], v[200:203], v[18:21]
	v_mfma_f32_16x16x32_bf16 v[10:13], v[164:167], v[204:207], v[10:13]
	v_mfma_f32_16x16x32_bf16 v[10:13], v[168:171], v[208:211], v[10:13]
	v_mfma_f32_16x16x32_bf16 v[2:5], v[172:175], v[204:207], v[2:5]
	v_mfma_f32_16x16x32_bf16 v[2:5], v[176:179], v[208:211], v[2:5]
	s_setprio 0
	s_barrier
	s_add_i32 s73, s73, 2
	s_addk_i32 s71, 0x100
	s_addk_i32 s72, 0x100
	s_cmp_ge_i32 s73, s3
	s_cbranch_scc0 .LBB0_642
	s_and_b64 vcc, exec, s[42:43]
	s_cbranch_vccz .LBB0_645

.LBB0_799:
	ds_read_b128 v[134:137], v210
	ds_read_b128 v[138:141], v210 offset:1024
	ds_read_b128 v[142:145], v210 offset:2048
	ds_read_b128 v[148:151], v210 offset:3072
	ds_read_b128 v[152:155], v211
	ds_read_b128 v[156:159], v211 offset:1024
	ds_read_b128 v[160:163], v211 offset:2048
	ds_read_b128 v[164:167], v211 offset:3072
	s_add_i32 s18, s77, 0xffbf8080
	s_cmp_eq_u32 s62, s79
	s_cselect_b32 s80, s6, s18
	s_cselect_b32 s82, s7, s78
	s_or_b32 s81, s80, 0x80
	s_add_i32 s18, s77, 0xffea8000
	s_mov_b32 m0, s63
	ds_read_b128 v[168:171], v212
	ds_read_b128 v[172:175], v212 offset:1024
	ds_read_b128 v[176:179], v212 offset:2048
	ds_read_b128 v[180:183], v212 offset:3072
	ds_read_b128 v[184:187], v212 offset:4096
	ds_read_b128 v[188:191], v212 offset:5120
	ds_read_b128 v[192:195], v212 offset:6144
	ds_read_b128 v[196:199], v212 offset:7168
	buffer_load_dwordx4 v208, s[12:15], s18 offen lds
	s_mov_b32 m0, s66
	s_nop 0
	buffer_load_dwordx4 v208, s[12:15], s77 offen lds
	s_waitcnt vmcnt(8)
	s_waitcnt lgkmcnt(0)
	s_setprio 1
	s_barrier
	v_mfma_f32_16x16x32_bf16 v[126:129], v[134:137], v[168:171], v[126:129]
	v_mfma_f32_16x16x32_bf16 v[126:129], v[138:141], v[172:175], v[126:129]
	v_mfma_f32_16x16x32_bf16 v[122:125], v[142:145], v[168:171], v[122:125]
	v_mfma_f32_16x16x32_bf16 v[122:125], v[148:151], v[172:175], v[122:125]
	v_mfma_f32_16x16x32_bf16 v[118:121], v[134:137], v[176:179], v[118:121]
	v_mfma_f32_16x16x32_bf16 v[118:121], v[138:141], v[180:183], v[118:121]
	v_mfma_f32_16x16x32_bf16 v[114:117], v[142:145], v[176:179], v[114:117]
	v_mfma_f32_16x16x32_bf16 v[114:117], v[148:151], v[180:183], v[114:117]
	v_mfma_f32_16x16x32_bf16 v[106:109], v[134:137], v[184:187], v[106:109]
	v_mfma_f32_16x16x32_bf16 v[106:109], v[138:141], v[188:191], v[106:109]
	v_mfma_f32_16x16x32_bf16 v[98:101], v[142:145], v[184:187], v[98:101]
	v_mfma_f32_16x16x32_bf16 v[98:101], v[148:151], v[188:191], v[98:101]
	v_mfma_f32_16x16x32_bf16 v[90:93], v[134:137], v[192:195], v[90:93]
	v_mfma_f32_16x16x32_bf16 v[90:93], v[138:141], v[196:199], v[90:93]
	v_mfma_f32_16x16x32_bf16 v[82:85], v[142:145], v[192:195], v[82:85]
	v_mfma_f32_16x16x32_bf16 v[82:85], v[148:151], v[196:199], v[82:85]
	v_mfma_f32_16x16x32_bf16 v[110:113], v[152:155], v[168:171], v[110:113]
	v_mfma_f32_16x16x32_bf16 v[110:113], v[156:159], v[172:175], v[110:113]
	v_mfma_f32_16x16x32_bf16 v[102:105], v[160:163], v[168:171], v[102:105]
	v_mfma_f32_16x16x32_bf16 v[102:105], v[164:167], v[172:175], v[102:105]
	v_mfma_f32_16x16x32_bf16 v[94:97], v[152:155], v[176:179], v[94:97]
	v_mfma_f32_16x16x32_bf16 v[94:97], v[156:159], v[180:183], v[94:97]
	v_mfma_f32_16x16x32_bf16 v[86:89], v[160:163], v[176:179], v[86:89]
	v_mfma_f32_16x16x32_bf16 v[86:89], v[164:167], v[180:183], v[86:89]
	v_mfma_f32_16x16x32_bf16 v[78:81], v[152:155], v[184:187], v[78:81]
	v_mfma_f32_16x16x32_bf16 v[78:81], v[156:159], v[188:191], v[78:81]
	v_mfma_f32_16x16x32_bf16 v[74:77], v[160:163], v[184:187], v[74:77]
	v_mfma_f32_16x16x32_bf16 v[74:77], v[164:167], v[188:191], v[74:77]
	v_mfma_f32_16x16x32_bf16 v[70:73], v[152:155], v[192:195], v[70:73]
	v_mfma_f32_16x16x32_bf16 v[70:73], v[156:159], v[196:199], v[70:73]
	v_mfma_f32_16x16x32_bf16 v[66:69], v[160:163], v[192:195], v[66:69]
	v_mfma_f32_16x16x32_bf16 v[66:69], v[164:167], v[196:199], v[66:69]
	s_setprio 0
	s_barrier
	s_mov_b32 m0, s25
	s_mov_b32 s18, s14
	s_mov_b32 s19, s15
	ds_read_b128 v[168:171], v212 offset:16384
	ds_read_b128 v[172:175], v212 offset:17408
	ds_read_b128 v[176:179], v212 offset:18432
	ds_read_b128 v[180:183], v212 offset:19456
	ds_read_b128 v[184:187], v212 offset:20480
	ds_read_b128 v[188:191], v212 offset:21504
	ds_read_b128 v[192:195], v212 offset:22528
	ds_read_b128 v[196:199], v212 offset:23552
	buffer_load_dwordx4 v209, s[16:19], s82 offen lds
	s_add_i32 s83, s82, 0x158000
	s_mov_b32 m0, s27
	s_nop 0
	buffer_load_dwordx4 v209, s[16:19], s83 offen lds
	s_add_i32 s83, s82, 0x2b0000
	s_mov_b32 m0, s30
	s_nop 0
	buffer_load_dwordx4 v209, s[16:19], s83 offen lds
	s_add_i32 s83, s82, 0x408000
	s_mov_b32 m0, s31
	s_nop 0
	buffer_load_dwordx4 v209, s[16:19], s83 offen lds
	s_mov_b32 m0, s21
	s_add_i32 s83, s80, 0x158000
	buffer_load_dwordx4 v208, s[12:15], s80 offen lds
	s_mov_b32 m0, s48
	s_nop 0
	buffer_load_dwordx4 v208, s[12:15], s83 offen lds
	s_waitcnt vmcnt(8)
	s_waitcnt lgkmcnt(0)
	s_setprio 1
	s_barrier
	v_mfma_f32_16x16x32_bf16 v[62:65], v[134:137], v[168:171], v[62:65]
	v_mfma_f32_16x16x32_bf16 v[62:65], v[138:141], v[172:175], v[62:65]
	v_mfma_f32_16x16x32_bf16 v[58:61], v[142:145], v[168:171], v[58:61]
	v_mfma_f32_16x16x32_bf16 v[58:61], v[148:151], v[172:175], v[58:61]
	v_mfma_f32_16x16x32_bf16 v[54:57], v[134:137], v[176:179], v[54:57]
	v_mfma_f32_16x16x32_bf16 v[54:57], v[138:141], v[180:183], v[54:57]
	v_mfma_f32_16x16x32_bf16 v[50:53], v[142:145], v[176:179], v[50:53]
	v_mfma_f32_16x16x32_bf16 v[50:53], v[148:151], v[180:183], v[50:53]
	v_mfma_f32_16x16x32_bf16 v[42:45], v[134:137], v[184:187], v[42:45]
	v_mfma_f32_16x16x32_bf16 v[42:45], v[138:141], v[188:191], v[42:45]
	v_mfma_f32_16x16x32_bf16 v[34:37], v[142:145], v[184:187], v[34:37]
	v_mfma_f32_16x16x32_bf16 v[34:37], v[148:151], v[188:191], v[34:37]
	v_mfma_f32_16x16x32_bf16 v[26:29], v[134:137], v[192:195], v[26:29]
	v_mfma_f32_16x16x32_bf16 v[26:29], v[138:141], v[196:199], v[26:29]
	v_mfma_f32_16x16x32_bf16 v[18:21], v[142:145], v[192:195], v[18:21]
	v_mfma_f32_16x16x32_bf16 v[18:21], v[148:151], v[196:199], v[18:21]
	v_mfma_f32_16x16x32_bf16 v[46:49], v[152:155], v[168:171], v[46:49]
	v_mfma_f32_16x16x32_bf16 v[46:49], v[156:159], v[172:175], v[46:49]
	v_mfma_f32_16x16x32_bf16 v[38:41], v[160:163], v[168:171], v[38:41]
	v_mfma_f32_16x16x32_bf16 v[38:41], v[164:167], v[172:175], v[38:41]
	v_mfma_f32_16x16x32_bf16 v[30:33], v[152:155], v[176:179], v[30:33]
	v_mfma_f32_16x16x32_bf16 v[30:33], v[156:159], v[180:183], v[30:33]
	v_mfma_f32_16x16x32_bf16 v[22:25], v[160:163], v[176:179], v[22:25]
	v_mfma_f32_16x16x32_bf16 v[22:25], v[164:167], v[180:183], v[22:25]
	v_mfma_f32_16x16x32_bf16 v[14:17], v[152:155], v[184:187], v[14:17]
	v_mfma_f32_16x16x32_bf16 v[14:17], v[156:159], v[188:191], v[14:17]
	v_mfma_f32_16x16x32_bf16 v[10:13], v[160:163], v[184:187], v[10:13]
	v_mfma_f32_16x16x32_bf16 v[10:13], v[164:167], v[188:191], v[10:13]
	v_mfma_f32_16x16x32_bf16 v[6:9], v[152:155], v[192:195], v[6:9]
	v_mfma_f32_16x16x32_bf16 v[6:9], v[156:159], v[196:199], v[6:9]
	v_mfma_f32_16x16x32_bf16 v[2:5], v[160:163], v[192:195], v[2:5]
	v_mfma_f32_16x16x32_bf16 v[2:5], v[164:167], v[196:199], v[2:5]
	s_setprio 0
	s_barrier
	ds_read_b128 v[134:137], v213
	ds_read_b128 v[138:141], v213 offset:1024
	ds_read_b128 v[142:145], v213 offset:2048
	ds_read_b128 v[148:151], v213 offset:3072
	ds_read_b128 v[152:155], v214
	ds_read_b128 v[156:159], v214 offset:1024
	ds_read_b128 v[160:163], v214 offset:2048
	ds_read_b128 v[164:167], v214 offset:3072
	s_mov_b32 m0, s49
	s_add_i32 s83, s80, 0x2b0000
	ds_read_b128 v[168:171], v212 offset:32768
	ds_read_b128 v[172:175], v212 offset:33792
	ds_read_b128 v[176:179], v212 offset:34816
	ds_read_b128 v[180:183], v212 offset:35840
	ds_read_b128 v[184:187], v212 offset:36864
	ds_read_b128 v[188:191], v212 offset:37888
	ds_read_b128 v[192:195], v212 offset:38912
	ds_read_b128 v[196:199], v212 offset:39936
	buffer_load_dwordx4 v208, s[12:15], s83 offen lds
	s_add_i32 s83, s80, 0x408000
	s_mov_b32 m0, s50
	s_nop 0
	buffer_load_dwordx4 v208, s[12:15], s83 offen lds
	s_waitcnt vmcnt(8)
	s_waitcnt lgkmcnt(0)
	s_setprio 1
	s_barrier
	v_mfma_f32_16x16x32_bf16 v[126:129], v[134:137], v[168:171], v[126:129]
	v_mfma_f32_16x16x32_bf16 v[126:129], v[138:141], v[172:175], v[126:129]
	v_mfma_f32_16x16x32_bf16 v[122:125], v[142:145], v[168:171], v[122:125]
	v_mfma_f32_16x16x32_bf16 v[122:125], v[148:151], v[172:175], v[122:125]
	v_mfma_f32_16x16x32_bf16 v[118:121], v[134:137], v[176:179], v[118:121]
	v_mfma_f32_16x16x32_bf16 v[118:121], v[138:141], v[180:183], v[118:121]
	v_mfma_f32_16x16x32_bf16 v[114:117], v[142:145], v[176:179], v[114:117]
	v_mfma_f32_16x16x32_bf16 v[114:117], v[148:151], v[180:183], v[114:117]
	v_mfma_f32_16x16x32_bf16 v[106:109], v[134:137], v[184:187], v[106:109]
	v_mfma_f32_16x16x32_bf16 v[106:109], v[138:141], v[188:191], v[106:109]
	v_mfma_f32_16x16x32_bf16 v[98:101], v[142:145], v[184:187], v[98:101]
	v_mfma_f32_16x16x32_bf16 v[98:101], v[148:151], v[188:191], v[98:101]
	v_mfma_f32_16x16x32_bf16 v[90:93], v[134:137], v[192:195], v[90:93]
	v_mfma_f32_16x16x32_bf16 v[90:93], v[138:141], v[196:199], v[90:93]
	v_mfma_f32_16x16x32_bf16 v[82:85], v[142:145], v[192:195], v[82:85]
	v_mfma_f32_16x16x32_bf16 v[82:85], v[148:151], v[196:199], v[82:85]
	v_mfma_f32_16x16x32_bf16 v[110:113], v[152:155], v[168:171], v[110:113]
	v_mfma_f32_16x16x32_bf16 v[110:113], v[156:159], v[172:175], v[110:113]
	v_mfma_f32_16x16x32_bf16 v[102:105], v[160:163], v[168:171], v[102:105]
	v_mfma_f32_16x16x32_bf16 v[102:105], v[164:167], v[172:175], v[102:105]
	v_mfma_f32_16x16x32_bf16 v[94:97], v[152:155], v[176:179], v[94:97]
	v_mfma_f32_16x16x32_bf16 v[94:97], v[156:159], v[180:183], v[94:97]
	v_mfma_f32_16x16x32_bf16 v[86:89], v[160:163], v[176:179], v[86:89]
	v_mfma_f32_16x16x32_bf16 v[86:89], v[164:167], v[180:183], v[86:89]
	v_mfma_f32_16x16x32_bf16 v[78:81], v[152:155], v[184:187], v[78:81]
	v_mfma_f32_16x16x32_bf16 v[78:81], v[156:159], v[188:191], v[78:81]
	v_mfma_f32_16x16x32_bf16 v[74:77], v[160:163], v[184:187], v[74:77]
	v_mfma_f32_16x16x32_bf16 v[74:77], v[164:167], v[188:191], v[74:77]
	v_mfma_f32_16x16x32_bf16 v[70:73], v[152:155], v[192:195], v[70:73]
	v_mfma_f32_16x16x32_bf16 v[70:73], v[156:159], v[196:199], v[70:73]
	v_mfma_f32_16x16x32_bf16 v[66:69], v[160:163], v[192:195], v[66:69]
	v_mfma_f32_16x16x32_bf16 v[66:69], v[164:167], v[196:199], v[66:69]
	s_setprio 0
	s_barrier
	s_mov_b32 m0, s54
	s_or_b32 s83, s82, 0x80
	ds_read_b128 v[168:171], v212 offset:49152
	ds_read_b128 v[172:175], v212 offset:50176
	ds_read_b128 v[176:179], v212 offset:51200
	ds_read_b128 v[180:183], v212 offset:52224
	ds_read_b128 v[184:187], v212 offset:53248
	ds_read_b128 v[188:191], v212 offset:54272
	ds_read_b128 v[192:195], v212 offset:55296
	ds_read_b128 v[196:199], v212 offset:56320
	buffer_load_dwordx4 v209, s[16:19], s83 offen lds
	s_add_i32 s83, s82, 0x158080
	s_mov_b32 m0, s55
	s_add_i32 s80, s80, 0x158080
	buffer_load_dwordx4 v209, s[16:19], s83 offen lds
	s_add_i32 s83, s82, 0x2b0080
	s_mov_b32 m0, s58
	s_add_i32 s82, s82, 0x408080
	buffer_load_dwordx4 v209, s[16:19], s83 offen lds
	s_mov_b32 m0, s59
	s_nop 0
	buffer_load_dwordx4 v209, s[16:19], s82 offen lds
	s_mov_b32 m0, s56
	s_nop 0
	buffer_load_dwordx4 v208, s[12:15], s81 offen lds
	s_mov_b32 m0, s57
	s_nop 0
	buffer_load_dwordx4 v208, s[12:15], s80 offen lds
	s_waitcnt vmcnt(8)
	s_waitcnt lgkmcnt(0)
	s_setprio 1
	s_barrier
	v_mfma_f32_16x16x32_bf16 v[62:65], v[134:137], v[168:171], v[62:65]
	v_mfma_f32_16x16x32_bf16 v[62:65], v[138:141], v[172:175], v[62:65]
	v_mfma_f32_16x16x32_bf16 v[58:61], v[142:145], v[168:171], v[58:61]
	v_mfma_f32_16x16x32_bf16 v[58:61], v[148:151], v[172:175], v[58:61]
	v_mfma_f32_16x16x32_bf16 v[54:57], v[134:137], v[176:179], v[54:57]
	v_mfma_f32_16x16x32_bf16 v[54:57], v[138:141], v[180:183], v[54:57]
	v_mfma_f32_16x16x32_bf16 v[50:53], v[142:145], v[176:179], v[50:53]
	v_mfma_f32_16x16x32_bf16 v[50:53], v[148:151], v[180:183], v[50:53]
	v_mfma_f32_16x16x32_bf16 v[42:45], v[134:137], v[184:187], v[42:45]
	v_mfma_f32_16x16x32_bf16 v[42:45], v[138:141], v[188:191], v[42:45]
	v_mfma_f32_16x16x32_bf16 v[34:37], v[142:145], v[184:187], v[34:37]
	v_mfma_f32_16x16x32_bf16 v[34:37], v[148:151], v[188:191], v[34:37]
	v_mfma_f32_16x16x32_bf16 v[26:29], v[134:137], v[192:195], v[26:29]
	v_mfma_f32_16x16x32_bf16 v[26:29], v[138:141], v[196:199], v[26:29]
	v_mfma_f32_16x16x32_bf16 v[18:21], v[142:145], v[192:195], v[18:21]
	v_mfma_f32_16x16x32_bf16 v[18:21], v[148:151], v[196:199], v[18:21]
	v_mfma_f32_16x16x32_bf16 v[46:49], v[152:155], v[168:171], v[46:49]
	v_mfma_f32_16x16x32_bf16 v[46:49], v[156:159], v[172:175], v[46:49]
	v_mfma_f32_16x16x32_bf16 v[38:41], v[160:163], v[168:171], v[38:41]
	v_mfma_f32_16x16x32_bf16 v[38:41], v[164:167], v[172:175], v[38:41]
	v_mfma_f32_16x16x32_bf16 v[30:33], v[152:155], v[176:179], v[30:33]
	v_mfma_f32_16x16x32_bf16 v[30:33], v[156:159], v[180:183], v[30:33]
	v_mfma_f32_16x16x32_bf16 v[22:25], v[160:163], v[176:179], v[22:25]
	v_mfma_f32_16x16x32_bf16 v[22:25], v[164:167], v[180:183], v[22:25]
	v_mfma_f32_16x16x32_bf16 v[14:17], v[152:155], v[184:187], v[14:17]
	v_mfma_f32_16x16x32_bf16 v[14:17], v[156:159], v[188:191], v[14:17]
	v_mfma_f32_16x16x32_bf16 v[10:13], v[160:163], v[184:187], v[10:13]
	v_mfma_f32_16x16x32_bf16 v[10:13], v[164:167], v[188:191], v[10:13]
	v_mfma_f32_16x16x32_bf16 v[6:9], v[152:155], v[192:195], v[6:9]
	v_mfma_f32_16x16x32_bf16 v[6:9], v[156:159], v[196:199], v[6:9]
	v_mfma_f32_16x16x32_bf16 v[2:5], v[160:163], v[192:195], v[2:5]
	v_mfma_f32_16x16x32_bf16 v[2:5], v[164:167], v[196:199], v[2:5]
	s_setprio 0
	s_barrier
	s_add_i32 s79, s79, 2
	s_addk_i32 s77, 0x100
	s_addk_i32 s78, 0x100
	s_cmp_ge_i32 s79, s3
	s_cbranch_scc0 .LBB0_799
	v_pk_mul_f32 v[184:185], v[128:129], 0.5 op_sel_hi:[1,0]
	v_pk_mul_f32 v[186:187], v[126:127], 0.5 op_sel_hi:[1,0]
	v_pk_mul_f32 v[188:189], v[124:125], 0.5 op_sel_hi:[1,0]
	v_pk_mul_f32 v[190:191], v[122:123], 0.5 op_sel_hi:[1,0]
	v_pk_mul_f32 v[198:199], v[112:113], 0.5 op_sel_hi:[1,0]
	v_pk_mul_f32 v[196:197], v[110:111], 0.5 op_sel_hi:[1,0]
	v_pk_mul_f32 v[194:195], v[104:105], 0.5 op_sel_hi:[1,0]
	v_pk_mul_f32 v[192:193], v[102:103], 0.5 op_sel_hi:[1,0]
	v_pk_mul_f32 v[182:183], v[120:121], 0.5 op_sel_hi:[1,0]
	v_pk_mul_f32 v[180:181], v[118:119], 0.5 op_sel_hi:[1,0]
	v_pk_mul_f32 v[178:179], v[116:117], 0.5 op_sel_hi:[1,0]
	v_pk_mul_f32 v[176:177], v[114:115], 0.5 op_sel_hi:[1,0]
	v_pk_mul_f32 v[172:173], v[96:97], 0.5 op_sel_hi:[1,0]
	v_pk_mul_f32 v[170:171], v[94:95], 0.5 op_sel_hi:[1,0]
	v_pk_mul_f32 v[168:169], v[88:89], 0.5 op_sel_hi:[1,0]
	v_pk_mul_f32 v[166:167], v[86:87], 0.5 op_sel_hi:[1,0]
	v_pk_mul_f32 v[164:165], v[108:109], 0.5 op_sel_hi:[1,0]
	v_pk_mul_f32 v[162:163], v[106:107], 0.5 op_sel_hi:[1,0]
	v_pk_mul_f32 v[160:161], v[100:101], 0.5 op_sel_hi:[1,0]
	v_pk_mul_f32 v[158:159], v[98:99], 0.5 op_sel_hi:[1,0]
	v_pk_mul_f32 v[156:157], v[80:81], 0.5 op_sel_hi:[1,0]
	v_pk_mul_f32 v[154:155], v[78:79], 0.5 op_sel_hi:[1,0]
	v_pk_mul_f32 v[152:153], v[76:77], 0.5 op_sel_hi:[1,0]
	v_pk_mul_f32 v[150:151], v[74:75], 0.5 op_sel_hi:[1,0]
	v_pk_mul_f32 v[144:145], v[92:93], 0.5 op_sel_hi:[1,0]
	v_pk_mul_f32 v[142:143], v[90:91], 0.5 op_sel_hi:[1,0]
	v_pk_mul_f32 v[140:141], v[84:85], 0.5 op_sel_hi:[1,0]
	v_pk_mul_f32 v[138:139], v[82:83], 0.5 op_sel_hi:[1,0]
	v_pk_mul_f32 v[136:137], v[72:73], 0.5 op_sel_hi:[1,0]
	v_pk_mul_f32 v[134:135], v[70:71], 0.5 op_sel_hi:[1,0]
	v_pk_mul_f32 v[128:129], v[68:69], 0.5 op_sel_hi:[1,0]
	v_pk_mul_f32 v[126:127], v[66:67], 0.5 op_sel_hi:[1,0]
	v_pk_mul_f32 v[122:123], v[64:65], 0.5 op_sel_hi:[1,0]
	v_pk_mul_f32 v[120:121], v[62:63], 0.5 op_sel_hi:[1,0]
	v_pk_mul_f32 v[118:119], v[60:61], 0.5 op_sel_hi:[1,0]
	v_pk_mul_f32 v[116:117], v[58:59], 0.5 op_sel_hi:[1,0]
	v_pk_mul_f32 v[112:113], v[48:49], 0.5 op_sel_hi:[1,0]
	v_pk_mul_f32 v[110:111], v[46:47], 0.5 op_sel_hi:[1,0]
	v_pk_mul_f32 v[108:109], v[40:41], 0.5 op_sel_hi:[1,0]
	v_pk_mul_f32 v[106:107], v[38:39], 0.5 op_sel_hi:[1,0]
	v_pk_mul_f32 v[104:105], v[56:57], 0.5 op_sel_hi:[1,0]
	v_pk_mul_f32 v[102:103], v[54:55], 0.5 op_sel_hi:[1,0]
	v_pk_mul_f32 v[100:101], v[52:53], 0.5 op_sel_hi:[1,0]
	v_pk_mul_f32 v[98:99], v[50:51], 0.5 op_sel_hi:[1,0]
	v_pk_mul_f32 v[96:97], v[32:33], 0.5 op_sel_hi:[1,0]
	v_pk_mul_f32 v[94:95], v[30:31], 0.5 op_sel_hi:[1,0]
	v_pk_mul_f32 v[92:93], v[24:25], 0.5 op_sel_hi:[1,0]
	v_pk_mul_f32 v[90:91], v[22:23], 0.5 op_sel_hi:[1,0]
	v_pk_mul_f32 v[88:89], v[44:45], 0.5 op_sel_hi:[1,0]
	v_pk_mul_f32 v[86:87], v[42:43], 0.5 op_sel_hi:[1,0]
	v_pk_mul_f32 v[84:85], v[36:37], 0.5 op_sel_hi:[1,0]
	v_pk_mul_f32 v[82:83], v[34:35], 0.5 op_sel_hi:[1,0]
	v_pk_mul_f32 v[80:81], v[16:17], 0.5 op_sel_hi:[1,0]
	v_pk_mul_f32 v[78:79], v[14:15], 0.5 op_sel_hi:[1,0]
	v_pk_mul_f32 v[76:77], v[12:13], 0.5 op_sel_hi:[1,0]
	v_pk_mul_f32 v[74:75], v[10:11], 0.5 op_sel_hi:[1,0]
	v_pk_mul_f32 v[72:73], v[28:29], 0.5 op_sel_hi:[1,0]
	v_pk_mul_f32 v[70:71], v[26:27], 0.5 op_sel_hi:[1,0]
	v_pk_mul_f32 v[68:69], v[20:21], 0.5 op_sel_hi:[1,0]
	v_pk_mul_f32 v[66:67], v[18:19], 0.5 op_sel_hi:[1,0]
	v_pk_mul_f32 v[64:65], v[8:9], 0.5 op_sel_hi:[1,0]
	v_pk_mul_f32 v[62:63], v[6:7], 0.5 op_sel_hi:[1,0]
	v_pk_mul_f32 v[60:61], v[4:5], 0.5 op_sel_hi:[1,0]
	v_pk_mul_f32 v[58:59], v[2:3], 0.5 op_sel_hi:[1,0]
	s_and_b64 vcc, exec, s[38:39]
	s_cbranch_vccz .LBB0_802

.LBB0_892:
	ds_read_b128 v[130:133], v172
	ds_read_b128 v[134:137], v172 offset:1024
	ds_read_b128 v[148:151], v172 offset:2048
	ds_read_b128 v[152:155], v172 offset:3072
	ds_read_b128 v[156:159], v173
	ds_read_b128 v[160:163], v173 offset:1024
	ds_read_b128 v[164:167], v173 offset:2048
	ds_read_b128 v[180:183], v173 offset:3072
	s_add_i32 s18, s8, 0xffe80080
	s_cmp_eq_u32 s77, s52
	s_cselect_b32 s53, s6, s18
	s_cselect_b32 s58, s7, s9
	s_or_b32 s57, s53, 0x80
	s_add_i32 s18, s8, 0xfff80000
	s_mov_b32 m0, s78
	ds_read_b128 v[184:187], v174
	ds_read_b128 v[188:191], v174 offset:1024
	ds_read_b128 v[192:195], v174 offset:2048
	ds_read_b128 v[196:199], v174 offset:3072
	ds_read_b128 v[200:203], v174 offset:4096
	ds_read_b128 v[204:207], v174 offset:5120
	ds_read_b128 v[208:211], v174 offset:6144
	ds_read_b128 v[212:215], v174 offset:7168
	buffer_load_dwordx4 v170, s[12:15], s18 offen lds
	s_mov_b32 m0, s79
	s_nop 0
	buffer_load_dwordx4 v170, s[12:15], s8 offen lds
	s_waitcnt vmcnt(8)
	s_waitcnt lgkmcnt(0)
	s_setprio 1
	s_barrier
	v_mfma_f32_16x16x32_bf16 v[126:129], v[130:133], v[184:187], v[126:129]
	v_mfma_f32_16x16x32_bf16 v[126:129], v[134:137], v[188:191], v[126:129]
	v_mfma_f32_16x16x32_bf16 v[118:121], v[148:151], v[184:187], v[118:121]
	v_mfma_f32_16x16x32_bf16 v[118:121], v[152:155], v[188:191], v[118:121]
	v_mfma_f32_16x16x32_bf16 v[110:113], v[130:133], v[192:195], v[110:113]
	v_mfma_f32_16x16x32_bf16 v[110:113], v[134:137], v[196:199], v[110:113]
	v_mfma_f32_16x16x32_bf16 v[102:105], v[148:151], v[192:195], v[102:105]
	v_mfma_f32_16x16x32_bf16 v[102:105], v[152:155], v[196:199], v[102:105]
	v_mfma_f32_16x16x32_bf16 v[94:97], v[130:133], v[200:203], v[94:97]
	v_mfma_f32_16x16x32_bf16 v[94:97], v[134:137], v[204:207], v[94:97]
	v_mfma_f32_16x16x32_bf16 v[90:93], v[148:151], v[200:203], v[90:93]
	v_mfma_f32_16x16x32_bf16 v[90:93], v[152:155], v[204:207], v[90:93]
	v_mfma_f32_16x16x32_bf16 v[78:81], v[130:133], v[208:211], v[78:81]
	v_mfma_f32_16x16x32_bf16 v[78:81], v[134:137], v[212:215], v[78:81]
	v_mfma_f32_16x16x32_bf16 v[70:73], v[148:151], v[208:211], v[70:73]
	v_mfma_f32_16x16x32_bf16 v[70:73], v[152:155], v[212:215], v[70:73]
	v_mfma_f32_16x16x32_bf16 v[122:125], v[156:159], v[184:187], v[122:125]
	v_mfma_f32_16x16x32_bf16 v[122:125], v[160:163], v[188:191], v[122:125]
	v_mfma_f32_16x16x32_bf16 v[114:117], v[164:167], v[184:187], v[114:117]
	v_mfma_f32_16x16x32_bf16 v[114:117], v[180:183], v[188:191], v[114:117]
	v_mfma_f32_16x16x32_bf16 v[106:109], v[156:159], v[192:195], v[106:109]
	v_mfma_f32_16x16x32_bf16 v[106:109], v[160:163], v[196:199], v[106:109]
	v_mfma_f32_16x16x32_bf16 v[98:101], v[164:167], v[192:195], v[98:101]
	v_mfma_f32_16x16x32_bf16 v[98:101], v[180:183], v[196:199], v[98:101]
	v_mfma_f32_16x16x32_bf16 v[86:89], v[156:159], v[200:203], v[86:89]
	v_mfma_f32_16x16x32_bf16 v[86:89], v[160:163], v[204:207], v[86:89]
	v_mfma_f32_16x16x32_bf16 v[82:85], v[164:167], v[200:203], v[82:85]
	v_mfma_f32_16x16x32_bf16 v[82:85], v[180:183], v[204:207], v[82:85]
	v_mfma_f32_16x16x32_bf16 v[74:77], v[156:159], v[208:211], v[74:77]
	v_mfma_f32_16x16x32_bf16 v[74:77], v[160:163], v[212:215], v[74:77]
	v_mfma_f32_16x16x32_bf16 v[66:69], v[164:167], v[208:211], v[66:69]
	v_mfma_f32_16x16x32_bf16 v[66:69], v[180:183], v[212:215], v[66:69]
	s_setprio 0
	s_barrier
	s_mov_b32 m0, s27
	s_mov_b32 s18, s14
	s_mov_b32 s19, s15
	ds_read_b128 v[184:187], v174 offset:16384
	ds_read_b128 v[188:191], v174 offset:17408
	ds_read_b128 v[192:195], v174 offset:18432
	ds_read_b128 v[196:199], v174 offset:19456
	ds_read_b128 v[200:203], v174 offset:20480
	ds_read_b128 v[204:207], v174 offset:21504
	ds_read_b128 v[208:211], v174 offset:22528
	ds_read_b128 v[212:215], v174 offset:23552
	buffer_load_dwordx4 v171, s[16:19], s58 offen lds
	s_add_i32 s59, s58, 0x80000
	s_mov_b32 m0, s60
	s_nop 0
	buffer_load_dwordx4 v171, s[16:19], s59 offen lds
	s_add_i32 s59, s58, 0x100000
	s_mov_b32 m0, s61
	s_nop 0
	buffer_load_dwordx4 v171, s[16:19], s59 offen lds
	s_add_i32 s59, s58, 0x180000
	s_mov_b32 m0, s62
	s_nop 0
	buffer_load_dwordx4 v171, s[16:19], s59 offen lds
	s_mov_b32 m0, s25
	s_add_i32 s59, s53, 0x80000
	buffer_load_dwordx4 v170, s[12:15], s53 offen lds
	s_mov_b32 m0, s63
	s_nop 0
	buffer_load_dwordx4 v170, s[12:15], s59 offen lds
	s_waitcnt vmcnt(8)
	s_waitcnt lgkmcnt(0)
	s_setprio 1
	s_barrier
	v_mfma_f32_16x16x32_bf16 v[62:65], v[130:133], v[184:187], v[62:65]
	v_mfma_f32_16x16x32_bf16 v[62:65], v[134:137], v[188:191], v[62:65]
	v_mfma_f32_16x16x32_bf16 v[54:57], v[148:151], v[184:187], v[54:57]
	v_mfma_f32_16x16x32_bf16 v[54:57], v[152:155], v[188:191], v[54:57]
	v_mfma_f32_16x16x32_bf16 v[46:49], v[130:133], v[192:195], v[46:49]
	v_mfma_f32_16x16x32_bf16 v[46:49], v[134:137], v[196:199], v[46:49]
	v_mfma_f32_16x16x32_bf16 v[38:41], v[148:151], v[192:195], v[38:41]
	v_mfma_f32_16x16x32_bf16 v[38:41], v[152:155], v[196:199], v[38:41]
	v_mfma_f32_16x16x32_bf16 v[30:33], v[130:133], v[200:203], v[30:33]
	v_mfma_f32_16x16x32_bf16 v[30:33], v[134:137], v[204:207], v[30:33]
	v_mfma_f32_16x16x32_bf16 v[22:25], v[148:151], v[200:203], v[22:25]
	v_mfma_f32_16x16x32_bf16 v[22:25], v[152:155], v[204:207], v[22:25]
	v_mfma_f32_16x16x32_bf16 v[14:17], v[130:133], v[208:211], v[14:17]
	v_mfma_f32_16x16x32_bf16 v[14:17], v[134:137], v[212:215], v[14:17]
	v_mfma_f32_16x16x32_bf16 v[6:9], v[148:151], v[208:211], v[6:9]
	v_mfma_f32_16x16x32_bf16 v[6:9], v[152:155], v[212:215], v[6:9]
	v_mfma_f32_16x16x32_bf16 v[58:61], v[156:159], v[184:187], v[58:61]
	v_mfma_f32_16x16x32_bf16 v[58:61], v[160:163], v[188:191], v[58:61]
	v_mfma_f32_16x16x32_bf16 v[50:53], v[164:167], v[184:187], v[50:53]
	v_mfma_f32_16x16x32_bf16 v[50:53], v[180:183], v[188:191], v[50:53]
	v_mfma_f32_16x16x32_bf16 v[42:45], v[156:159], v[192:195], v[42:45]
	v_mfma_f32_16x16x32_bf16 v[42:45], v[160:163], v[196:199], v[42:45]
	v_mfma_f32_16x16x32_bf16 v[34:37], v[164:167], v[192:195], v[34:37]
	v_mfma_f32_16x16x32_bf16 v[34:37], v[180:183], v[196:199], v[34:37]
	v_mfma_f32_16x16x32_bf16 v[26:29], v[156:159], v[200:203], v[26:29]
	v_mfma_f32_16x16x32_bf16 v[26:29], v[160:163], v[204:207], v[26:29]
	v_mfma_f32_16x16x32_bf16 v[18:21], v[164:167], v[200:203], v[18:21]
	v_mfma_f32_16x16x32_bf16 v[18:21], v[180:183], v[204:207], v[18:21]
	v_mfma_f32_16x16x32_bf16 v[10:13], v[156:159], v[208:211], v[10:13]
	v_mfma_f32_16x16x32_bf16 v[10:13], v[160:163], v[212:215], v[10:13]
	v_mfma_f32_16x16x32_bf16 v[2:5], v[164:167], v[208:211], v[2:5]
	v_mfma_f32_16x16x32_bf16 v[2:5], v[180:183], v[212:215], v[2:5]
	s_setprio 0
	s_barrier
	ds_read_b128 v[130:133], v175
	ds_read_b128 v[134:137], v175 offset:1024
	ds_read_b128 v[148:151], v175 offset:2048
	ds_read_b128 v[152:155], v175 offset:3072
	ds_read_b128 v[156:159], v176
	ds_read_b128 v[160:163], v176 offset:1024
	ds_read_b128 v[164:167], v176 offset:2048
	ds_read_b128 v[180:183], v176 offset:3072
	s_mov_b32 m0, s64
	s_add_i32 s59, s53, 0x100000
	ds_read_b128 v[184:187], v174 offset:32768
	ds_read_b128 v[188:191], v174 offset:33792
	ds_read_b128 v[192:195], v174 offset:34816
	ds_read_b128 v[196:199], v174 offset:35840
	ds_read_b128 v[200:203], v174 offset:36864
	ds_read_b128 v[204:207], v174 offset:37888
	ds_read_b128 v[208:211], v174 offset:38912
	ds_read_b128 v[212:215], v174 offset:39936
	buffer_load_dwordx4 v170, s[12:15], s59 offen lds
	s_add_i32 s59, s53, 0x180000
	s_mov_b32 m0, s65
	s_nop 0
	buffer_load_dwordx4 v170, s[12:15], s59 offen lds
	s_waitcnt vmcnt(8)
	s_waitcnt lgkmcnt(0)
	s_setprio 1
	s_barrier
	v_mfma_f32_16x16x32_bf16 v[126:129], v[130:133], v[184:187], v[126:129]
	v_mfma_f32_16x16x32_bf16 v[126:129], v[134:137], v[188:191], v[126:129]
	v_mfma_f32_16x16x32_bf16 v[118:121], v[148:151], v[184:187], v[118:121]
	v_mfma_f32_16x16x32_bf16 v[118:121], v[152:155], v[188:191], v[118:121]
	v_mfma_f32_16x16x32_bf16 v[110:113], v[130:133], v[192:195], v[110:113]
	v_mfma_f32_16x16x32_bf16 v[110:113], v[134:137], v[196:199], v[110:113]
	v_mfma_f32_16x16x32_bf16 v[102:105], v[148:151], v[192:195], v[102:105]
	v_mfma_f32_16x16x32_bf16 v[102:105], v[152:155], v[196:199], v[102:105]
	v_mfma_f32_16x16x32_bf16 v[94:97], v[130:133], v[200:203], v[94:97]
	v_mfma_f32_16x16x32_bf16 v[94:97], v[134:137], v[204:207], v[94:97]
	v_mfma_f32_16x16x32_bf16 v[90:93], v[148:151], v[200:203], v[90:93]
	v_mfma_f32_16x16x32_bf16 v[90:93], v[152:155], v[204:207], v[90:93]
	v_mfma_f32_16x16x32_bf16 v[78:81], v[130:133], v[208:211], v[78:81]
	v_mfma_f32_16x16x32_bf16 v[78:81], v[134:137], v[212:215], v[78:81]
	v_mfma_f32_16x16x32_bf16 v[70:73], v[148:151], v[208:211], v[70:73]
	v_mfma_f32_16x16x32_bf16 v[70:73], v[152:155], v[212:215], v[70:73]
	v_mfma_f32_16x16x32_bf16 v[122:125], v[156:159], v[184:187], v[122:125]
	v_mfma_f32_16x16x32_bf16 v[122:125], v[160:163], v[188:191], v[122:125]
	v_mfma_f32_16x16x32_bf16 v[114:117], v[164:167], v[184:187], v[114:117]
	v_mfma_f32_16x16x32_bf16 v[114:117], v[180:183], v[188:191], v[114:117]
	v_mfma_f32_16x16x32_bf16 v[106:109], v[156:159], v[192:195], v[106:109]
	v_mfma_f32_16x16x32_bf16 v[106:109], v[160:163], v[196:199], v[106:109]
	v_mfma_f32_16x16x32_bf16 v[98:101], v[164:167], v[192:195], v[98:101]
	v_mfma_f32_16x16x32_bf16 v[98:101], v[180:183], v[196:199], v[98:101]
	v_mfma_f32_16x16x32_bf16 v[86:89], v[156:159], v[200:203], v[86:89]
	v_mfma_f32_16x16x32_bf16 v[86:89], v[160:163], v[204:207], v[86:89]
	v_mfma_f32_16x16x32_bf16 v[82:85], v[164:167], v[200:203], v[82:85]
	v_mfma_f32_16x16x32_bf16 v[82:85], v[180:183], v[204:207], v[82:85]
	v_mfma_f32_16x16x32_bf16 v[74:77], v[156:159], v[208:211], v[74:77]
	v_mfma_f32_16x16x32_bf16 v[74:77], v[160:163], v[212:215], v[74:77]
	v_mfma_f32_16x16x32_bf16 v[66:69], v[164:167], v[208:211], v[66:69]
	v_mfma_f32_16x16x32_bf16 v[66:69], v[180:183], v[212:215], v[66:69]
	s_setprio 0
	s_barrier
	s_mov_b32 m0, s70
	s_or_b32 s59, s58, 0x80
	ds_read_b128 v[184:187], v174 offset:49152
	ds_read_b128 v[188:191], v174 offset:50176
	ds_read_b128 v[192:195], v174 offset:51200
	ds_read_b128 v[196:199], v174 offset:52224
	ds_read_b128 v[200:203], v174 offset:53248
	ds_read_b128 v[204:207], v174 offset:54272
	ds_read_b128 v[208:211], v174 offset:55296
	ds_read_b128 v[212:215], v174 offset:56320
	buffer_load_dwordx4 v171, s[16:19], s59 offen lds
	s_add_i32 s59, s58, 0x80080
	s_mov_b32 m0, s71
	s_add_i32 s53, s53, 0x80080
	buffer_load_dwordx4 v171, s[16:19], s59 offen lds
	s_add_i32 s59, s58, 0x100080
	s_mov_b32 m0, s74
	s_add_i32 s58, s58, 0x180080
	buffer_load_dwordx4 v171, s[16:19], s59 offen lds
	s_mov_b32 m0, s75
	s_nop 0
	buffer_load_dwordx4 v171, s[16:19], s58 offen lds
	s_mov_b32 m0, s72
	s_nop 0
	buffer_load_dwordx4 v170, s[12:15], s57 offen lds
	s_mov_b32 m0, s73
	s_nop 0
	buffer_load_dwordx4 v170, s[12:15], s53 offen lds
	s_waitcnt vmcnt(8)
	s_waitcnt lgkmcnt(0)
	s_setprio 1
	s_barrier
	v_mfma_f32_16x16x32_bf16 v[62:65], v[130:133], v[184:187], v[62:65]
	v_mfma_f32_16x16x32_bf16 v[62:65], v[134:137], v[188:191], v[62:65]
	v_mfma_f32_16x16x32_bf16 v[54:57], v[148:151], v[184:187], v[54:57]
	v_mfma_f32_16x16x32_bf16 v[54:57], v[152:155], v[188:191], v[54:57]
	v_mfma_f32_16x16x32_bf16 v[46:49], v[130:133], v[192:195], v[46:49]
	v_mfma_f32_16x16x32_bf16 v[46:49], v[134:137], v[196:199], v[46:49]
	v_mfma_f32_16x16x32_bf16 v[38:41], v[148:151], v[192:195], v[38:41]
	v_mfma_f32_16x16x32_bf16 v[38:41], v[152:155], v[196:199], v[38:41]
	v_mfma_f32_16x16x32_bf16 v[30:33], v[130:133], v[200:203], v[30:33]
	v_mfma_f32_16x16x32_bf16 v[30:33], v[134:137], v[204:207], v[30:33]
	v_mfma_f32_16x16x32_bf16 v[22:25], v[148:151], v[200:203], v[22:25]
	v_mfma_f32_16x16x32_bf16 v[22:25], v[152:155], v[204:207], v[22:25]
	v_mfma_f32_16x16x32_bf16 v[14:17], v[130:133], v[208:211], v[14:17]
	v_mfma_f32_16x16x32_bf16 v[14:17], v[134:137], v[212:215], v[14:17]
	v_mfma_f32_16x16x32_bf16 v[6:9], v[148:151], v[208:211], v[6:9]
	v_mfma_f32_16x16x32_bf16 v[6:9], v[152:155], v[212:215], v[6:9]
	v_mfma_f32_16x16x32_bf16 v[58:61], v[156:159], v[184:187], v[58:61]
	v_mfma_f32_16x16x32_bf16 v[58:61], v[160:163], v[188:191], v[58:61]
	v_mfma_f32_16x16x32_bf16 v[50:53], v[164:167], v[184:187], v[50:53]
	v_mfma_f32_16x16x32_bf16 v[50:53], v[180:183], v[188:191], v[50:53]
	v_mfma_f32_16x16x32_bf16 v[42:45], v[156:159], v[192:195], v[42:45]
	v_mfma_f32_16x16x32_bf16 v[42:45], v[160:163], v[196:199], v[42:45]
	v_mfma_f32_16x16x32_bf16 v[34:37], v[164:167], v[192:195], v[34:37]
	v_mfma_f32_16x16x32_bf16 v[34:37], v[180:183], v[196:199], v[34:37]
	v_mfma_f32_16x16x32_bf16 v[26:29], v[156:159], v[200:203], v[26:29]
	v_mfma_f32_16x16x32_bf16 v[26:29], v[160:163], v[204:207], v[26:29]
	v_mfma_f32_16x16x32_bf16 v[18:21], v[164:167], v[200:203], v[18:21]
	v_mfma_f32_16x16x32_bf16 v[18:21], v[180:183], v[204:207], v[18:21]
	v_mfma_f32_16x16x32_bf16 v[10:13], v[156:159], v[208:211], v[10:13]
	v_mfma_f32_16x16x32_bf16 v[10:13], v[160:163], v[212:215], v[10:13]
	v_mfma_f32_16x16x32_bf16 v[2:5], v[164:167], v[208:211], v[2:5]
	v_mfma_f32_16x16x32_bf16 v[2:5], v[180:183], v[212:215], v[2:5]
	s_setprio 0
	s_barrier
	s_add_i32 s52, s52, 2
	s_addk_i32 s8, 0x100
	s_addk_i32 s9, 0x100
	s_cmp_ge_i32 s52, s21
	s_cbranch_scc0 .LBB0_892
	s_and_b64 vcc, exec, s[48:49]
	s_cbranch_vccz .LBB0_895

.LBB0_1020:
	v_add_u32_e32 v142, 0x10000, v162
	v_add_u32_e32 v150, 0x14000, v162
	ds_read_b128 v[130:133], v142
	ds_read_b128 v[134:137], v142 offset:1024
	ds_read_b128 v[138:141], v142 offset:2048
	ds_read_b128 v[142:145], v142 offset:3072
	ds_read_b128 v[154:157], v150
	ds_read_b128 v[164:167], v150 offset:1024
	ds_read_b128 v[168:171], v150 offset:2048
	ds_read_b128 v[172:175], v150 offset:3072
	s_add_i32 s90, s6, 0x100
	s_add_i32 s7, s88, s6
	s_cmp_eq_u32 s81, s89
	s_cselect_b32 s91, 0, s90
	s_cselect_b32 s93, s87, s7
	s_add_i32 s91, s91, s70
	s_or_b32 s92, s91, 0x80
	s_add_i32 s6, s3, s6
	s_mov_b32 m0, s82
	s_add_i32 s7, s6, 0x20080
	ds_read_b128 v[176:179], v163
	ds_read_b128 v[180:183], v163 offset:1024
	ds_read_b128 v[184:187], v163 offset:2048
	ds_read_b128 v[188:191], v163 offset:3072
	ds_read_b128 v[192:195], v163 offset:4096
	ds_read_b128 v[196:199], v163 offset:5120
	ds_read_b128 v[200:203], v163 offset:6144
	ds_read_b128 v[204:207], v163 offset:7168
	buffer_load_dwordx4 v161, s[12:15], s7 offen lds
	s_add_i32 s6, s6, 0x30080
	s_mov_b32 m0, s83
	s_nop 0
	buffer_load_dwordx4 v161, s[12:15], s6 offen lds
	s_waitcnt vmcnt(8)
	s_waitcnt lgkmcnt(0)
	s_setprio 1
	s_barrier
	v_mfma_f32_16x16x32_bf16 v[126:129], v[130:133], v[176:179], v[126:129]
	v_mfma_f32_16x16x32_bf16 v[126:129], v[134:137], v[180:183], v[126:129]
	v_mfma_f32_16x16x32_bf16 v[122:125], v[138:141], v[176:179], v[122:125]
	v_mfma_f32_16x16x32_bf16 v[122:125], v[142:145], v[180:183], v[122:125]
	v_mfma_f32_16x16x32_bf16 v[110:113], v[130:133], v[184:187], v[110:113]
	v_mfma_f32_16x16x32_bf16 v[110:113], v[134:137], v[188:191], v[110:113]
	v_mfma_f32_16x16x32_bf16 v[106:109], v[138:141], v[184:187], v[106:109]
	v_mfma_f32_16x16x32_bf16 v[106:109], v[142:145], v[188:191], v[106:109]
	v_mfma_f32_16x16x32_bf16 v[94:97], v[130:133], v[192:195], v[94:97]
	v_mfma_f32_16x16x32_bf16 v[94:97], v[134:137], v[196:199], v[94:97]
	v_mfma_f32_16x16x32_bf16 v[90:93], v[138:141], v[192:195], v[90:93]
	v_mfma_f32_16x16x32_bf16 v[90:93], v[142:145], v[196:199], v[90:93]
	v_mfma_f32_16x16x32_bf16 v[78:81], v[130:133], v[200:203], v[78:81]
	v_mfma_f32_16x16x32_bf16 v[78:81], v[134:137], v[204:207], v[78:81]
	v_mfma_f32_16x16x32_bf16 v[74:77], v[138:141], v[200:203], v[74:77]
	v_mfma_f32_16x16x32_bf16 v[74:77], v[142:145], v[204:207], v[74:77]
	v_mfma_f32_16x16x32_bf16 v[118:121], v[154:157], v[176:179], v[118:121]
	v_mfma_f32_16x16x32_bf16 v[118:121], v[164:167], v[180:183], v[118:121]
	v_mfma_f32_16x16x32_bf16 v[114:117], v[168:171], v[176:179], v[114:117]
	v_mfma_f32_16x16x32_bf16 v[114:117], v[172:175], v[180:183], v[114:117]
	v_mfma_f32_16x16x32_bf16 v[102:105], v[154:157], v[184:187], v[102:105]
	v_mfma_f32_16x16x32_bf16 v[102:105], v[164:167], v[188:191], v[102:105]
	v_mfma_f32_16x16x32_bf16 v[98:101], v[168:171], v[184:187], v[98:101]
	v_mfma_f32_16x16x32_bf16 v[98:101], v[172:175], v[188:191], v[98:101]
	v_mfma_f32_16x16x32_bf16 v[86:89], v[154:157], v[192:195], v[86:89]
	v_mfma_f32_16x16x32_bf16 v[86:89], v[164:167], v[196:199], v[86:89]
	v_mfma_f32_16x16x32_bf16 v[82:85], v[168:171], v[192:195], v[82:85]
	v_mfma_f32_16x16x32_bf16 v[82:85], v[172:175], v[196:199], v[82:85]
	v_mfma_f32_16x16x32_bf16 v[70:73], v[154:157], v[200:203], v[70:73]
	v_mfma_f32_16x16x32_bf16 v[70:73], v[164:167], v[204:207], v[70:73]
	v_mfma_f32_16x16x32_bf16 v[66:69], v[168:171], v[200:203], v[66:69]
	v_mfma_f32_16x16x32_bf16 v[66:69], v[172:175], v[204:207], v[66:69]
	s_setprio 0
	s_barrier
	s_mov_b32 m0, s66
	s_mov_b32 s6, s14
	s_mov_b32 s7, s15
	ds_read_b128 v[176:179], v163 offset:16384
	ds_read_b128 v[180:183], v163 offset:17408
	ds_read_b128 v[184:187], v163 offset:18432
	ds_read_b128 v[188:191], v163 offset:19456
	ds_read_b128 v[192:195], v163 offset:20480
	ds_read_b128 v[196:199], v163 offset:21504
	ds_read_b128 v[200:203], v163 offset:22528
	ds_read_b128 v[204:207], v163 offset:23552
	buffer_load_dwordx4 v160, s[4:7], s93 offen lds
	s_add_i32 s94, s93, 0x10000
	s_mov_b32 m0, s67
	s_nop 0
	buffer_load_dwordx4 v160, s[4:7], s94 offen lds
	s_add_i32 s94, s93, 0x20000
	s_mov_b32 m0, s68
	s_nop 0
	buffer_load_dwordx4 v160, s[4:7], s94 offen lds
	s_add_i32 s94, s93, 0x30000
	s_mov_b32 m0, s69
	s_nop 0
	buffer_load_dwordx4 v160, s[4:7], s94 offen lds
	s_mov_b32 m0, s65
	s_add_i32 s94, s91, 0x10000
	buffer_load_dwordx4 v161, s[12:15], s91 offen lds
	s_mov_b32 m0, s71
	s_nop 0
	buffer_load_dwordx4 v161, s[12:15], s94 offen lds
	s_waitcnt vmcnt(8)
	s_waitcnt lgkmcnt(0)
	s_setprio 1
	s_barrier
	v_mfma_f32_16x16x32_bf16 v[62:65], v[130:133], v[176:179], v[62:65]
	v_mfma_f32_16x16x32_bf16 v[62:65], v[134:137], v[180:183], v[62:65]
	v_mfma_f32_16x16x32_bf16 v[58:61], v[138:141], v[176:179], v[58:61]
	v_mfma_f32_16x16x32_bf16 v[58:61], v[142:145], v[180:183], v[58:61]
	v_mfma_f32_16x16x32_bf16 v[46:49], v[130:133], v[184:187], v[46:49]
	v_mfma_f32_16x16x32_bf16 v[46:49], v[134:137], v[188:191], v[46:49]
	v_mfma_f32_16x16x32_bf16 v[42:45], v[138:141], v[184:187], v[42:45]
	v_mfma_f32_16x16x32_bf16 v[42:45], v[142:145], v[188:191], v[42:45]
	v_mfma_f32_16x16x32_bf16 v[30:33], v[130:133], v[192:195], v[30:33]
	v_mfma_f32_16x16x32_bf16 v[30:33], v[134:137], v[196:199], v[30:33]
	v_mfma_f32_16x16x32_bf16 v[26:29], v[138:141], v[192:195], v[26:29]
	v_mfma_f32_16x16x32_bf16 v[26:29], v[142:145], v[196:199], v[26:29]
	v_mfma_f32_16x16x32_bf16 v[14:17], v[130:133], v[200:203], v[14:17]
	v_mfma_f32_16x16x32_bf16 v[14:17], v[134:137], v[204:207], v[14:17]
	v_mfma_f32_16x16x32_bf16 v[10:13], v[138:141], v[200:203], v[10:13]
	v_mfma_f32_16x16x32_bf16 v[10:13], v[142:145], v[204:207], v[10:13]
	v_mfma_f32_16x16x32_bf16 v[54:57], v[154:157], v[176:179], v[54:57]
	v_mfma_f32_16x16x32_bf16 v[54:57], v[164:167], v[180:183], v[54:57]
	v_mfma_f32_16x16x32_bf16 v[50:53], v[168:171], v[176:179], v[50:53]
	v_mfma_f32_16x16x32_bf16 v[50:53], v[172:175], v[180:183], v[50:53]
	v_mfma_f32_16x16x32_bf16 v[38:41], v[154:157], v[184:187], v[38:41]
	v_mfma_f32_16x16x32_bf16 v[38:41], v[164:167], v[188:191], v[38:41]
	v_mfma_f32_16x16x32_bf16 v[34:37], v[168:171], v[184:187], v[34:37]
	v_mfma_f32_16x16x32_bf16 v[34:37], v[172:175], v[188:191], v[34:37]
	v_mfma_f32_16x16x32_bf16 v[22:25], v[154:157], v[192:195], v[22:25]
	v_mfma_f32_16x16x32_bf16 v[22:25], v[164:167], v[196:199], v[22:25]
	v_mfma_f32_16x16x32_bf16 v[18:21], v[168:171], v[192:195], v[18:21]
	v_mfma_f32_16x16x32_bf16 v[18:21], v[172:175], v[196:199], v[18:21]
	v_mfma_f32_16x16x32_bf16 v[6:9], v[154:157], v[200:203], v[6:9]
	v_mfma_f32_16x16x32_bf16 v[6:9], v[164:167], v[204:207], v[6:9]
	v_mfma_f32_16x16x32_bf16 v[2:5], v[168:171], v[200:203], v[2:5]
	v_mfma_f32_16x16x32_bf16 v[2:5], v[172:175], v[204:207], v[2:5]
	s_setprio 0
	s_barrier
	v_add_u32_e32 v142, 0x18000, v162
	v_add_u32_e32 v150, 0x1c000, v162
	ds_read_b128 v[130:133], v142
	ds_read_b128 v[134:137], v142 offset:1024
	ds_read_b128 v[138:141], v142 offset:2048
	ds_read_b128 v[142:145], v142 offset:3072
	ds_read_b128 v[154:157], v150
	ds_read_b128 v[164:167], v150 offset:1024
	ds_read_b128 v[168:171], v150 offset:2048
	ds_read_b128 v[172:175], v150 offset:3072
	s_mov_b32 m0, s72
	s_add_i32 s94, s91, 0x20000
	ds_read_b128 v[176:179], v163 offset:32768
	ds_read_b128 v[180:183], v163 offset:33792
	ds_read_b128 v[184:187], v163 offset:34816
	ds_read_b128 v[188:191], v163 offset:35840
	ds_read_b128 v[192:195], v163 offset:36864
	ds_read_b128 v[196:199], v163 offset:37888
	ds_read_b128 v[200:203], v163 offset:38912
	ds_read_b128 v[204:207], v163 offset:39936
	buffer_load_dwordx4 v161, s[12:15], s94 offen lds
	s_add_i32 s94, s91, 0x30000
	s_mov_b32 m0, s73
	s_nop 0
	buffer_load_dwordx4 v161, s[12:15], s94 offen lds
	s_waitcnt vmcnt(8)
	s_waitcnt lgkmcnt(0)
	s_setprio 1
	s_barrier
	v_mfma_f32_16x16x32_bf16 v[126:129], v[130:133], v[176:179], v[126:129]
	v_mfma_f32_16x16x32_bf16 v[126:129], v[134:137], v[180:183], v[126:129]
	v_mfma_f32_16x16x32_bf16 v[122:125], v[138:141], v[176:179], v[122:125]
	v_mfma_f32_16x16x32_bf16 v[122:125], v[142:145], v[180:183], v[122:125]
	v_mfma_f32_16x16x32_bf16 v[110:113], v[130:133], v[184:187], v[110:113]
	v_mfma_f32_16x16x32_bf16 v[110:113], v[134:137], v[188:191], v[110:113]
	v_mfma_f32_16x16x32_bf16 v[106:109], v[138:141], v[184:187], v[106:109]
	v_mfma_f32_16x16x32_bf16 v[106:109], v[142:145], v[188:191], v[106:109]
	v_mfma_f32_16x16x32_bf16 v[94:97], v[130:133], v[192:195], v[94:97]
	v_mfma_f32_16x16x32_bf16 v[94:97], v[134:137], v[196:199], v[94:97]
	v_mfma_f32_16x16x32_bf16 v[90:93], v[138:141], v[192:195], v[90:93]
	v_mfma_f32_16x16x32_bf16 v[90:93], v[142:145], v[196:199], v[90:93]
	v_mfma_f32_16x16x32_bf16 v[78:81], v[130:133], v[200:203], v[78:81]
	v_mfma_f32_16x16x32_bf16 v[78:81], v[134:137], v[204:207], v[78:81]
	v_mfma_f32_16x16x32_bf16 v[74:77], v[138:141], v[200:203], v[74:77]
	v_mfma_f32_16x16x32_bf16 v[74:77], v[142:145], v[204:207], v[74:77]
	v_mfma_f32_16x16x32_bf16 v[118:121], v[154:157], v[176:179], v[118:121]
	v_mfma_f32_16x16x32_bf16 v[118:121], v[164:167], v[180:183], v[118:121]
	v_mfma_f32_16x16x32_bf16 v[114:117], v[168:171], v[176:179], v[114:117]
	v_mfma_f32_16x16x32_bf16 v[114:117], v[172:175], v[180:183], v[114:117]
	v_mfma_f32_16x16x32_bf16 v[102:105], v[154:157], v[184:187], v[102:105]
	v_mfma_f32_16x16x32_bf16 v[102:105], v[164:167], v[188:191], v[102:105]
	v_mfma_f32_16x16x32_bf16 v[98:101], v[168:171], v[184:187], v[98:101]
	v_mfma_f32_16x16x32_bf16 v[98:101], v[172:175], v[188:191], v[98:101]
	v_mfma_f32_16x16x32_bf16 v[86:89], v[154:157], v[192:195], v[86:89]
	v_mfma_f32_16x16x32_bf16 v[86:89], v[164:167], v[196:199], v[86:89]
	v_mfma_f32_16x16x32_bf16 v[82:85], v[168:171], v[192:195], v[82:85]
	v_mfma_f32_16x16x32_bf16 v[82:85], v[172:175], v[196:199], v[82:85]
	v_mfma_f32_16x16x32_bf16 v[70:73], v[154:157], v[200:203], v[70:73]
	v_mfma_f32_16x16x32_bf16 v[70:73], v[164:167], v[204:207], v[70:73]
	v_mfma_f32_16x16x32_bf16 v[66:69], v[168:171], v[200:203], v[66:69]
	v_mfma_f32_16x16x32_bf16 v[66:69], v[172:175], v[204:207], v[66:69]
	s_setprio 0
	s_barrier
	s_mov_b32 m0, s74
	s_or_b32 s94, s93, 0x80
	ds_read_b128 v[176:179], v163 offset:49152
	ds_read_b128 v[180:183], v163 offset:50176
	ds_read_b128 v[184:187], v163 offset:51200
	ds_read_b128 v[188:191], v163 offset:52224
	ds_read_b128 v[192:195], v163 offset:53248
	ds_read_b128 v[196:199], v163 offset:54272
	ds_read_b128 v[200:203], v163 offset:55296
	ds_read_b128 v[204:207], v163 offset:56320
	buffer_load_dwordx4 v160, s[4:7], s94 offen lds
	s_add_i32 s94, s93, 0x10080
	s_mov_b32 m0, s75
	s_add_i32 s91, s91, 0x10080
	buffer_load_dwordx4 v160, s[4:7], s94 offen lds
	s_add_i32 s94, s93, 0x20080
	s_mov_b32 m0, s78
	s_add_i32 s93, s93, 0x30080
	buffer_load_dwordx4 v160, s[4:7], s94 offen lds
	s_mov_b32 m0, s79
	s_nop 0
	buffer_load_dwordx4 v160, s[4:7], s93 offen lds
	s_mov_b32 m0, s76
	s_nop 0
	buffer_load_dwordx4 v161, s[12:15], s92 offen lds
	s_mov_b32 m0, s77
	s_nop 0
	buffer_load_dwordx4 v161, s[12:15], s91 offen lds
	s_waitcnt vmcnt(8)
	s_waitcnt lgkmcnt(0)
	s_setprio 1
	s_barrier
	v_mfma_f32_16x16x32_bf16 v[62:65], v[130:133], v[176:179], v[62:65]
	v_mfma_f32_16x16x32_bf16 v[62:65], v[134:137], v[180:183], v[62:65]
	v_mfma_f32_16x16x32_bf16 v[58:61], v[138:141], v[176:179], v[58:61]
	v_mfma_f32_16x16x32_bf16 v[58:61], v[142:145], v[180:183], v[58:61]
	v_mfma_f32_16x16x32_bf16 v[46:49], v[130:133], v[184:187], v[46:49]
	v_mfma_f32_16x16x32_bf16 v[46:49], v[134:137], v[188:191], v[46:49]
	v_mfma_f32_16x16x32_bf16 v[42:45], v[138:141], v[184:187], v[42:45]
	v_mfma_f32_16x16x32_bf16 v[42:45], v[142:145], v[188:191], v[42:45]
	v_mfma_f32_16x16x32_bf16 v[30:33], v[130:133], v[192:195], v[30:33]
	v_mfma_f32_16x16x32_bf16 v[30:33], v[134:137], v[196:199], v[30:33]
	v_mfma_f32_16x16x32_bf16 v[26:29], v[138:141], v[192:195], v[26:29]
	v_mfma_f32_16x16x32_bf16 v[26:29], v[142:145], v[196:199], v[26:29]
	v_mfma_f32_16x16x32_bf16 v[14:17], v[130:133], v[200:203], v[14:17]
	v_mfma_f32_16x16x32_bf16 v[14:17], v[134:137], v[204:207], v[14:17]
	v_mfma_f32_16x16x32_bf16 v[10:13], v[138:141], v[200:203], v[10:13]
	v_mfma_f32_16x16x32_bf16 v[10:13], v[142:145], v[204:207], v[10:13]
	v_mfma_f32_16x16x32_bf16 v[54:57], v[154:157], v[176:179], v[54:57]
	v_mfma_f32_16x16x32_bf16 v[54:57], v[164:167], v[180:183], v[54:57]
	v_mfma_f32_16x16x32_bf16 v[50:53], v[168:171], v[176:179], v[50:53]
	v_mfma_f32_16x16x32_bf16 v[50:53], v[172:175], v[180:183], v[50:53]
	v_mfma_f32_16x16x32_bf16 v[38:41], v[154:157], v[184:187], v[38:41]
	v_mfma_f32_16x16x32_bf16 v[38:41], v[164:167], v[188:191], v[38:41]
	v_mfma_f32_16x16x32_bf16 v[34:37], v[168:171], v[184:187], v[34:37]
	v_mfma_f32_16x16x32_bf16 v[34:37], v[172:175], v[188:191], v[34:37]
	v_mfma_f32_16x16x32_bf16 v[22:25], v[154:157], v[192:195], v[22:25]
	v_mfma_f32_16x16x32_bf16 v[22:25], v[164:167], v[196:199], v[22:25]
	v_mfma_f32_16x16x32_bf16 v[18:21], v[168:171], v[192:195], v[18:21]
	v_mfma_f32_16x16x32_bf16 v[18:21], v[172:175], v[196:199], v[18:21]
	v_mfma_f32_16x16x32_bf16 v[6:9], v[154:157], v[200:203], v[6:9]
	v_mfma_f32_16x16x32_bf16 v[6:9], v[164:167], v[204:207], v[6:9]
	v_mfma_f32_16x16x32_bf16 v[2:5], v[168:171], v[200:203], v[2:5]
	v_mfma_f32_16x16x32_bf16 v[2:5], v[172:175], v[204:207], v[2:5]
	s_setprio 0
	s_barrier
	s_add_i32 s89, s89, 2
	s_cmp_ge_i32 s89, s63
	s_mov_b32 s6, s90
	s_cbranch_scc0 .LBB0_1020
	s_and_b64 vcc, exec, s[54:55]
	s_cbranch_vccz .LBB0_1023

.LBB0_1035:
	ds_read_b128 v[140:143], v134
	ds_read_b128 v[148:151], v134 offset:1024
	ds_read_b128 v[152:155], v134 offset:2048
	ds_read_b128 v[156:159], v134 offset:3072
	ds_read_b128 v[160:163], v135
	ds_read_b128 v[164:167], v135 offset:1024
	ds_read_b128 v[168:171], v135 offset:2048
	ds_read_b128 v[172:175], v135 offset:3072
	s_add_i32 s73, s70, 0xfffb8080
	s_cmp_eq_u32 s53, s72
	s_cselect_b32 s73, s68, s73
	s_cselect_b32 s75, s69, s71
	s_add_i32 s74, s73, 0x80
	s_add_i32 s76, s70, 0xfffe8000
	s_mov_b32 m0, s54
	ds_read_b128 v[176:179], v136
	ds_read_b128 v[180:183], v136 offset:1024
	ds_read_b128 v[184:187], v136 offset:2048
	ds_read_b128 v[188:191], v136 offset:3072
	ds_read_b128 v[192:195], v136 offset:4096
	ds_read_b128 v[196:199], v136 offset:5120
	ds_read_b128 v[200:203], v136 offset:6144
	ds_read_b128 v[204:207], v136 offset:7168
	buffer_load_dwordx4 v132, s[12:15], s76 offen lds
	s_mov_b32 m0, s55
	s_nop 0
	buffer_load_dwordx4 v132, s[12:15], s70 offen lds
	s_waitcnt vmcnt(8)
	s_waitcnt lgkmcnt(0)
	s_setprio 1
	s_barrier
	v_mfma_f32_16x16x32_bf16 v[126:129], v[140:143], v[176:179], v[126:129]
	v_mfma_f32_16x16x32_bf16 v[126:129], v[148:151], v[180:183], v[126:129]
	v_mfma_f32_16x16x32_bf16 v[122:125], v[152:155], v[176:179], v[122:125]
	v_mfma_f32_16x16x32_bf16 v[122:125], v[156:159], v[180:183], v[122:125]
	v_mfma_f32_16x16x32_bf16 v[110:113], v[140:143], v[184:187], v[110:113]
	v_mfma_f32_16x16x32_bf16 v[110:113], v[148:151], v[188:191], v[110:113]
	v_mfma_f32_16x16x32_bf16 v[106:109], v[152:155], v[184:187], v[106:109]
	v_mfma_f32_16x16x32_bf16 v[106:109], v[156:159], v[188:191], v[106:109]
	v_mfma_f32_16x16x32_bf16 v[94:97], v[140:143], v[192:195], v[94:97]
	v_mfma_f32_16x16x32_bf16 v[94:97], v[148:151], v[196:199], v[94:97]
	v_mfma_f32_16x16x32_bf16 v[90:93], v[152:155], v[192:195], v[90:93]
	v_mfma_f32_16x16x32_bf16 v[90:93], v[156:159], v[196:199], v[90:93]
	v_mfma_f32_16x16x32_bf16 v[78:81], v[140:143], v[200:203], v[78:81]
	v_mfma_f32_16x16x32_bf16 v[78:81], v[148:151], v[204:207], v[78:81]
	v_mfma_f32_16x16x32_bf16 v[74:77], v[152:155], v[200:203], v[74:77]
	v_mfma_f32_16x16x32_bf16 v[74:77], v[156:159], v[204:207], v[74:77]
	v_mfma_f32_16x16x32_bf16 v[118:121], v[160:163], v[176:179], v[118:121]
	v_mfma_f32_16x16x32_bf16 v[118:121], v[164:167], v[180:183], v[118:121]
	v_mfma_f32_16x16x32_bf16 v[114:117], v[168:171], v[176:179], v[114:117]
	v_mfma_f32_16x16x32_bf16 v[114:117], v[172:175], v[180:183], v[114:117]
	v_mfma_f32_16x16x32_bf16 v[102:105], v[160:163], v[184:187], v[102:105]
	v_mfma_f32_16x16x32_bf16 v[102:105], v[164:167], v[188:191], v[102:105]
	v_mfma_f32_16x16x32_bf16 v[98:101], v[168:171], v[184:187], v[98:101]
	v_mfma_f32_16x16x32_bf16 v[98:101], v[172:175], v[188:191], v[98:101]
	v_mfma_f32_16x16x32_bf16 v[86:89], v[160:163], v[192:195], v[86:89]
	v_mfma_f32_16x16x32_bf16 v[86:89], v[164:167], v[196:199], v[86:89]
	v_mfma_f32_16x16x32_bf16 v[82:85], v[168:171], v[192:195], v[82:85]
	v_mfma_f32_16x16x32_bf16 v[82:85], v[172:175], v[196:199], v[82:85]
	v_mfma_f32_16x16x32_bf16 v[70:73], v[160:163], v[200:203], v[70:73]
	v_mfma_f32_16x16x32_bf16 v[70:73], v[164:167], v[204:207], v[70:73]
	v_mfma_f32_16x16x32_bf16 v[66:69], v[168:171], v[200:203], v[66:69]
	v_mfma_f32_16x16x32_bf16 v[66:69], v[172:175], v[204:207], v[66:69]
	s_setprio 0
	s_barrier
	s_mov_b32 m0, s30
	ds_read_b128 v[176:179], v136 offset:16384
	ds_read_b128 v[180:183], v136 offset:17408
	ds_read_b128 v[184:187], v136 offset:18432
	ds_read_b128 v[188:191], v136 offset:19456
	ds_read_b128 v[192:195], v136 offset:20480
	ds_read_b128 v[196:199], v136 offset:21504
	ds_read_b128 v[200:203], v136 offset:22528
	ds_read_b128 v[204:207], v136 offset:23552
	buffer_load_dwordx4 v133, s[16:19], s75 offen lds
	s_add_i32 s76, s75, 0x200000
	s_mov_b32 m0, s31
	s_nop 0
	buffer_load_dwordx4 v133, s[16:19], s76 offen lds
	s_add_i32 s76, s75, 0x400000
	s_mov_b32 m0, s35
	s_nop 0
	buffer_load_dwordx4 v133, s[16:19], s76 offen lds
	s_add_i32 s76, s75, 0x600000
	s_mov_b32 m0, s42
	s_nop 0
	buffer_load_dwordx4 v133, s[16:19], s76 offen lds
	s_mov_b32 m0, s27
	s_add_i32 s76, s73, 0x18000
	buffer_load_dwordx4 v132, s[12:15], s73 offen lds
	s_mov_b32 m0, s43
	s_nop 0
	buffer_load_dwordx4 v132, s[12:15], s76 offen lds
	s_waitcnt vmcnt(8)
	s_waitcnt lgkmcnt(0)
	s_setprio 1
	s_barrier
	v_mfma_f32_16x16x32_bf16 v[62:65], v[140:143], v[176:179], v[62:65]
	v_mfma_f32_16x16x32_bf16 v[62:65], v[148:151], v[180:183], v[62:65]
	v_mfma_f32_16x16x32_bf16 v[58:61], v[152:155], v[176:179], v[58:61]
	v_mfma_f32_16x16x32_bf16 v[58:61], v[156:159], v[180:183], v[58:61]
	v_mfma_f32_16x16x32_bf16 v[46:49], v[140:143], v[184:187], v[46:49]
	v_mfma_f32_16x16x32_bf16 v[46:49], v[148:151], v[188:191], v[46:49]
	v_mfma_f32_16x16x32_bf16 v[42:45], v[152:155], v[184:187], v[42:45]
	v_mfma_f32_16x16x32_bf16 v[42:45], v[156:159], v[188:191], v[42:45]
	v_mfma_f32_16x16x32_bf16 v[30:33], v[140:143], v[192:195], v[30:33]
	v_mfma_f32_16x16x32_bf16 v[30:33], v[148:151], v[196:199], v[30:33]
	v_mfma_f32_16x16x32_bf16 v[26:29], v[152:155], v[192:195], v[26:29]
	v_mfma_f32_16x16x32_bf16 v[26:29], v[156:159], v[196:199], v[26:29]
	v_mfma_f32_16x16x32_bf16 v[14:17], v[140:143], v[200:203], v[14:17]
	v_mfma_f32_16x16x32_bf16 v[14:17], v[148:151], v[204:207], v[14:17]
	v_mfma_f32_16x16x32_bf16 v[10:13], v[152:155], v[200:203], v[10:13]
	v_mfma_f32_16x16x32_bf16 v[10:13], v[156:159], v[204:207], v[10:13]
	v_mfma_f32_16x16x32_bf16 v[54:57], v[160:163], v[176:179], v[54:57]
	v_mfma_f32_16x16x32_bf16 v[54:57], v[164:167], v[180:183], v[54:57]
	v_mfma_f32_16x16x32_bf16 v[50:53], v[168:171], v[176:179], v[50:53]
	v_mfma_f32_16x16x32_bf16 v[50:53], v[172:175], v[180:183], v[50:53]
	v_mfma_f32_16x16x32_bf16 v[38:41], v[160:163], v[184:187], v[38:41]
	v_mfma_f32_16x16x32_bf16 v[38:41], v[164:167], v[188:191], v[38:41]
	v_mfma_f32_16x16x32_bf16 v[34:37], v[168:171], v[184:187], v[34:37]
	v_mfma_f32_16x16x32_bf16 v[34:37], v[172:175], v[188:191], v[34:37]
	v_mfma_f32_16x16x32_bf16 v[22:25], v[160:163], v[192:195], v[22:25]
	v_mfma_f32_16x16x32_bf16 v[22:25], v[164:167], v[196:199], v[22:25]
	v_mfma_f32_16x16x32_bf16 v[18:21], v[168:171], v[192:195], v[18:21]
	v_mfma_f32_16x16x32_bf16 v[18:21], v[172:175], v[196:199], v[18:21]
	v_mfma_f32_16x16x32_bf16 v[6:9], v[160:163], v[200:203], v[6:9]
	v_mfma_f32_16x16x32_bf16 v[6:9], v[164:167], v[204:207], v[6:9]
	v_mfma_f32_16x16x32_bf16 v[2:5], v[168:171], v[200:203], v[2:5]
	v_mfma_f32_16x16x32_bf16 v[2:5], v[172:175], v[204:207], v[2:5]
	s_setprio 0
	s_barrier
	ds_read_b128 v[140:143], v137
	ds_read_b128 v[148:151], v137 offset:1024
	ds_read_b128 v[152:155], v137 offset:2048
	ds_read_b128 v[156:159], v137 offset:3072
	ds_read_b128 v[160:163], v138
	ds_read_b128 v[164:167], v138 offset:1024
	ds_read_b128 v[168:171], v138 offset:2048
	ds_read_b128 v[172:175], v138 offset:3072
	s_mov_b32 m0, s44
	s_add_i32 s76, s73, 0x30000
	ds_read_b128 v[176:179], v136 offset:32768
	ds_read_b128 v[180:183], v136 offset:33792
	ds_read_b128 v[184:187], v136 offset:34816
	ds_read_b128 v[188:191], v136 offset:35840
	ds_read_b128 v[192:195], v136 offset:36864
	ds_read_b128 v[196:199], v136 offset:37888
	ds_read_b128 v[200:203], v136 offset:38912
	ds_read_b128 v[204:207], v136 offset:39936
	buffer_load_dwordx4 v132, s[12:15], s76 offen lds
	s_add_i32 s76, s73, 0x48000
	s_mov_b32 m0, s45
	s_nop 0
	buffer_load_dwordx4 v132, s[12:15], s76 offen lds
	s_waitcnt vmcnt(8)
	s_waitcnt lgkmcnt(0)
	s_setprio 1
	s_barrier
	v_mfma_f32_16x16x32_bf16 v[126:129], v[140:143], v[176:179], v[126:129]
	v_mfma_f32_16x16x32_bf16 v[126:129], v[148:151], v[180:183], v[126:129]
	v_mfma_f32_16x16x32_bf16 v[122:125], v[152:155], v[176:179], v[122:125]
	v_mfma_f32_16x16x32_bf16 v[122:125], v[156:159], v[180:183], v[122:125]
	v_mfma_f32_16x16x32_bf16 v[110:113], v[140:143], v[184:187], v[110:113]
	v_mfma_f32_16x16x32_bf16 v[110:113], v[148:151], v[188:191], v[110:113]
	v_mfma_f32_16x16x32_bf16 v[106:109], v[152:155], v[184:187], v[106:109]
	v_mfma_f32_16x16x32_bf16 v[106:109], v[156:159], v[188:191], v[106:109]
	v_mfma_f32_16x16x32_bf16 v[94:97], v[140:143], v[192:195], v[94:97]
	v_mfma_f32_16x16x32_bf16 v[94:97], v[148:151], v[196:199], v[94:97]
	v_mfma_f32_16x16x32_bf16 v[90:93], v[152:155], v[192:195], v[90:93]
	v_mfma_f32_16x16x32_bf16 v[90:93], v[156:159], v[196:199], v[90:93]
	v_mfma_f32_16x16x32_bf16 v[78:81], v[140:143], v[200:203], v[78:81]
	v_mfma_f32_16x16x32_bf16 v[78:81], v[148:151], v[204:207], v[78:81]
	v_mfma_f32_16x16x32_bf16 v[74:77], v[152:155], v[200:203], v[74:77]
	v_mfma_f32_16x16x32_bf16 v[74:77], v[156:159], v[204:207], v[74:77]
	v_mfma_f32_16x16x32_bf16 v[118:121], v[160:163], v[176:179], v[118:121]
	v_mfma_f32_16x16x32_bf16 v[118:121], v[164:167], v[180:183], v[118:121]
	v_mfma_f32_16x16x32_bf16 v[114:117], v[168:171], v[176:179], v[114:117]
	v_mfma_f32_16x16x32_bf16 v[114:117], v[172:175], v[180:183], v[114:117]
	v_mfma_f32_16x16x32_bf16 v[102:105], v[160:163], v[184:187], v[102:105]
	v_mfma_f32_16x16x32_bf16 v[102:105], v[164:167], v[188:191], v[102:105]
	v_mfma_f32_16x16x32_bf16 v[98:101], v[168:171], v[184:187], v[98:101]
	v_mfma_f32_16x16x32_bf16 v[98:101], v[172:175], v[188:191], v[98:101]
	v_mfma_f32_16x16x32_bf16 v[86:89], v[160:163], v[192:195], v[86:89]
	v_mfma_f32_16x16x32_bf16 v[86:89], v[164:167], v[196:199], v[86:89]
	v_mfma_f32_16x16x32_bf16 v[82:85], v[168:171], v[192:195], v[82:85]
	v_mfma_f32_16x16x32_bf16 v[82:85], v[172:175], v[196:199], v[82:85]
	v_mfma_f32_16x16x32_bf16 v[70:73], v[160:163], v[200:203], v[70:73]
	v_mfma_f32_16x16x32_bf16 v[70:73], v[164:167], v[204:207], v[70:73]
	v_mfma_f32_16x16x32_bf16 v[66:69], v[168:171], v[200:203], v[66:69]
	v_mfma_f32_16x16x32_bf16 v[66:69], v[172:175], v[204:207], v[66:69]
	s_setprio 0
	s_barrier
	s_mov_b32 m0, s46
	s_add_i32 s76, s75, 0x80
	ds_read_b128 v[176:179], v136 offset:49152
	ds_read_b128 v[180:183], v136 offset:50176
	ds_read_b128 v[184:187], v136 offset:51200
	ds_read_b128 v[188:191], v136 offset:52224
	ds_read_b128 v[192:195], v136 offset:53248
	ds_read_b128 v[196:199], v136 offset:54272
	ds_read_b128 v[200:203], v136 offset:55296
	ds_read_b128 v[204:207], v136 offset:56320
	buffer_load_dwordx4 v133, s[16:19], s76 offen lds
	s_add_i32 s76, s75, 0x200080
	s_mov_b32 m0, s47
	s_add_i32 s73, s73, 0x18080
	buffer_load_dwordx4 v133, s[16:19], s76 offen lds
	s_add_i32 s76, s75, 0x400080
	s_mov_b32 m0, s50
	s_add_i32 s75, s75, 0x600080
	buffer_load_dwordx4 v133, s[16:19], s76 offen lds
	s_mov_b32 m0, s51
	s_nop 0
	buffer_load_dwordx4 v133, s[16:19], s75 offen lds
	s_mov_b32 m0, s48
	s_nop 0
	buffer_load_dwordx4 v132, s[12:15], s74 offen lds
	s_mov_b32 m0, s49
	s_nop 0
	buffer_load_dwordx4 v132, s[12:15], s73 offen lds
	s_waitcnt vmcnt(8)
	s_waitcnt lgkmcnt(0)
	s_setprio 1
	s_barrier
	v_mfma_f32_16x16x32_bf16 v[62:65], v[140:143], v[176:179], v[62:65]
	v_mfma_f32_16x16x32_bf16 v[62:65], v[148:151], v[180:183], v[62:65]
	v_mfma_f32_16x16x32_bf16 v[58:61], v[152:155], v[176:179], v[58:61]
	v_mfma_f32_16x16x32_bf16 v[58:61], v[156:159], v[180:183], v[58:61]
	v_mfma_f32_16x16x32_bf16 v[46:49], v[140:143], v[184:187], v[46:49]
	v_mfma_f32_16x16x32_bf16 v[46:49], v[148:151], v[188:191], v[46:49]
	v_mfma_f32_16x16x32_bf16 v[42:45], v[152:155], v[184:187], v[42:45]
	v_mfma_f32_16x16x32_bf16 v[42:45], v[156:159], v[188:191], v[42:45]
	v_mfma_f32_16x16x32_bf16 v[30:33], v[140:143], v[192:195], v[30:33]
	v_mfma_f32_16x16x32_bf16 v[30:33], v[148:151], v[196:199], v[30:33]
	v_mfma_f32_16x16x32_bf16 v[26:29], v[152:155], v[192:195], v[26:29]
	v_mfma_f32_16x16x32_bf16 v[26:29], v[156:159], v[196:199], v[26:29]
	v_mfma_f32_16x16x32_bf16 v[14:17], v[140:143], v[200:203], v[14:17]
	v_mfma_f32_16x16x32_bf16 v[14:17], v[148:151], v[204:207], v[14:17]
	v_mfma_f32_16x16x32_bf16 v[10:13], v[152:155], v[200:203], v[10:13]
	v_mfma_f32_16x16x32_bf16 v[10:13], v[156:159], v[204:207], v[10:13]
	v_mfma_f32_16x16x32_bf16 v[54:57], v[160:163], v[176:179], v[54:57]
	v_mfma_f32_16x16x32_bf16 v[54:57], v[164:167], v[180:183], v[54:57]
	v_mfma_f32_16x16x32_bf16 v[50:53], v[168:171], v[176:179], v[50:53]
	v_mfma_f32_16x16x32_bf16 v[50:53], v[172:175], v[180:183], v[50:53]
	v_mfma_f32_16x16x32_bf16 v[38:41], v[160:163], v[184:187], v[38:41]
	v_mfma_f32_16x16x32_bf16 v[38:41], v[164:167], v[188:191], v[38:41]
	v_mfma_f32_16x16x32_bf16 v[34:37], v[168:171], v[184:187], v[34:37]
	v_mfma_f32_16x16x32_bf16 v[34:37], v[172:175], v[188:191], v[34:37]
	v_mfma_f32_16x16x32_bf16 v[22:25], v[160:163], v[192:195], v[22:25]
	v_mfma_f32_16x16x32_bf16 v[22:25], v[164:167], v[196:199], v[22:25]
	v_mfma_f32_16x16x32_bf16 v[18:21], v[168:171], v[192:195], v[18:21]
	v_mfma_f32_16x16x32_bf16 v[18:21], v[172:175], v[196:199], v[18:21]
	v_mfma_f32_16x16x32_bf16 v[6:9], v[160:163], v[200:203], v[6:9]
	v_mfma_f32_16x16x32_bf16 v[6:9], v[164:167], v[204:207], v[6:9]
	v_mfma_f32_16x16x32_bf16 v[2:5], v[168:171], v[200:203], v[2:5]
	v_mfma_f32_16x16x32_bf16 v[2:5], v[172:175], v[204:207], v[2:5]
	s_setprio 0
	s_barrier
	s_add_i32 s72, s72, 2
	s_addk_i32 s70, 0x100
	s_addk_i32 s71, 0x100
	s_cmp_ge_i32 s72, s21
	s_cbranch_scc0 .LBB0_1035

.LBB0_1050:
	ds_read_b128 v[132:135], v142
	ds_read_b128 v[136:139], v142 offset:1024
	ds_read_b128 v[148:151], v142 offset:2048
	ds_read_b128 v[152:155], v142 offset:3072
	ds_read_b128 v[156:159], v143
	ds_read_b128 v[160:163], v143 offset:1024
	ds_read_b128 v[164:167], v143 offset:2048
	ds_read_b128 v[168:171], v143 offset:3072
	s_add_i32 s18, s61, 0xfff40080
	s_cmp_eq_u32 s54, s62
	s_cselect_b32 s64, s35, s18
	s_add_i32 s63, s64, 0x80
	s_add_i32 s18, s61, 0xfffc0000
	s_mov_b32 m0, s55
	ds_read_b128 v[172:175], v144
	ds_read_b128 v[176:179], v144 offset:1024
	ds_read_b128 v[180:183], v144 offset:2048
	ds_read_b128 v[184:187], v144 offset:3072
	ds_read_b128 v[188:191], v144 offset:4096
	ds_read_b128 v[192:195], v144 offset:5120
	ds_read_b128 v[196:199], v144 offset:6144
	ds_read_b128 v[200:203], v144 offset:7168
	buffer_load_dwordx4 v140, s[12:15], s18 offen lds
	s_mov_b32 m0, s56
	s_nop 0
	buffer_load_dwordx4 v140, s[12:15], s61 offen lds
	s_waitcnt vmcnt(8)
	s_waitcnt lgkmcnt(0)
	s_setprio 1
	s_barrier
	v_mfma_f32_16x16x32_bf16 v[126:129], v[132:135], v[172:175], v[126:129]
	v_mfma_f32_16x16x32_bf16 v[126:129], v[136:139], v[176:179], v[126:129]
	v_mfma_f32_16x16x32_bf16 v[122:125], v[148:151], v[172:175], v[122:125]
	v_mfma_f32_16x16x32_bf16 v[122:125], v[152:155], v[176:179], v[122:125]
	v_mfma_f32_16x16x32_bf16 v[110:113], v[132:135], v[180:183], v[110:113]
	v_mfma_f32_16x16x32_bf16 v[110:113], v[136:139], v[184:187], v[110:113]
	v_mfma_f32_16x16x32_bf16 v[106:109], v[148:151], v[180:183], v[106:109]
	v_mfma_f32_16x16x32_bf16 v[106:109], v[152:155], v[184:187], v[106:109]
	v_mfma_f32_16x16x32_bf16 v[94:97], v[132:135], v[188:191], v[94:97]
	v_mfma_f32_16x16x32_bf16 v[94:97], v[136:139], v[192:195], v[94:97]
	v_mfma_f32_16x16x32_bf16 v[90:93], v[148:151], v[188:191], v[90:93]
	v_mfma_f32_16x16x32_bf16 v[90:93], v[152:155], v[192:195], v[90:93]
	v_mfma_f32_16x16x32_bf16 v[78:81], v[132:135], v[196:199], v[78:81]
	v_mfma_f32_16x16x32_bf16 v[78:81], v[136:139], v[200:203], v[78:81]
	v_mfma_f32_16x16x32_bf16 v[74:77], v[148:151], v[196:199], v[74:77]
	v_mfma_f32_16x16x32_bf16 v[74:77], v[152:155], v[200:203], v[74:77]
	v_mfma_f32_16x16x32_bf16 v[118:121], v[156:159], v[172:175], v[118:121]
	v_mfma_f32_16x16x32_bf16 v[118:121], v[160:163], v[176:179], v[118:121]
	v_mfma_f32_16x16x32_bf16 v[114:117], v[164:167], v[172:175], v[114:117]
	v_mfma_f32_16x16x32_bf16 v[114:117], v[168:171], v[176:179], v[114:117]
	v_mfma_f32_16x16x32_bf16 v[102:105], v[156:159], v[180:183], v[102:105]
	v_mfma_f32_16x16x32_bf16 v[102:105], v[160:163], v[184:187], v[102:105]
	v_mfma_f32_16x16x32_bf16 v[98:101], v[164:167], v[180:183], v[98:101]
	v_mfma_f32_16x16x32_bf16 v[98:101], v[168:171], v[184:187], v[98:101]
	v_mfma_f32_16x16x32_bf16 v[86:89], v[156:159], v[188:191], v[86:89]
	v_mfma_f32_16x16x32_bf16 v[86:89], v[160:163], v[192:195], v[86:89]
	v_mfma_f32_16x16x32_bf16 v[82:85], v[164:167], v[188:191], v[82:85]
	v_mfma_f32_16x16x32_bf16 v[82:85], v[168:171], v[192:195], v[82:85]
	v_mfma_f32_16x16x32_bf16 v[70:73], v[156:159], v[196:199], v[70:73]
	v_mfma_f32_16x16x32_bf16 v[70:73], v[160:163], v[200:203], v[70:73]
	v_mfma_f32_16x16x32_bf16 v[66:69], v[164:167], v[196:199], v[66:69]
	v_mfma_f32_16x16x32_bf16 v[66:69], v[168:171], v[200:203], v[66:69]
	s_setprio 0
	s_barrier
	s_mov_b32 m0, s25
	s_mov_b32 s18, s14
	s_mov_b32 s19, s15
	ds_read_b128 v[172:175], v144 offset:16384
	ds_read_b128 v[176:179], v144 offset:17408
	ds_read_b128 v[180:183], v144 offset:18432
	ds_read_b128 v[184:187], v144 offset:19456
	ds_read_b128 v[188:191], v144 offset:20480
	ds_read_b128 v[192:195], v144 offset:21504
	ds_read_b128 v[196:199], v144 offset:22528
	ds_read_b128 v[200:203], v144 offset:23552
	buffer_load_dwordx4 v141, s[16:19], s64 offen lds
	s_add_i32 s65, s64, 0x40000
	s_mov_b32 m0, s27
	s_add_i32 s66, s64, 0x80000
	buffer_load_dwordx4 v141, s[16:19], s65 offen lds
	s_mov_b32 m0, s30
	s_add_i32 s67, s64, 0xc0000
	buffer_load_dwordx4 v141, s[16:19], s66 offen lds
	s_mov_b32 m0, s31
	s_nop 0
	buffer_load_dwordx4 v141, s[16:19], s67 offen lds
	s_mov_b32 m0, s21
	s_nop 0
	buffer_load_dwordx4 v140, s[12:15], s64 offen lds
	s_mov_b32 m0, s38
	s_nop 0
	buffer_load_dwordx4 v140, s[12:15], s65 offen lds
	s_waitcnt vmcnt(8)
	s_waitcnt lgkmcnt(0)
	s_setprio 1
	s_barrier
	v_mfma_f32_16x16x32_bf16 v[62:65], v[132:135], v[172:175], v[62:65]
	v_mfma_f32_16x16x32_bf16 v[62:65], v[136:139], v[176:179], v[62:65]
	v_mfma_f32_16x16x32_bf16 v[58:61], v[148:151], v[172:175], v[58:61]
	v_mfma_f32_16x16x32_bf16 v[58:61], v[152:155], v[176:179], v[58:61]
	v_mfma_f32_16x16x32_bf16 v[46:49], v[132:135], v[180:183], v[46:49]
	v_mfma_f32_16x16x32_bf16 v[46:49], v[136:139], v[184:187], v[46:49]
	v_mfma_f32_16x16x32_bf16 v[42:45], v[148:151], v[180:183], v[42:45]
	v_mfma_f32_16x16x32_bf16 v[42:45], v[152:155], v[184:187], v[42:45]
	v_mfma_f32_16x16x32_bf16 v[30:33], v[132:135], v[188:191], v[30:33]
	v_mfma_f32_16x16x32_bf16 v[30:33], v[136:139], v[192:195], v[30:33]
	v_mfma_f32_16x16x32_bf16 v[26:29], v[148:151], v[188:191], v[26:29]
	v_mfma_f32_16x16x32_bf16 v[26:29], v[152:155], v[192:195], v[26:29]
	v_mfma_f32_16x16x32_bf16 v[14:17], v[132:135], v[196:199], v[14:17]
	v_mfma_f32_16x16x32_bf16 v[14:17], v[136:139], v[200:203], v[14:17]
	v_mfma_f32_16x16x32_bf16 v[10:13], v[148:151], v[196:199], v[10:13]
	v_mfma_f32_16x16x32_bf16 v[10:13], v[152:155], v[200:203], v[10:13]
	v_mfma_f32_16x16x32_bf16 v[54:57], v[156:159], v[172:175], v[54:57]
	v_mfma_f32_16x16x32_bf16 v[54:57], v[160:163], v[176:179], v[54:57]
	v_mfma_f32_16x16x32_bf16 v[50:53], v[164:167], v[172:175], v[50:53]
	v_mfma_f32_16x16x32_bf16 v[50:53], v[168:171], v[176:179], v[50:53]
	v_mfma_f32_16x16x32_bf16 v[38:41], v[156:159], v[180:183], v[38:41]
	v_mfma_f32_16x16x32_bf16 v[38:41], v[160:163], v[184:187], v[38:41]
	v_mfma_f32_16x16x32_bf16 v[34:37], v[164:167], v[180:183], v[34:37]
	v_mfma_f32_16x16x32_bf16 v[34:37], v[168:171], v[184:187], v[34:37]
	v_mfma_f32_16x16x32_bf16 v[22:25], v[156:159], v[188:191], v[22:25]
	v_mfma_f32_16x16x32_bf16 v[22:25], v[160:163], v[192:195], v[22:25]
	v_mfma_f32_16x16x32_bf16 v[18:21], v[164:167], v[188:191], v[18:21]
	v_mfma_f32_16x16x32_bf16 v[18:21], v[168:171], v[192:195], v[18:21]
	v_mfma_f32_16x16x32_bf16 v[6:9], v[156:159], v[196:199], v[6:9]
	v_mfma_f32_16x16x32_bf16 v[6:9], v[160:163], v[200:203], v[6:9]
	v_mfma_f32_16x16x32_bf16 v[2:5], v[164:167], v[196:199], v[2:5]
	v_mfma_f32_16x16x32_bf16 v[2:5], v[168:171], v[200:203], v[2:5]
	s_setprio 0
	s_barrier
	ds_read_b128 v[132:135], v145
	ds_read_b128 v[136:139], v145 offset:1024
	ds_read_b128 v[148:151], v145 offset:2048
	ds_read_b128 v[152:155], v145 offset:3072
	ds_read_b128 v[156:159], v147
	ds_read_b128 v[160:163], v147 offset:1024
	ds_read_b128 v[164:167], v147 offset:2048
	ds_read_b128 v[168:171], v147 offset:3072
	s_mov_b32 m0, s39
	ds_read_b128 v[172:175], v144 offset:32768
	ds_read_b128 v[176:179], v144 offset:33792
	ds_read_b128 v[180:183], v144 offset:34816
	ds_read_b128 v[184:187], v144 offset:35840
	ds_read_b128 v[188:191], v144 offset:36864
	ds_read_b128 v[192:195], v144 offset:37888
	ds_read_b128 v[196:199], v144 offset:38912
	ds_read_b128 v[200:203], v144 offset:39936
	buffer_load_dwordx4 v140, s[12:15], s66 offen lds
	s_mov_b32 m0, s40
	s_nop 0
	buffer_load_dwordx4 v140, s[12:15], s67 offen lds
	s_waitcnt vmcnt(8)
	s_waitcnt lgkmcnt(0)
	s_setprio 1
	s_barrier
	v_mfma_f32_16x16x32_bf16 v[126:129], v[132:135], v[172:175], v[126:129]
	v_mfma_f32_16x16x32_bf16 v[126:129], v[136:139], v[176:179], v[126:129]
	v_mfma_f32_16x16x32_bf16 v[122:125], v[148:151], v[172:175], v[122:125]
	v_mfma_f32_16x16x32_bf16 v[122:125], v[152:155], v[176:179], v[122:125]
	v_mfma_f32_16x16x32_bf16 v[110:113], v[132:135], v[180:183], v[110:113]
	v_mfma_f32_16x16x32_bf16 v[110:113], v[136:139], v[184:187], v[110:113]
	v_mfma_f32_16x16x32_bf16 v[106:109], v[148:151], v[180:183], v[106:109]
	v_mfma_f32_16x16x32_bf16 v[106:109], v[152:155], v[184:187], v[106:109]
	v_mfma_f32_16x16x32_bf16 v[94:97], v[132:135], v[188:191], v[94:97]
	v_mfma_f32_16x16x32_bf16 v[94:97], v[136:139], v[192:195], v[94:97]
	v_mfma_f32_16x16x32_bf16 v[90:93], v[148:151], v[188:191], v[90:93]
	v_mfma_f32_16x16x32_bf16 v[90:93], v[152:155], v[192:195], v[90:93]
	v_mfma_f32_16x16x32_bf16 v[78:81], v[132:135], v[196:199], v[78:81]
	v_mfma_f32_16x16x32_bf16 v[78:81], v[136:139], v[200:203], v[78:81]
	v_mfma_f32_16x16x32_bf16 v[74:77], v[148:151], v[196:199], v[74:77]
	v_mfma_f32_16x16x32_bf16 v[74:77], v[152:155], v[200:203], v[74:77]
	v_mfma_f32_16x16x32_bf16 v[118:121], v[156:159], v[172:175], v[118:121]
	v_mfma_f32_16x16x32_bf16 v[118:121], v[160:163], v[176:179], v[118:121]
	v_mfma_f32_16x16x32_bf16 v[114:117], v[164:167], v[172:175], v[114:117]
	v_mfma_f32_16x16x32_bf16 v[114:117], v[168:171], v[176:179], v[114:117]
	v_mfma_f32_16x16x32_bf16 v[102:105], v[156:159], v[180:183], v[102:105]
	v_mfma_f32_16x16x32_bf16 v[102:105], v[160:163], v[184:187], v[102:105]
	v_mfma_f32_16x16x32_bf16 v[98:101], v[164:167], v[180:183], v[98:101]
	v_mfma_f32_16x16x32_bf16 v[98:101], v[168:171], v[184:187], v[98:101]
	v_mfma_f32_16x16x32_bf16 v[86:89], v[156:159], v[188:191], v[86:89]
	v_mfma_f32_16x16x32_bf16 v[86:89], v[160:163], v[192:195], v[86:89]
	v_mfma_f32_16x16x32_bf16 v[82:85], v[164:167], v[188:191], v[82:85]
	v_mfma_f32_16x16x32_bf16 v[82:85], v[168:171], v[192:195], v[82:85]
	v_mfma_f32_16x16x32_bf16 v[70:73], v[156:159], v[196:199], v[70:73]
	v_mfma_f32_16x16x32_bf16 v[70:73], v[160:163], v[200:203], v[70:73]
	v_mfma_f32_16x16x32_bf16 v[66:69], v[164:167], v[196:199], v[66:69]
	v_mfma_f32_16x16x32_bf16 v[66:69], v[168:171], v[200:203], v[66:69]
	s_setprio 0
	s_barrier
	s_mov_b32 m0, s48
	ds_read_b128 v[172:175], v144 offset:49152
	ds_read_b128 v[176:179], v144 offset:50176
	ds_read_b128 v[180:183], v144 offset:51200
	ds_read_b128 v[184:187], v144 offset:52224
	ds_read_b128 v[188:191], v144 offset:53248
	ds_read_b128 v[192:195], v144 offset:54272
	ds_read_b128 v[196:199], v144 offset:55296
	ds_read_b128 v[200:203], v144 offset:56320
	buffer_load_dwordx4 v141, s[16:19], s63 offen lds
	s_add_i32 s65, s64, 0x40080
	s_mov_b32 m0, s49
	s_add_i32 s66, s64, 0x80080
	buffer_load_dwordx4 v141, s[16:19], s65 offen lds
	s_mov_b32 m0, s52
	s_add_i32 s64, s64, 0xc0080
	buffer_load_dwordx4 v141, s[16:19], s66 offen lds
	s_mov_b32 m0, s53
	s_nop 0
	buffer_load_dwordx4 v141, s[16:19], s64 offen lds
	s_mov_b32 m0, s50
	s_nop 0
	buffer_load_dwordx4 v140, s[12:15], s63 offen lds
	s_mov_b32 m0, s51
	s_nop 0
	buffer_load_dwordx4 v140, s[12:15], s65 offen lds
	s_waitcnt vmcnt(8)
	s_waitcnt lgkmcnt(0)
	s_setprio 1
	s_barrier
	v_mfma_f32_16x16x32_bf16 v[62:65], v[132:135], v[172:175], v[62:65]
	v_mfma_f32_16x16x32_bf16 v[62:65], v[136:139], v[176:179], v[62:65]
	v_mfma_f32_16x16x32_bf16 v[58:61], v[148:151], v[172:175], v[58:61]
	v_mfma_f32_16x16x32_bf16 v[58:61], v[152:155], v[176:179], v[58:61]
	v_mfma_f32_16x16x32_bf16 v[46:49], v[132:135], v[180:183], v[46:49]
	v_mfma_f32_16x16x32_bf16 v[46:49], v[136:139], v[184:187], v[46:49]
	v_mfma_f32_16x16x32_bf16 v[42:45], v[148:151], v[180:183], v[42:45]
	v_mfma_f32_16x16x32_bf16 v[42:45], v[152:155], v[184:187], v[42:45]
	v_mfma_f32_16x16x32_bf16 v[30:33], v[132:135], v[188:191], v[30:33]
	v_mfma_f32_16x16x32_bf16 v[30:33], v[136:139], v[192:195], v[30:33]
	v_mfma_f32_16x16x32_bf16 v[26:29], v[148:151], v[188:191], v[26:29]
	v_mfma_f32_16x16x32_bf16 v[26:29], v[152:155], v[192:195], v[26:29]
	v_mfma_f32_16x16x32_bf16 v[14:17], v[132:135], v[196:199], v[14:17]
	v_mfma_f32_16x16x32_bf16 v[14:17], v[136:139], v[200:203], v[14:17]
	v_mfma_f32_16x16x32_bf16 v[10:13], v[148:151], v[196:199], v[10:13]
	v_mfma_f32_16x16x32_bf16 v[10:13], v[152:155], v[200:203], v[10:13]
	v_mfma_f32_16x16x32_bf16 v[54:57], v[156:159], v[172:175], v[54:57]
	v_mfma_f32_16x16x32_bf16 v[54:57], v[160:163], v[176:179], v[54:57]
	v_mfma_f32_16x16x32_bf16 v[50:53], v[164:167], v[172:175], v[50:53]
	v_mfma_f32_16x16x32_bf16 v[50:53], v[168:171], v[176:179], v[50:53]
	v_mfma_f32_16x16x32_bf16 v[38:41], v[156:159], v[180:183], v[38:41]
	v_mfma_f32_16x16x32_bf16 v[38:41], v[160:163], v[184:187], v[38:41]
	v_mfma_f32_16x16x32_bf16 v[34:37], v[164:167], v[180:183], v[34:37]
	v_mfma_f32_16x16x32_bf16 v[34:37], v[168:171], v[184:187], v[34:37]
	v_mfma_f32_16x16x32_bf16 v[22:25], v[156:159], v[188:191], v[22:25]
	v_mfma_f32_16x16x32_bf16 v[22:25], v[160:163], v[192:195], v[22:25]
	v_mfma_f32_16x16x32_bf16 v[18:21], v[164:167], v[188:191], v[18:21]
	v_mfma_f32_16x16x32_bf16 v[18:21], v[168:171], v[192:195], v[18:21]
	v_mfma_f32_16x16x32_bf16 v[6:9], v[156:159], v[196:199], v[6:9]
	v_mfma_f32_16x16x32_bf16 v[6:9], v[160:163], v[200:203], v[6:9]
	v_mfma_f32_16x16x32_bf16 v[2:5], v[164:167], v[196:199], v[2:5]
	v_mfma_f32_16x16x32_bf16 v[2:5], v[168:171], v[200:203], v[2:5]
	s_setprio 0
	s_barrier
	s_add_i32 s62, s62, 2
	s_addk_i32 s61, 0x100
	s_cmp_ge_i32 s62, s3
	s_cbranch_scc0 .LBB0_1050

.LBB0_1181:
	v_add_u32_e32 v2, 0x10000, v232
	ds_read_b128 v[134:137], v2
	ds_read_b128 v[138:141], v2 offset:1024
	ds_read_b128 v[142:145], v2 offset:2048
	ds_read_b128 v[146:149], v2 offset:3072
	v_add_u32_e32 v2, 0x14000, v232
	ds_read_b128 v[150:153], v2
	ds_read_b128 v[154:157], v2 offset:1024
	ds_read_b128 v[158:161], v2 offset:2048
	ds_read_b128 v[162:165], v2 offset:3072
	s_add_i32 s50, s47, s90
	s_and_b64 s[18:19], exec, s[18:19]
	s_cselect_b32 s51, s88, s50
	s_add_i32 s50, s92, 0x80
	s_or_b32 s52, s51, 0x80
	s_add_i32 s18, s89, s93
	s_add_i32 s94, s94, 0x1bfffc80
	s_cmp_lt_u32 s91, 8
	s_cselect_b32 s18, s18, s94
	s_mov_b32 m0, s74
	s_add_i32 s19, s18, 0x80000
	ds_read_b128 v[166:169], v233
	ds_read_b128 v[170:173], v233 offset:1024
	ds_read_b128 v[174:177], v233 offset:2048
	ds_read_b128 v[178:181], v233 offset:3072
	ds_read_b128 v[182:185], v233 offset:4096
	ds_read_b128 v[186:189], v233 offset:5120
	ds_read_b128 v[190:193], v233 offset:6144
	ds_read_b128 v[194:197], v233 offset:7168
	buffer_load_dwordx4 v230, s[12:15], s19 offen lds
	s_add_i32 s18, s18, 0xc0000
	s_mov_b32 m0, s75
	s_nop 0
	buffer_load_dwordx4 v230, s[12:15], s18 offen lds
	s_waitcnt vmcnt(8)
	s_waitcnt lgkmcnt(0)
	s_setprio 1
	s_barrier
	v_mfma_f32_16x16x32_bf16 v[130:133], v[134:137], v[166:169], v[130:133]
	v_mfma_f32_16x16x32_bf16 v[130:133], v[138:141], v[170:173], v[130:133]
	v_mfma_f32_16x16x32_bf16 v[126:129], v[142:145], v[166:169], v[126:129]
	v_mfma_f32_16x16x32_bf16 v[126:129], v[146:149], v[170:173], v[126:129]
	v_mfma_f32_16x16x32_bf16 v[114:117], v[134:137], v[174:177], v[114:117]
	v_mfma_f32_16x16x32_bf16 v[114:117], v[138:141], v[178:181], v[114:117]
	v_mfma_f32_16x16x32_bf16 v[110:113], v[142:145], v[174:177], v[110:113]
	v_mfma_f32_16x16x32_bf16 v[110:113], v[146:149], v[178:181], v[110:113]
	v_mfma_f32_16x16x32_bf16 v[98:101], v[134:137], v[182:185], v[98:101]
	v_mfma_f32_16x16x32_bf16 v[98:101], v[138:141], v[186:189], v[98:101]
	v_mfma_f32_16x16x32_bf16 v[94:97], v[142:145], v[182:185], v[94:97]
	v_mfma_f32_16x16x32_bf16 v[94:97], v[146:149], v[186:189], v[94:97]
	v_mfma_f32_16x16x32_bf16 v[82:85], v[134:137], v[190:193], v[82:85]
	v_mfma_f32_16x16x32_bf16 v[82:85], v[138:141], v[194:197], v[82:85]
	v_mfma_f32_16x16x32_bf16 v[78:81], v[142:145], v[190:193], v[78:81]
	v_mfma_f32_16x16x32_bf16 v[78:81], v[146:149], v[194:197], v[78:81]
	v_mfma_f32_16x16x32_bf16 v[122:125], v[150:153], v[166:169], v[122:125]
	v_mfma_f32_16x16x32_bf16 v[122:125], v[154:157], v[170:173], v[122:125]
	v_mfma_f32_16x16x32_bf16 v[118:121], v[158:161], v[166:169], v[118:121]
	v_mfma_f32_16x16x32_bf16 v[118:121], v[162:165], v[170:173], v[118:121]
	v_mfma_f32_16x16x32_bf16 v[106:109], v[150:153], v[174:177], v[106:109]
	v_mfma_f32_16x16x32_bf16 v[106:109], v[154:157], v[178:181], v[106:109]
	v_mfma_f32_16x16x32_bf16 v[102:105], v[158:161], v[174:177], v[102:105]
	v_mfma_f32_16x16x32_bf16 v[102:105], v[162:165], v[178:181], v[102:105]
	v_mfma_f32_16x16x32_bf16 v[90:93], v[150:153], v[182:185], v[90:93]
	v_mfma_f32_16x16x32_bf16 v[90:93], v[154:157], v[186:189], v[90:93]
	v_mfma_f32_16x16x32_bf16 v[86:89], v[158:161], v[182:185], v[86:89]
	v_mfma_f32_16x16x32_bf16 v[86:89], v[162:165], v[186:189], v[86:89]
	v_mfma_f32_16x16x32_bf16 v[74:77], v[150:153], v[190:193], v[74:77]
	v_mfma_f32_16x16x32_bf16 v[74:77], v[154:157], v[194:197], v[74:77]
	v_mfma_f32_16x16x32_bf16 v[70:73], v[158:161], v[190:193], v[70:73]
	v_mfma_f32_16x16x32_bf16 v[70:73], v[162:165], v[194:197], v[70:73]
	s_setprio 0
	s_barrier
	s_mov_b32 m0, s27
	s_mov_b32 s18, s14
	s_mov_b32 s19, s15
	ds_read_b128 v[166:169], v233 offset:16384
	ds_read_b128 v[170:173], v233 offset:17408
	ds_read_b128 v[174:177], v233 offset:18432
	ds_read_b128 v[178:181], v233 offset:19456
	ds_read_b128 v[182:185], v233 offset:20480
	ds_read_b128 v[186:189], v233 offset:21504
	ds_read_b128 v[190:193], v233 offset:22528
	ds_read_b128 v[194:197], v233 offset:23552
	buffer_load_dwordx4 v231, s[16:19], s51 offen lds
	s_add_i32 s53, s51, 0x18000
	s_mov_b32 m0, s30
	s_nop 0
	buffer_load_dwordx4 v231, s[16:19], s53 offen lds
	s_add_i32 s53, s51, 0x30000
	s_mov_b32 m0, s31
	s_nop 0
	buffer_load_dwordx4 v231, s[16:19], s53 offen lds
	s_add_i32 s53, s51, 0x48000
	s_mov_b32 m0, s54
	s_nop 0
	buffer_load_dwordx4 v231, s[16:19], s53 offen lds
	s_mov_b32 m0, s25
	s_add_i32 s53, s92, 0x40000
	buffer_load_dwordx4 v230, s[12:15], s92 offen lds
	s_mov_b32 m0, s55
	s_nop 0
	buffer_load_dwordx4 v230, s[12:15], s53 offen lds
	s_waitcnt vmcnt(8)
	s_waitcnt lgkmcnt(0)
	s_setprio 1
	s_barrier
	v_mfma_f32_16x16x32_bf16 v[66:69], v[134:137], v[166:169], v[66:69]
	v_mfma_f32_16x16x32_bf16 v[62:65], v[142:145], v[166:169], v[62:65]
	v_mfma_f32_16x16x32_bf16 v[50:53], v[134:137], v[174:177], v[50:53]
	v_mfma_f32_16x16x32_bf16 v[46:49], v[142:145], v[174:177], v[46:49]
	v_mfma_f32_16x16x32_bf16 v[34:37], v[134:137], v[182:185], v[34:37]
	v_mfma_f32_16x16x32_bf16 v[30:33], v[142:145], v[182:185], v[30:33]
	v_mfma_f32_16x16x32_bf16 v[18:21], v[134:137], v[190:193], v[18:21]
	v_mfma_f32_16x16x32_bf16 v[14:17], v[142:145], v[190:193], v[14:17]
	v_mfma_f32_16x16x32_bf16 v[58:61], v[150:153], v[166:169], v[58:61]
	v_mfma_f32_16x16x32_bf16 v[54:57], v[158:161], v[166:169], v[54:57]
	v_mfma_f32_16x16x32_bf16 v[42:45], v[150:153], v[174:177], v[42:45]
	v_mfma_f32_16x16x32_bf16 v[38:41], v[158:161], v[174:177], v[38:41]
	v_mfma_f32_16x16x32_bf16 v[26:29], v[150:153], v[182:185], v[26:29]
	v_mfma_f32_16x16x32_bf16 v[22:25], v[158:161], v[182:185], v[22:25]
	v_mfma_f32_16x16x32_bf16 v[10:13], v[150:153], v[190:193], v[10:13]
	v_mfma_f32_16x16x32_bf16 v[4:7], v[158:161], v[190:193], v[6:9]
	v_mfma_f32_16x16x32_bf16 v[66:69], v[138:141], v[170:173], v[66:69]
	v_mfma_f32_16x16x32_bf16 v[62:65], v[146:149], v[170:173], v[62:65]
	v_mfma_f32_16x16x32_bf16 v[50:53], v[138:141], v[178:181], v[50:53]
	v_mfma_f32_16x16x32_bf16 v[46:49], v[146:149], v[178:181], v[46:49]
	v_mfma_f32_16x16x32_bf16 v[34:37], v[138:141], v[186:189], v[34:37]
	v_mfma_f32_16x16x32_bf16 v[30:33], v[146:149], v[186:189], v[30:33]
	v_mfma_f32_16x16x32_bf16 v[18:21], v[138:141], v[194:197], v[18:21]
	v_mfma_f32_16x16x32_bf16 v[14:17], v[146:149], v[194:197], v[14:17]
	v_mfma_f32_16x16x32_bf16 v[58:61], v[154:157], v[170:173], v[58:61]
	v_mfma_f32_16x16x32_bf16 v[54:57], v[162:165], v[170:173], v[54:57]
	v_mfma_f32_16x16x32_bf16 v[42:45], v[154:157], v[178:181], v[42:45]
	v_mfma_f32_16x16x32_bf16 v[38:41], v[162:165], v[178:181], v[38:41]
	v_mfma_f32_16x16x32_bf16 v[26:29], v[154:157], v[186:189], v[26:29]
	v_mfma_f32_16x16x32_bf16 v[22:25], v[162:165], v[186:189], v[22:25]
	v_mfma_f32_16x16x32_bf16 v[10:13], v[154:157], v[194:197], v[10:13]
	v_mfma_f32_16x16x32_bf16 v[4:7], v[162:165], v[194:197], v[4:7]
	s_setprio 0
	s_barrier
	v_add_u32_e32 v2, 0x18000, v232
	ds_read_b128 v[134:137], v2
	ds_read_b128 v[138:141], v2 offset:1024
	ds_read_b128 v[142:145], v2 offset:2048
	ds_read_b128 v[146:149], v2 offset:3072
	v_add_u32_e32 v2, 0x1c000, v232
	ds_read_b128 v[150:153], v2
	ds_read_b128 v[154:157], v2 offset:1024
	ds_read_b128 v[158:161], v2 offset:2048
	ds_read_b128 v[162:165], v2 offset:3072
	s_mov_b32 m0, s56
	s_add_i32 s53, s92, 0x80000
	ds_read_b128 v[166:169], v233 offset:32768
	ds_read_b128 v[170:173], v233 offset:33792
	ds_read_b128 v[174:177], v233 offset:34816
	ds_read_b128 v[178:181], v233 offset:35840
	ds_read_b128 v[182:185], v233 offset:36864
	ds_read_b128 v[186:189], v233 offset:37888
	ds_read_b128 v[190:193], v233 offset:38912
	ds_read_b128 v[194:197], v233 offset:39936
	buffer_load_dwordx4 v230, s[12:15], s53 offen lds
	s_add_i32 s53, s92, 0xc0000
	s_mov_b32 m0, s57
	s_nop 0
	buffer_load_dwordx4 v230, s[12:15], s53 offen lds
	s_waitcnt vmcnt(8)
	s_waitcnt lgkmcnt(0)
	s_setprio 1
	s_barrier
	v_mfma_f32_16x16x32_bf16 v[130:133], v[134:137], v[166:169], v[130:133]
	v_mfma_f32_16x16x32_bf16 v[130:133], v[138:141], v[170:173], v[130:133]
	v_mfma_f32_16x16x32_bf16 v[126:129], v[142:145], v[166:169], v[126:129]
	v_mfma_f32_16x16x32_bf16 v[126:129], v[146:149], v[170:173], v[126:129]
	v_mfma_f32_16x16x32_bf16 v[114:117], v[134:137], v[174:177], v[114:117]
	v_mfma_f32_16x16x32_bf16 v[114:117], v[138:141], v[178:181], v[114:117]
	v_mfma_f32_16x16x32_bf16 v[110:113], v[142:145], v[174:177], v[110:113]
	v_mfma_f32_16x16x32_bf16 v[110:113], v[146:149], v[178:181], v[110:113]
	v_mfma_f32_16x16x32_bf16 v[98:101], v[134:137], v[182:185], v[98:101]
	v_mfma_f32_16x16x32_bf16 v[98:101], v[138:141], v[186:189], v[98:101]
	v_mfma_f32_16x16x32_bf16 v[94:97], v[142:145], v[182:185], v[94:97]
	v_mfma_f32_16x16x32_bf16 v[94:97], v[146:149], v[186:189], v[94:97]
	v_mfma_f32_16x16x32_bf16 v[82:85], v[134:137], v[190:193], v[82:85]
	v_mfma_f32_16x16x32_bf16 v[82:85], v[138:141], v[194:197], v[82:85]
	v_mfma_f32_16x16x32_bf16 v[78:81], v[142:145], v[190:193], v[78:81]
	v_mfma_f32_16x16x32_bf16 v[78:81], v[146:149], v[194:197], v[78:81]
	v_mfma_f32_16x16x32_bf16 v[122:125], v[150:153], v[166:169], v[122:125]
	v_mfma_f32_16x16x32_bf16 v[122:125], v[154:157], v[170:173], v[122:125]
	v_mfma_f32_16x16x32_bf16 v[118:121], v[158:161], v[166:169], v[118:121]
	v_mfma_f32_16x16x32_bf16 v[118:121], v[162:165], v[170:173], v[118:121]
	v_mfma_f32_16x16x32_bf16 v[106:109], v[150:153], v[174:177], v[106:109]
	v_mfma_f32_16x16x32_bf16 v[106:109], v[154:157], v[178:181], v[106:109]
	v_mfma_f32_16x16x32_bf16 v[102:105], v[158:161], v[174:177], v[102:105]
	v_mfma_f32_16x16x32_bf16 v[102:105], v[162:165], v[178:181], v[102:105]
	v_mfma_f32_16x16x32_bf16 v[90:93], v[150:153], v[182:185], v[90:93]
	v_mfma_f32_16x16x32_bf16 v[90:93], v[154:157], v[186:189], v[90:93]
	v_mfma_f32_16x16x32_bf16 v[86:89], v[158:161], v[182:185], v[86:89]
	v_mfma_f32_16x16x32_bf16 v[86:89], v[162:165], v[186:189], v[86:89]
	v_mfma_f32_16x16x32_bf16 v[74:77], v[150:153], v[190:193], v[74:77]
	v_mfma_f32_16x16x32_bf16 v[74:77], v[154:157], v[194:197], v[74:77]
	v_mfma_f32_16x16x32_bf16 v[70:73], v[158:161], v[190:193], v[70:73]
	v_mfma_f32_16x16x32_bf16 v[70:73], v[162:165], v[194:197], v[70:73]
	s_setprio 0
	s_barrier
	s_mov_b32 m0, s64
	ds_read_b128 v[166:169], v233 offset:49152
	ds_read_b128 v[170:173], v233 offset:50176
	ds_read_b128 v[174:177], v233 offset:51200
	ds_read_b128 v[178:181], v233 offset:52224
	ds_read_b128 v[182:185], v233 offset:53248
	ds_read_b128 v[186:189], v233 offset:54272
	ds_read_b128 v[190:193], v233 offset:55296
	ds_read_b128 v[194:197], v233 offset:56320
	buffer_load_dwordx4 v231, s[16:19], s52 offen lds
	s_add_i32 s52, s51, 0x18080
	s_mov_b32 m0, s65
	s_nop 0
	buffer_load_dwordx4 v231, s[16:19], s52 offen lds
	s_add_i32 s52, s51, 0x30080
	s_mov_b32 m0, s68
	s_add_i32 s51, s51, 0x48080
	buffer_load_dwordx4 v231, s[16:19], s52 offen lds
	s_mov_b32 m0, s69
	s_nop 0
	buffer_load_dwordx4 v231, s[16:19], s51 offen lds
	s_mov_b32 m0, s66
	s_add_i32 s18, s92, 0x40080
	buffer_load_dwordx4 v230, s[12:15], s50 offen lds
	s_mov_b32 m0, s67
	s_nop 0
	buffer_load_dwordx4 v230, s[12:15], s18 offen lds
	s_waitcnt vmcnt(8)
	s_waitcnt lgkmcnt(0)
	s_setprio 1
	s_barrier
	v_mfma_f32_16x16x32_bf16 v[66:69], v[134:137], v[166:169], v[66:69]
	v_mfma_f32_16x16x32_bf16 v[62:65], v[142:145], v[166:169], v[62:65]
	v_mfma_f32_16x16x32_bf16 v[50:53], v[134:137], v[174:177], v[50:53]
	v_mfma_f32_16x16x32_bf16 v[46:49], v[142:145], v[174:177], v[46:49]
	v_mfma_f32_16x16x32_bf16 v[34:37], v[134:137], v[182:185], v[34:37]
	v_mfma_f32_16x16x32_bf16 v[30:33], v[142:145], v[182:185], v[30:33]
	v_mfma_f32_16x16x32_bf16 v[18:21], v[134:137], v[190:193], v[18:21]
	v_mfma_f32_16x16x32_bf16 v[14:17], v[142:145], v[190:193], v[14:17]
	v_mfma_f32_16x16x32_bf16 v[58:61], v[150:153], v[166:169], v[58:61]
	v_mfma_f32_16x16x32_bf16 v[54:57], v[158:161], v[166:169], v[54:57]
	v_mfma_f32_16x16x32_bf16 v[42:45], v[150:153], v[174:177], v[42:45]
	v_mfma_f32_16x16x32_bf16 v[38:41], v[158:161], v[174:177], v[38:41]
	v_mfma_f32_16x16x32_bf16 v[26:29], v[150:153], v[182:185], v[26:29]
	v_mfma_f32_16x16x32_bf16 v[22:25], v[158:161], v[182:185], v[22:25]
	v_mfma_f32_16x16x32_bf16 v[8:11], v[150:153], v[190:193], v[10:13]
	v_mfma_f32_16x16x32_bf16 v[4:7], v[158:161], v[190:193], v[4:7]
	v_mfma_f32_16x16x32_bf16 v[66:69], v[138:141], v[170:173], v[66:69]
	v_mfma_f32_16x16x32_bf16 v[62:65], v[146:149], v[170:173], v[62:65]
	v_mfma_f32_16x16x32_bf16 v[50:53], v[138:141], v[178:181], v[50:53]
	v_mfma_f32_16x16x32_bf16 v[46:49], v[146:149], v[178:181], v[46:49]
	v_mfma_f32_16x16x32_bf16 v[34:37], v[138:141], v[186:189], v[34:37]
	v_mfma_f32_16x16x32_bf16 v[30:33], v[146:149], v[186:189], v[30:33]
	v_mfma_f32_16x16x32_bf16 v[18:21], v[138:141], v[194:197], v[18:21]
	v_mfma_f32_16x16x32_bf16 v[14:17], v[146:149], v[194:197], v[14:17]
	v_mfma_f32_16x16x32_bf16 v[58:61], v[154:157], v[170:173], v[58:61]
	v_mfma_f32_16x16x32_bf16 v[54:57], v[162:165], v[170:173], v[54:57]
	v_mfma_f32_16x16x32_bf16 v[42:45], v[154:157], v[178:181], v[42:45]
	v_mfma_f32_16x16x32_bf16 v[38:41], v[162:165], v[178:181], v[38:41]
	v_mfma_f32_16x16x32_bf16 v[26:29], v[154:157], v[186:189], v[26:29]
	v_mfma_f32_16x16x32_bf16 v[22:25], v[162:165], v[186:189], v[22:25]
	v_mfma_f32_16x16x32_bf16 v[10:13], v[154:157], v[194:197], v[8:11]
	v_mfma_f32_16x16x32_bf16 v[6:9], v[162:165], v[194:197], v[4:7]
	s_setprio 0
	s_barrier
	s_add_i32 s91, s91, 2
	s_addk_i32 s90, 0x100
	s_cmp_ge_i32 s91, s3
	s_cbranch_scc1 .LBB0_1193

.LBB0_1290:
	ds_read_b128 v[106:109], v224
	ds_read_b128 v[118:121], v224 offset:1024
	ds_read_b128 v[130:133], v224 offset:2048
	ds_read_b128 v[138:141], v224 offset:3072
	ds_read_b128 v[146:149], v225
	ds_read_b128 v[150:153], v225 offset:1024
	ds_read_b128 v[154:157], v225 offset:2048
	ds_read_b128 v[158:161], v225 offset:3072
	s_add_i32 s18, s72, 0xffe80080
	s_cmp_eq_u32 s56, s74
	s_cselect_b32 s75, s6, s18
	s_cselect_b32 s77, s7, s73
	s_or_b32 s76, s75, 0x80
	s_add_i32 s18, s72, 0xfff80000
	s_mov_b32 m0, s57
	ds_read_b128 v[162:165], v226
	ds_read_b128 v[166:169], v226 offset:1024
	ds_read_b128 v[170:173], v226 offset:2048
	ds_read_b128 v[174:177], v226 offset:3072
	ds_read_b128 v[178:181], v226 offset:4096
	ds_read_b128 v[182:185], v226 offset:5120
	ds_read_b128 v[190:193], v226 offset:6144
	ds_read_b128 v[194:197], v226 offset:7168
	buffer_load_dwordx4 v222, s[12:15], s18 offen lds
	s_mov_b32 m0, s60
	s_nop 0
	buffer_load_dwordx4 v222, s[12:15], s72 offen lds
	s_waitcnt vmcnt(8)
	s_waitcnt lgkmcnt(0)
	s_setprio 1
	s_barrier
	v_mfma_f32_16x16x32_bf16 v[142:145], v[106:109], v[162:165], v[142:145]
	v_mfma_f32_16x16x32_bf16 v[142:145], v[118:121], v[166:169], v[142:145]
	v_mfma_f32_16x16x32_bf16 v[134:137], v[130:133], v[162:165], v[134:137]
	v_mfma_f32_16x16x32_bf16 v[134:137], v[138:141], v[166:169], v[134:137]
	v_mfma_f32_16x16x32_bf16 v[114:117], v[106:109], v[170:173], v[114:117]
	v_mfma_f32_16x16x32_bf16 v[114:117], v[118:121], v[174:177], v[114:117]
	v_mfma_f32_16x16x32_bf16 v[110:113], v[130:133], v[170:173], v[110:113]
	v_mfma_f32_16x16x32_bf16 v[110:113], v[138:141], v[174:177], v[110:113]
	v_mfma_f32_16x16x32_bf16 v[94:97], v[106:109], v[178:181], v[94:97]
	v_mfma_f32_16x16x32_bf16 v[94:97], v[118:121], v[182:185], v[94:97]
	v_mfma_f32_16x16x32_bf16 v[90:93], v[130:133], v[178:181], v[90:93]
	v_mfma_f32_16x16x32_bf16 v[90:93], v[138:141], v[182:185], v[90:93]
	v_mfma_f32_16x16x32_bf16 v[78:81], v[106:109], v[190:193], v[78:81]
	v_mfma_f32_16x16x32_bf16 v[78:81], v[118:121], v[194:197], v[78:81]
	v_mfma_f32_16x16x32_bf16 v[74:77], v[130:133], v[190:193], v[74:77]
	v_mfma_f32_16x16x32_bf16 v[74:77], v[138:141], v[194:197], v[74:77]
	v_mfma_f32_16x16x32_bf16 v[126:129], v[146:149], v[162:165], v[126:129]
	v_mfma_f32_16x16x32_bf16 v[126:129], v[150:153], v[166:169], v[126:129]
	v_mfma_f32_16x16x32_bf16 v[122:125], v[154:157], v[162:165], v[122:125]
	v_mfma_f32_16x16x32_bf16 v[122:125], v[158:161], v[166:169], v[122:125]
	v_mfma_f32_16x16x32_bf16 v[102:105], v[146:149], v[170:173], v[102:105]
	v_mfma_f32_16x16x32_bf16 v[102:105], v[150:153], v[174:177], v[102:105]
	v_mfma_f32_16x16x32_bf16 v[98:101], v[154:157], v[170:173], v[98:101]
	v_mfma_f32_16x16x32_bf16 v[98:101], v[158:161], v[174:177], v[98:101]
	v_mfma_f32_16x16x32_bf16 v[86:89], v[146:149], v[178:181], v[86:89]
	v_mfma_f32_16x16x32_bf16 v[86:89], v[150:153], v[182:185], v[86:89]
	v_mfma_f32_16x16x32_bf16 v[82:85], v[154:157], v[178:181], v[82:85]
	v_mfma_f32_16x16x32_bf16 v[82:85], v[158:161], v[182:185], v[82:85]
	v_mfma_f32_16x16x32_bf16 v[70:73], v[146:149], v[190:193], v[70:73]
	v_mfma_f32_16x16x32_bf16 v[70:73], v[150:153], v[194:197], v[70:73]
	v_mfma_f32_16x16x32_bf16 v[66:69], v[154:157], v[190:193], v[66:69]
	v_mfma_f32_16x16x32_bf16 v[66:69], v[158:161], v[194:197], v[66:69]
	s_setprio 0
	s_barrier
	s_mov_b32 m0, s27
	s_mov_b32 s18, s14
	s_mov_b32 s19, s15
	ds_read_b128 v[162:165], v226 offset:16384
	ds_read_b128 v[166:169], v226 offset:17408
	ds_read_b128 v[170:173], v226 offset:18432
	ds_read_b128 v[174:177], v226 offset:19456
	ds_read_b128 v[178:181], v226 offset:20480
	ds_read_b128 v[182:185], v226 offset:21504
	ds_read_b128 v[190:193], v226 offset:22528
	ds_read_b128 v[194:197], v226 offset:23552
	buffer_load_dwordx4 v223, s[16:19], s77 offen lds
	s_add_i32 s78, s77, 0x80000
	s_mov_b32 m0, s30
	s_nop 0
	buffer_load_dwordx4 v223, s[16:19], s78 offen lds
	s_add_i32 s78, s77, 0x100000
	s_mov_b32 m0, s31
	s_nop 0
	buffer_load_dwordx4 v223, s[16:19], s78 offen lds
	s_add_i32 s78, s77, 0x180000
	s_mov_b32 m0, s41
	s_nop 0
	buffer_load_dwordx4 v223, s[16:19], s78 offen lds
	s_mov_b32 m0, s25
	s_add_i32 s78, s75, 0x80000
	buffer_load_dwordx4 v222, s[12:15], s75 offen lds
	s_mov_b32 m0, s42
	s_nop 0
	buffer_load_dwordx4 v222, s[12:15], s78 offen lds
	s_waitcnt vmcnt(8)
	s_waitcnt lgkmcnt(0)
	s_setprio 1
	s_barrier
	v_mfma_f32_16x16x32_bf16 v[62:65], v[106:109], v[162:165], v[62:65]
	v_mfma_f32_16x16x32_bf16 v[62:65], v[118:121], v[166:169], v[62:65]
	v_mfma_f32_16x16x32_bf16 v[58:61], v[130:133], v[162:165], v[58:61]
	v_mfma_f32_16x16x32_bf16 v[58:61], v[138:141], v[166:169], v[58:61]
	v_mfma_f32_16x16x32_bf16 v[46:49], v[106:109], v[170:173], v[46:49]
	v_mfma_f32_16x16x32_bf16 v[46:49], v[118:121], v[174:177], v[46:49]
	v_mfma_f32_16x16x32_bf16 v[42:45], v[130:133], v[170:173], v[42:45]
	v_mfma_f32_16x16x32_bf16 v[42:45], v[138:141], v[174:177], v[42:45]
	v_mfma_f32_16x16x32_bf16 v[30:33], v[106:109], v[178:181], v[30:33]
	v_mfma_f32_16x16x32_bf16 v[30:33], v[118:121], v[182:185], v[30:33]
	v_mfma_f32_16x16x32_bf16 v[26:29], v[130:133], v[178:181], v[26:29]
	v_mfma_f32_16x16x32_bf16 v[26:29], v[138:141], v[182:185], v[26:29]
	v_mfma_f32_16x16x32_bf16 v[14:17], v[106:109], v[190:193], v[14:17]
	v_mfma_f32_16x16x32_bf16 v[14:17], v[118:121], v[194:197], v[14:17]
	v_mfma_f32_16x16x32_bf16 v[10:13], v[130:133], v[190:193], v[10:13]
	v_mfma_f32_16x16x32_bf16 v[10:13], v[138:141], v[194:197], v[10:13]
	v_mfma_f32_16x16x32_bf16 v[54:57], v[146:149], v[162:165], v[54:57]
	v_mfma_f32_16x16x32_bf16 v[54:57], v[150:153], v[166:169], v[54:57]
	v_mfma_f32_16x16x32_bf16 v[50:53], v[154:157], v[162:165], v[50:53]
	v_mfma_f32_16x16x32_bf16 v[50:53], v[158:161], v[166:169], v[50:53]
	v_mfma_f32_16x16x32_bf16 v[38:41], v[146:149], v[170:173], v[38:41]
	v_mfma_f32_16x16x32_bf16 v[38:41], v[150:153], v[174:177], v[38:41]
	v_mfma_f32_16x16x32_bf16 v[34:37], v[154:157], v[170:173], v[34:37]
	v_mfma_f32_16x16x32_bf16 v[34:37], v[158:161], v[174:177], v[34:37]
	v_mfma_f32_16x16x32_bf16 v[22:25], v[146:149], v[178:181], v[22:25]
	v_mfma_f32_16x16x32_bf16 v[22:25], v[150:153], v[182:185], v[22:25]
	v_mfma_f32_16x16x32_bf16 v[18:21], v[154:157], v[178:181], v[18:21]
	v_mfma_f32_16x16x32_bf16 v[18:21], v[158:161], v[182:185], v[18:21]
	v_mfma_f32_16x16x32_bf16 v[6:9], v[146:149], v[190:193], v[6:9]
	v_mfma_f32_16x16x32_bf16 v[6:9], v[150:153], v[194:197], v[6:9]
	v_mfma_f32_16x16x32_bf16 v[2:5], v[154:157], v[190:193], v[2:5]
	v_mfma_f32_16x16x32_bf16 v[2:5], v[158:161], v[194:197], v[2:5]
	s_setprio 0
	s_barrier
	ds_read_b128 v[106:109], v227
	ds_read_b128 v[118:121], v227 offset:1024
	ds_read_b128 v[130:133], v227 offset:2048
	ds_read_b128 v[138:141], v227 offset:3072
	ds_read_b128 v[146:149], v228
	ds_read_b128 v[150:153], v228 offset:1024
	ds_read_b128 v[154:157], v228 offset:2048
	ds_read_b128 v[158:161], v228 offset:3072
	s_mov_b32 m0, s43
	s_add_i32 s78, s75, 0x100000
	ds_read_b128 v[162:165], v226 offset:32768
	ds_read_b128 v[166:169], v226 offset:33792
	ds_read_b128 v[170:173], v226 offset:34816
	ds_read_b128 v[174:177], v226 offset:35840
	ds_read_b128 v[178:181], v226 offset:36864
	ds_read_b128 v[182:185], v226 offset:37888
	ds_read_b128 v[190:193], v226 offset:38912
	ds_read_b128 v[194:197], v226 offset:39936
	buffer_load_dwordx4 v222, s[12:15], s78 offen lds
	s_add_i32 s78, s75, 0x180000
	s_mov_b32 m0, s44
	s_nop 0
	buffer_load_dwordx4 v222, s[12:15], s78 offen lds
	s_waitcnt vmcnt(8)
	s_waitcnt lgkmcnt(0)
	s_setprio 1
	s_barrier
	v_mfma_f32_16x16x32_bf16 v[142:145], v[106:109], v[162:165], v[142:145]
	v_mfma_f32_16x16x32_bf16 v[142:145], v[118:121], v[166:169], v[142:145]
	v_mfma_f32_16x16x32_bf16 v[134:137], v[130:133], v[162:165], v[134:137]
	v_mfma_f32_16x16x32_bf16 v[134:137], v[138:141], v[166:169], v[134:137]
	v_mfma_f32_16x16x32_bf16 v[114:117], v[106:109], v[170:173], v[114:117]
	v_mfma_f32_16x16x32_bf16 v[114:117], v[118:121], v[174:177], v[114:117]
	v_mfma_f32_16x16x32_bf16 v[110:113], v[130:133], v[170:173], v[110:113]
	v_mfma_f32_16x16x32_bf16 v[110:113], v[138:141], v[174:177], v[110:113]
	v_mfma_f32_16x16x32_bf16 v[94:97], v[106:109], v[178:181], v[94:97]
	v_mfma_f32_16x16x32_bf16 v[94:97], v[118:121], v[182:185], v[94:97]
	v_mfma_f32_16x16x32_bf16 v[90:93], v[130:133], v[178:181], v[90:93]
	v_mfma_f32_16x16x32_bf16 v[90:93], v[138:141], v[182:185], v[90:93]
	v_mfma_f32_16x16x32_bf16 v[78:81], v[106:109], v[190:193], v[78:81]
	v_mfma_f32_16x16x32_bf16 v[78:81], v[118:121], v[194:197], v[78:81]
	v_mfma_f32_16x16x32_bf16 v[74:77], v[130:133], v[190:193], v[74:77]
	v_mfma_f32_16x16x32_bf16 v[74:77], v[138:141], v[194:197], v[74:77]
	v_mfma_f32_16x16x32_bf16 v[126:129], v[146:149], v[162:165], v[126:129]
	v_mfma_f32_16x16x32_bf16 v[126:129], v[150:153], v[166:169], v[126:129]
	v_mfma_f32_16x16x32_bf16 v[122:125], v[154:157], v[162:165], v[122:125]
	v_mfma_f32_16x16x32_bf16 v[122:125], v[158:161], v[166:169], v[122:125]
	v_mfma_f32_16x16x32_bf16 v[102:105], v[146:149], v[170:173], v[102:105]
	v_mfma_f32_16x16x32_bf16 v[102:105], v[150:153], v[174:177], v[102:105]
	v_mfma_f32_16x16x32_bf16 v[98:101], v[154:157], v[170:173], v[98:101]
	v_mfma_f32_16x16x32_bf16 v[98:101], v[158:161], v[174:177], v[98:101]
	v_mfma_f32_16x16x32_bf16 v[86:89], v[146:149], v[178:181], v[86:89]
	v_mfma_f32_16x16x32_bf16 v[86:89], v[150:153], v[182:185], v[86:89]
	v_mfma_f32_16x16x32_bf16 v[82:85], v[154:157], v[178:181], v[82:85]
	v_mfma_f32_16x16x32_bf16 v[82:85], v[158:161], v[182:185], v[82:85]
	v_mfma_f32_16x16x32_bf16 v[70:73], v[146:149], v[190:193], v[70:73]
	v_mfma_f32_16x16x32_bf16 v[70:73], v[150:153], v[194:197], v[70:73]
	v_mfma_f32_16x16x32_bf16 v[66:69], v[154:157], v[190:193], v[66:69]
	v_mfma_f32_16x16x32_bf16 v[66:69], v[158:161], v[194:197], v[66:69]
	s_setprio 0
	s_barrier
	s_mov_b32 m0, s48
	s_or_b32 s78, s77, 0x80
	ds_read_b128 v[162:165], v226 offset:49152
	ds_read_b128 v[166:169], v226 offset:50176
	ds_read_b128 v[170:173], v226 offset:51200
	ds_read_b128 v[174:177], v226 offset:52224
	ds_read_b128 v[178:181], v226 offset:53248
	ds_read_b128 v[182:185], v226 offset:54272
	ds_read_b128 v[190:193], v226 offset:55296
	ds_read_b128 v[194:197], v226 offset:56320
	buffer_load_dwordx4 v223, s[16:19], s78 offen lds
	s_add_i32 s78, s77, 0x80080
	s_mov_b32 m0, s49
	s_add_i32 s75, s75, 0x80080
	buffer_load_dwordx4 v223, s[16:19], s78 offen lds
	s_add_i32 s78, s77, 0x100080
	s_mov_b32 m0, s52
	s_add_i32 s77, s77, 0x180080
	buffer_load_dwordx4 v223, s[16:19], s78 offen lds
	s_mov_b32 m0, s53
	s_nop 0
	buffer_load_dwordx4 v223, s[16:19], s77 offen lds
	s_mov_b32 m0, s50
	s_nop 0
	buffer_load_dwordx4 v222, s[12:15], s76 offen lds
	s_mov_b32 m0, s51
	s_nop 0
	buffer_load_dwordx4 v222, s[12:15], s75 offen lds
	s_waitcnt vmcnt(8)
	s_waitcnt lgkmcnt(0)
	s_setprio 1
	s_barrier
	v_mfma_f32_16x16x32_bf16 v[62:65], v[106:109], v[162:165], v[62:65]
	v_mfma_f32_16x16x32_bf16 v[62:65], v[118:121], v[166:169], v[62:65]
	v_mfma_f32_16x16x32_bf16 v[58:61], v[130:133], v[162:165], v[58:61]
	v_mfma_f32_16x16x32_bf16 v[58:61], v[138:141], v[166:169], v[58:61]
	v_mfma_f32_16x16x32_bf16 v[46:49], v[106:109], v[170:173], v[46:49]
	v_mfma_f32_16x16x32_bf16 v[46:49], v[118:121], v[174:177], v[46:49]
	v_mfma_f32_16x16x32_bf16 v[42:45], v[130:133], v[170:173], v[42:45]
	v_mfma_f32_16x16x32_bf16 v[42:45], v[138:141], v[174:177], v[42:45]
	v_mfma_f32_16x16x32_bf16 v[30:33], v[106:109], v[178:181], v[30:33]
	v_mfma_f32_16x16x32_bf16 v[30:33], v[118:121], v[182:185], v[30:33]
	v_mfma_f32_16x16x32_bf16 v[26:29], v[130:133], v[178:181], v[26:29]
	v_mfma_f32_16x16x32_bf16 v[26:29], v[138:141], v[182:185], v[26:29]
	v_mfma_f32_16x16x32_bf16 v[14:17], v[106:109], v[190:193], v[14:17]
	v_mfma_f32_16x16x32_bf16 v[14:17], v[118:121], v[194:197], v[14:17]
	v_mfma_f32_16x16x32_bf16 v[10:13], v[130:133], v[190:193], v[10:13]
	v_mfma_f32_16x16x32_bf16 v[10:13], v[138:141], v[194:197], v[10:13]
	v_mfma_f32_16x16x32_bf16 v[54:57], v[146:149], v[162:165], v[54:57]
	v_mfma_f32_16x16x32_bf16 v[54:57], v[150:153], v[166:169], v[54:57]
	v_mfma_f32_16x16x32_bf16 v[50:53], v[154:157], v[162:165], v[50:53]
	v_mfma_f32_16x16x32_bf16 v[50:53], v[158:161], v[166:169], v[50:53]
	v_mfma_f32_16x16x32_bf16 v[38:41], v[146:149], v[170:173], v[38:41]
	v_mfma_f32_16x16x32_bf16 v[38:41], v[150:153], v[174:177], v[38:41]
	v_mfma_f32_16x16x32_bf16 v[34:37], v[154:157], v[170:173], v[34:37]
	v_mfma_f32_16x16x32_bf16 v[34:37], v[158:161], v[174:177], v[34:37]
	v_mfma_f32_16x16x32_bf16 v[22:25], v[146:149], v[178:181], v[22:25]
	v_mfma_f32_16x16x32_bf16 v[22:25], v[150:153], v[182:185], v[22:25]
	v_mfma_f32_16x16x32_bf16 v[18:21], v[154:157], v[178:181], v[18:21]
	v_mfma_f32_16x16x32_bf16 v[18:21], v[158:161], v[182:185], v[18:21]
	v_mfma_f32_16x16x32_bf16 v[6:9], v[146:149], v[190:193], v[6:9]
	v_mfma_f32_16x16x32_bf16 v[6:9], v[150:153], v[194:197], v[6:9]
	v_mfma_f32_16x16x32_bf16 v[2:5], v[154:157], v[190:193], v[2:5]
	v_mfma_f32_16x16x32_bf16 v[2:5], v[158:161], v[194:197], v[2:5]
	s_setprio 0
	s_barrier
	s_add_i32 s74, s74, 2
	s_addk_i32 s72, 0x100
	s_addk_i32 s73, 0x100
	s_cmp_ge_i32 s74, s3
	s_cbranch_scc0 .LBB0_1290
	s_and_b64 vcc, exec, s[38:39]
	s_cbranch_vccz .LBB0_1293

.LBB0_1382:
	ds_read_b128 v[144:147], v138
	ds_read_b128 v[148:151], v138 offset:1024
	ds_read_b128 v[152:155], v138 offset:2048
	ds_read_b128 v[156:159], v138 offset:3072
	ds_read_b128 v[160:163], v139
	ds_read_b128 v[164:167], v139 offset:1024
	ds_read_b128 v[168:171], v139 offset:2048
	ds_read_b128 v[172:175], v139 offset:3072
	s_add_i32 s14, s74, 0xffe80080
	s_cmp_eq_u32 s61, s76
	s_cselect_b32 s77, s72, s14
	s_cselect_b32 s79, s73, s75
	s_or_b32 s78, s77, 0x80
	s_add_i32 s14, s74, 0xfff80000
	s_mov_b32 m0, s62
	ds_read_b128 v[176:179], v140
	ds_read_b128 v[180:183], v140 offset:1024
	ds_read_b128 v[184:187], v140 offset:2048
	ds_read_b128 v[188:191], v140 offset:3072
	ds_read_b128 v[192:195], v140 offset:4096
	ds_read_b128 v[196:199], v140 offset:5120
	ds_read_b128 v[200:203], v140 offset:6144
	ds_read_b128 v[204:207], v140 offset:7168
	buffer_load_dwordx4 v136, s[16:19], s14 offen lds
	s_mov_b32 m0, s63
	s_nop 0
	buffer_load_dwordx4 v136, s[16:19], s74 offen lds
	s_waitcnt vmcnt(8)
	s_waitcnt lgkmcnt(0)
	s_setprio 1
	s_barrier
	v_mfma_f32_16x16x32_bf16 v[118:121], v[144:147], v[176:179], v[118:121]
	v_mfma_f32_16x16x32_bf16 v[118:121], v[148:151], v[180:183], v[118:121]
	v_mfma_f32_16x16x32_bf16 v[114:117], v[152:155], v[176:179], v[114:117]
	v_mfma_f32_16x16x32_bf16 v[114:117], v[156:159], v[180:183], v[114:117]
	v_mfma_f32_16x16x32_bf16 v[110:113], v[144:147], v[184:187], v[110:113]
	v_mfma_f32_16x16x32_bf16 v[110:113], v[148:151], v[188:191], v[110:113]
	v_mfma_f32_16x16x32_bf16 v[102:105], v[152:155], v[184:187], v[102:105]
	v_mfma_f32_16x16x32_bf16 v[102:105], v[156:159], v[188:191], v[102:105]
	v_mfma_f32_16x16x32_bf16 v[94:97], v[144:147], v[192:195], v[94:97]
	v_mfma_f32_16x16x32_bf16 v[94:97], v[148:151], v[196:199], v[94:97]
	v_mfma_f32_16x16x32_bf16 v[86:89], v[152:155], v[192:195], v[86:89]
	v_mfma_f32_16x16x32_bf16 v[86:89], v[156:159], v[196:199], v[86:89]
	v_mfma_f32_16x16x32_bf16 v[78:81], v[144:147], v[200:203], v[78:81]
	v_mfma_f32_16x16x32_bf16 v[78:81], v[148:151], v[204:207], v[78:81]
	v_mfma_f32_16x16x32_bf16 v[66:69], v[152:155], v[200:203], v[66:69]
	v_mfma_f32_16x16x32_bf16 v[66:69], v[156:159], v[204:207], v[66:69]
	v_mfma_f32_16x16x32_bf16 v[126:129], v[160:163], v[176:179], v[126:129]
	v_mfma_f32_16x16x32_bf16 v[126:129], v[164:167], v[180:183], v[126:129]
	v_mfma_f32_16x16x32_bf16 v[122:125], v[168:171], v[176:179], v[122:125]
	v_mfma_f32_16x16x32_bf16 v[122:125], v[172:175], v[180:183], v[122:125]
	v_mfma_f32_16x16x32_bf16 v[106:109], v[160:163], v[184:187], v[106:109]
	v_mfma_f32_16x16x32_bf16 v[106:109], v[164:167], v[188:191], v[106:109]
	v_mfma_f32_16x16x32_bf16 v[98:101], v[168:171], v[184:187], v[98:101]
	v_mfma_f32_16x16x32_bf16 v[98:101], v[172:175], v[188:191], v[98:101]
	v_mfma_f32_16x16x32_bf16 v[90:93], v[160:163], v[192:195], v[90:93]
	v_mfma_f32_16x16x32_bf16 v[90:93], v[164:167], v[196:199], v[90:93]
	v_mfma_f32_16x16x32_bf16 v[82:85], v[168:171], v[192:195], v[82:85]
	v_mfma_f32_16x16x32_bf16 v[82:85], v[172:175], v[196:199], v[82:85]
	v_mfma_f32_16x16x32_bf16 v[74:77], v[160:163], v[200:203], v[74:77]
	v_mfma_f32_16x16x32_bf16 v[74:77], v[164:167], v[204:207], v[74:77]
	v_mfma_f32_16x16x32_bf16 v[70:73], v[168:171], v[200:203], v[70:73]
	v_mfma_f32_16x16x32_bf16 v[70:73], v[172:175], v[204:207], v[70:73]
	s_setprio 0
	s_barrier
	s_mov_b32 m0, s45
	s_mov_b32 s14, s18
	s_mov_b32 s15, s19
	ds_read_b128 v[176:179], v140 offset:16384
	ds_read_b128 v[180:183], v140 offset:17408
	ds_read_b128 v[184:187], v140 offset:18432
	ds_read_b128 v[188:191], v140 offset:19456
	ds_read_b128 v[192:195], v140 offset:20480
	ds_read_b128 v[196:199], v140 offset:21504
	ds_read_b128 v[200:203], v140 offset:22528
	ds_read_b128 v[204:207], v140 offset:23552
	buffer_load_dwordx4 v137, s[12:15], s79 offen lds
	s_add_i32 s80, s79, 0x80000
	s_mov_b32 m0, s46
	s_nop 0
	buffer_load_dwordx4 v137, s[12:15], s80 offen lds
	s_add_i32 s80, s79, 0x100000
	s_mov_b32 m0, s47
	s_nop 0
	buffer_load_dwordx4 v137, s[12:15], s80 offen lds
	s_add_i32 s80, s79, 0x180000
	s_mov_b32 m0, s48
	s_nop 0
	buffer_load_dwordx4 v137, s[12:15], s80 offen lds
	s_mov_b32 m0, s44
	s_add_i32 s80, s77, 0x80000
	buffer_load_dwordx4 v136, s[16:19], s77 offen lds
	s_mov_b32 m0, s49
	s_nop 0
	buffer_load_dwordx4 v136, s[16:19], s80 offen lds
	s_waitcnt vmcnt(8)
	s_waitcnt lgkmcnt(0)
	s_setprio 1
	s_barrier
	v_mfma_f32_16x16x32_bf16 v[62:65], v[144:147], v[176:179], v[62:65]
	v_mfma_f32_16x16x32_bf16 v[62:65], v[148:151], v[180:183], v[62:65]
	v_mfma_f32_16x16x32_bf16 v[54:57], v[152:155], v[176:179], v[54:57]
	v_mfma_f32_16x16x32_bf16 v[54:57], v[156:159], v[180:183], v[54:57]
	v_mfma_f32_16x16x32_bf16 v[46:49], v[144:147], v[184:187], v[46:49]
	v_mfma_f32_16x16x32_bf16 v[46:49], v[148:151], v[188:191], v[46:49]
	v_mfma_f32_16x16x32_bf16 v[38:41], v[152:155], v[184:187], v[38:41]
	v_mfma_f32_16x16x32_bf16 v[38:41], v[156:159], v[188:191], v[38:41]
	v_mfma_f32_16x16x32_bf16 v[30:33], v[144:147], v[192:195], v[30:33]
	v_mfma_f32_16x16x32_bf16 v[30:33], v[148:151], v[196:199], v[30:33]
	v_mfma_f32_16x16x32_bf16 v[22:25], v[152:155], v[192:195], v[22:25]
	v_mfma_f32_16x16x32_bf16 v[22:25], v[156:159], v[196:199], v[22:25]
	v_mfma_f32_16x16x32_bf16 v[14:17], v[144:147], v[200:203], v[14:17]
	v_mfma_f32_16x16x32_bf16 v[14:17], v[148:151], v[204:207], v[14:17]
	v_mfma_f32_16x16x32_bf16 v[6:9], v[152:155], v[200:203], v[6:9]
	v_mfma_f32_16x16x32_bf16 v[6:9], v[156:159], v[204:207], v[6:9]
	v_mfma_f32_16x16x32_bf16 v[58:61], v[160:163], v[176:179], v[58:61]
	v_mfma_f32_16x16x32_bf16 v[58:61], v[164:167], v[180:183], v[58:61]
	v_mfma_f32_16x16x32_bf16 v[50:53], v[168:171], v[176:179], v[50:53]
	v_mfma_f32_16x16x32_bf16 v[50:53], v[172:175], v[180:183], v[50:53]
	v_mfma_f32_16x16x32_bf16 v[42:45], v[160:163], v[184:187], v[42:45]
	v_mfma_f32_16x16x32_bf16 v[42:45], v[164:167], v[188:191], v[42:45]
	v_mfma_f32_16x16x32_bf16 v[34:37], v[168:171], v[184:187], v[34:37]
	v_mfma_f32_16x16x32_bf16 v[34:37], v[172:175], v[188:191], v[34:37]
	v_mfma_f32_16x16x32_bf16 v[26:29], v[160:163], v[192:195], v[26:29]
	v_mfma_f32_16x16x32_bf16 v[26:29], v[164:167], v[196:199], v[26:29]
	v_mfma_f32_16x16x32_bf16 v[18:21], v[168:171], v[192:195], v[18:21]
	v_mfma_f32_16x16x32_bf16 v[18:21], v[172:175], v[196:199], v[18:21]
	v_mfma_f32_16x16x32_bf16 v[10:13], v[160:163], v[200:203], v[10:13]
	v_mfma_f32_16x16x32_bf16 v[10:13], v[164:167], v[204:207], v[10:13]
	v_mfma_f32_16x16x32_bf16 v[2:5], v[168:171], v[200:203], v[2:5]
	v_mfma_f32_16x16x32_bf16 v[2:5], v[172:175], v[204:207], v[2:5]
	s_setprio 0
	s_barrier
	ds_read_b128 v[144:147], v141
	ds_read_b128 v[148:151], v141 offset:1024
	ds_read_b128 v[152:155], v141 offset:2048
	ds_read_b128 v[156:159], v141 offset:3072
	ds_read_b128 v[160:163], v142
	ds_read_b128 v[164:167], v142 offset:1024
	ds_read_b128 v[168:171], v142 offset:2048
	ds_read_b128 v[172:175], v142 offset:3072
	s_mov_b32 m0, s50
	s_add_i32 s80, s77, 0x100000
	ds_read_b128 v[176:179], v140 offset:32768
	ds_read_b128 v[180:183], v140 offset:33792
	ds_read_b128 v[184:187], v140 offset:34816
	ds_read_b128 v[188:191], v140 offset:35840
	ds_read_b128 v[192:195], v140 offset:36864
	ds_read_b128 v[196:199], v140 offset:37888
	ds_read_b128 v[200:203], v140 offset:38912
	ds_read_b128 v[204:207], v140 offset:39936
	buffer_load_dwordx4 v136, s[16:19], s80 offen lds
	s_add_i32 s80, s77, 0x180000
	s_mov_b32 m0, s51
	s_nop 0
	buffer_load_dwordx4 v136, s[16:19], s80 offen lds
	s_waitcnt vmcnt(8)
	s_waitcnt lgkmcnt(0)
	s_setprio 1
	s_barrier
	v_mfma_f32_16x16x32_bf16 v[118:121], v[144:147], v[176:179], v[118:121]
	v_mfma_f32_16x16x32_bf16 v[118:121], v[148:151], v[180:183], v[118:121]
	v_mfma_f32_16x16x32_bf16 v[114:117], v[152:155], v[176:179], v[114:117]
	v_mfma_f32_16x16x32_bf16 v[114:117], v[156:159], v[180:183], v[114:117]
	v_mfma_f32_16x16x32_bf16 v[110:113], v[144:147], v[184:187], v[110:113]
	v_mfma_f32_16x16x32_bf16 v[110:113], v[148:151], v[188:191], v[110:113]
	v_mfma_f32_16x16x32_bf16 v[102:105], v[152:155], v[184:187], v[102:105]
	v_mfma_f32_16x16x32_bf16 v[102:105], v[156:159], v[188:191], v[102:105]
	v_mfma_f32_16x16x32_bf16 v[94:97], v[144:147], v[192:195], v[94:97]
	v_mfma_f32_16x16x32_bf16 v[94:97], v[148:151], v[196:199], v[94:97]
	v_mfma_f32_16x16x32_bf16 v[86:89], v[152:155], v[192:195], v[86:89]
	v_mfma_f32_16x16x32_bf16 v[86:89], v[156:159], v[196:199], v[86:89]
	v_mfma_f32_16x16x32_bf16 v[78:81], v[144:147], v[200:203], v[78:81]
	v_mfma_f32_16x16x32_bf16 v[78:81], v[148:151], v[204:207], v[78:81]
	v_mfma_f32_16x16x32_bf16 v[66:69], v[152:155], v[200:203], v[66:69]
	v_mfma_f32_16x16x32_bf16 v[66:69], v[156:159], v[204:207], v[66:69]
	v_mfma_f32_16x16x32_bf16 v[126:129], v[160:163], v[176:179], v[126:129]
	v_mfma_f32_16x16x32_bf16 v[126:129], v[164:167], v[180:183], v[126:129]
	v_mfma_f32_16x16x32_bf16 v[122:125], v[168:171], v[176:179], v[122:125]
	v_mfma_f32_16x16x32_bf16 v[122:125], v[172:175], v[180:183], v[122:125]
	v_mfma_f32_16x16x32_bf16 v[106:109], v[160:163], v[184:187], v[106:109]
	v_mfma_f32_16x16x32_bf16 v[106:109], v[164:167], v[188:191], v[106:109]
	v_mfma_f32_16x16x32_bf16 v[98:101], v[168:171], v[184:187], v[98:101]
	v_mfma_f32_16x16x32_bf16 v[98:101], v[172:175], v[188:191], v[98:101]
	v_mfma_f32_16x16x32_bf16 v[90:93], v[160:163], v[192:195], v[90:93]
	v_mfma_f32_16x16x32_bf16 v[90:93], v[164:167], v[196:199], v[90:93]
	v_mfma_f32_16x16x32_bf16 v[82:85], v[168:171], v[192:195], v[82:85]
	v_mfma_f32_16x16x32_bf16 v[82:85], v[172:175], v[196:199], v[82:85]
	v_mfma_f32_16x16x32_bf16 v[74:77], v[160:163], v[200:203], v[74:77]
	v_mfma_f32_16x16x32_bf16 v[74:77], v[164:167], v[204:207], v[74:77]
	v_mfma_f32_16x16x32_bf16 v[70:73], v[168:171], v[200:203], v[70:73]
	v_mfma_f32_16x16x32_bf16 v[70:73], v[172:175], v[204:207], v[70:73]
	s_setprio 0
	s_barrier
	s_mov_b32 m0, s53
	s_or_b32 s80, s79, 0x80
	ds_read_b128 v[176:179], v140 offset:49152
	ds_read_b128 v[180:183], v140 offset:50176
	ds_read_b128 v[184:187], v140 offset:51200
	ds_read_b128 v[188:191], v140 offset:52224
	ds_read_b128 v[192:195], v140 offset:53248
	ds_read_b128 v[196:199], v140 offset:54272
	ds_read_b128 v[200:203], v140 offset:55296
	ds_read_b128 v[204:207], v140 offset:56320
	buffer_load_dwordx4 v137, s[12:15], s80 offen lds
	s_add_i32 s80, s79, 0x80080
	s_mov_b32 m0, s54
	s_add_i32 s77, s77, 0x80080
	buffer_load_dwordx4 v137, s[12:15], s80 offen lds
	s_add_i32 s80, s79, 0x100080
	s_mov_b32 m0, s57
	s_add_i32 s79, s79, 0x180080
	buffer_load_dwordx4 v137, s[12:15], s80 offen lds
	s_mov_b32 m0, s58
	s_nop 0
	buffer_load_dwordx4 v137, s[12:15], s79 offen lds
	s_mov_b32 m0, s55
	s_nop 0
	buffer_load_dwordx4 v136, s[16:19], s78 offen lds
	s_mov_b32 m0, s56
	s_nop 0
	buffer_load_dwordx4 v136, s[16:19], s77 offen lds
	s_waitcnt vmcnt(8)
	s_waitcnt lgkmcnt(0)
	s_setprio 1
	s_barrier
	v_mfma_f32_16x16x32_bf16 v[62:65], v[144:147], v[176:179], v[62:65]
	v_mfma_f32_16x16x32_bf16 v[62:65], v[148:151], v[180:183], v[62:65]
	v_mfma_f32_16x16x32_bf16 v[54:57], v[152:155], v[176:179], v[54:57]
	v_mfma_f32_16x16x32_bf16 v[54:57], v[156:159], v[180:183], v[54:57]
	v_mfma_f32_16x16x32_bf16 v[46:49], v[144:147], v[184:187], v[46:49]
	v_mfma_f32_16x16x32_bf16 v[46:49], v[148:151], v[188:191], v[46:49]
	v_mfma_f32_16x16x32_bf16 v[38:41], v[152:155], v[184:187], v[38:41]
	v_mfma_f32_16x16x32_bf16 v[38:41], v[156:159], v[188:191], v[38:41]
	v_mfma_f32_16x16x32_bf16 v[30:33], v[144:147], v[192:195], v[30:33]
	v_mfma_f32_16x16x32_bf16 v[30:33], v[148:151], v[196:199], v[30:33]
	v_mfma_f32_16x16x32_bf16 v[22:25], v[152:155], v[192:195], v[22:25]
	v_mfma_f32_16x16x32_bf16 v[22:25], v[156:159], v[196:199], v[22:25]
	v_mfma_f32_16x16x32_bf16 v[14:17], v[144:147], v[200:203], v[14:17]
	v_mfma_f32_16x16x32_bf16 v[14:17], v[148:151], v[204:207], v[14:17]
	v_mfma_f32_16x16x32_bf16 v[6:9], v[152:155], v[200:203], v[6:9]
	v_mfma_f32_16x16x32_bf16 v[6:9], v[156:159], v[204:207], v[6:9]
	v_mfma_f32_16x16x32_bf16 v[58:61], v[160:163], v[176:179], v[58:61]
	v_mfma_f32_16x16x32_bf16 v[58:61], v[164:167], v[180:183], v[58:61]
	v_mfma_f32_16x16x32_bf16 v[50:53], v[168:171], v[176:179], v[50:53]
	v_mfma_f32_16x16x32_bf16 v[50:53], v[172:175], v[180:183], v[50:53]
	v_mfma_f32_16x16x32_bf16 v[42:45], v[160:163], v[184:187], v[42:45]
	v_mfma_f32_16x16x32_bf16 v[42:45], v[164:167], v[188:191], v[42:45]
	v_mfma_f32_16x16x32_bf16 v[34:37], v[168:171], v[184:187], v[34:37]
	v_mfma_f32_16x16x32_bf16 v[34:37], v[172:175], v[188:191], v[34:37]
	v_mfma_f32_16x16x32_bf16 v[26:29], v[160:163], v[192:195], v[26:29]
	v_mfma_f32_16x16x32_bf16 v[26:29], v[164:167], v[196:199], v[26:29]
	v_mfma_f32_16x16x32_bf16 v[18:21], v[168:171], v[192:195], v[18:21]
	v_mfma_f32_16x16x32_bf16 v[18:21], v[172:175], v[196:199], v[18:21]
	v_mfma_f32_16x16x32_bf16 v[10:13], v[160:163], v[200:203], v[10:13]
	v_mfma_f32_16x16x32_bf16 v[10:13], v[164:167], v[204:207], v[10:13]
	v_mfma_f32_16x16x32_bf16 v[2:5], v[168:171], v[200:203], v[2:5]
	v_mfma_f32_16x16x32_bf16 v[2:5], v[172:175], v[204:207], v[2:5]
	s_setprio 0
	s_barrier
	s_add_i32 s76, s76, 2
	s_addk_i32 s74, 0x100
	s_addk_i32 s75, 0x100
	s_cmp_ge_i32 s76, s27
	s_cbranch_scc0 .LBB0_1382
	s_and_b64 vcc, exec, s[42:43]
	s_cbranch_vccz .LBB0_1385

.LBB0_1402:
	ds_read_b128 v[146:149], v138
	ds_read_b128 v[150:153], v138 offset:1024
	ds_read_b128 v[154:157], v138 offset:2048
	ds_read_b128 v[158:161], v138 offset:3072
	ds_read_b128 v[162:165], v139
	ds_read_b128 v[166:169], v139 offset:1024
	ds_read_b128 v[170:173], v139 offset:2048
	ds_read_b128 v[174:177], v139 offset:3072
	s_add_i32 s22, s75, 0xffe80080
	s_cmp_eq_u32 s62, s77
	s_cselect_b32 s78, s73, s22
	s_cselect_b32 s80, s74, s76
	s_or_b32 s79, s78, 0x80
	s_add_i32 s22, s75, 0xfff80000
	s_mov_b32 m0, s63
	ds_read_b128 v[178:181], v140
	ds_read_b128 v[182:185], v140 offset:1024
	ds_read_b128 v[186:189], v140 offset:2048
	ds_read_b128 v[190:193], v140 offset:3072
	ds_read_b128 v[194:197], v140 offset:4096
	ds_read_b128 v[198:201], v140 offset:5120
	ds_read_b128 v[202:205], v140 offset:6144
	ds_read_b128 v[206:209], v140 offset:7168
	buffer_load_dwordx4 v136, s[16:19], s22 offen lds
	s_mov_b32 m0, s64
	s_nop 0
	buffer_load_dwordx4 v136, s[16:19], s75 offen lds
	s_waitcnt vmcnt(8)
	s_waitcnt lgkmcnt(0)
	s_setprio 1
	s_barrier
	v_mfma_f32_16x16x32_bf16 v[118:121], v[146:149], v[178:181], v[118:121]
	v_mfma_f32_16x16x32_bf16 v[118:121], v[150:153], v[182:185], v[118:121]
	v_mfma_f32_16x16x32_bf16 v[114:117], v[154:157], v[178:181], v[114:117]
	v_mfma_f32_16x16x32_bf16 v[114:117], v[158:161], v[182:185], v[114:117]
	v_mfma_f32_16x16x32_bf16 v[110:113], v[146:149], v[186:189], v[110:113]
	v_mfma_f32_16x16x32_bf16 v[110:113], v[150:153], v[190:193], v[110:113]
	v_mfma_f32_16x16x32_bf16 v[102:105], v[154:157], v[186:189], v[102:105]
	v_mfma_f32_16x16x32_bf16 v[102:105], v[158:161], v[190:193], v[102:105]
	v_mfma_f32_16x16x32_bf16 v[94:97], v[146:149], v[194:197], v[94:97]
	v_mfma_f32_16x16x32_bf16 v[94:97], v[150:153], v[198:201], v[94:97]
	v_mfma_f32_16x16x32_bf16 v[86:89], v[154:157], v[194:197], v[86:89]
	v_mfma_f32_16x16x32_bf16 v[86:89], v[158:161], v[198:201], v[86:89]
	v_mfma_f32_16x16x32_bf16 v[78:81], v[146:149], v[202:205], v[78:81]
	v_mfma_f32_16x16x32_bf16 v[78:81], v[150:153], v[206:209], v[78:81]
	v_mfma_f32_16x16x32_bf16 v[66:69], v[154:157], v[202:205], v[66:69]
	v_mfma_f32_16x16x32_bf16 v[66:69], v[158:161], v[206:209], v[66:69]
	v_mfma_f32_16x16x32_bf16 v[126:129], v[162:165], v[178:181], v[126:129]
	v_mfma_f32_16x16x32_bf16 v[126:129], v[166:169], v[182:185], v[126:129]
	v_mfma_f32_16x16x32_bf16 v[122:125], v[170:173], v[178:181], v[122:125]
	v_mfma_f32_16x16x32_bf16 v[122:125], v[174:177], v[182:185], v[122:125]
	v_mfma_f32_16x16x32_bf16 v[106:109], v[162:165], v[186:189], v[106:109]
	v_mfma_f32_16x16x32_bf16 v[106:109], v[166:169], v[190:193], v[106:109]
	v_mfma_f32_16x16x32_bf16 v[98:101], v[170:173], v[186:189], v[98:101]
	v_mfma_f32_16x16x32_bf16 v[98:101], v[174:177], v[190:193], v[98:101]
	v_mfma_f32_16x16x32_bf16 v[90:93], v[162:165], v[194:197], v[90:93]
	v_mfma_f32_16x16x32_bf16 v[90:93], v[166:169], v[198:201], v[90:93]
	v_mfma_f32_16x16x32_bf16 v[82:85], v[170:173], v[194:197], v[82:85]
	v_mfma_f32_16x16x32_bf16 v[82:85], v[174:177], v[198:201], v[82:85]
	v_mfma_f32_16x16x32_bf16 v[74:77], v[162:165], v[202:205], v[74:77]
	v_mfma_f32_16x16x32_bf16 v[74:77], v[166:169], v[206:209], v[74:77]
	v_mfma_f32_16x16x32_bf16 v[70:73], v[170:173], v[202:205], v[70:73]
	v_mfma_f32_16x16x32_bf16 v[70:73], v[174:177], v[206:209], v[70:73]
	s_setprio 0
	s_barrier
	s_mov_b32 m0, s31
	s_mov_b32 s22, s18
	s_mov_b32 s23, s19
	ds_read_b128 v[178:181], v140 offset:16384
	ds_read_b128 v[182:185], v140 offset:17408
	ds_read_b128 v[186:189], v140 offset:18432
	ds_read_b128 v[190:193], v140 offset:19456
	ds_read_b128 v[194:197], v140 offset:20480
	ds_read_b128 v[198:201], v140 offset:21504
	ds_read_b128 v[202:205], v140 offset:22528
	ds_read_b128 v[206:209], v140 offset:23552
	buffer_load_dwordx4 v137, s[20:23], s80 offen lds
	s_add_i32 s81, s80, 0x80000
	s_mov_b32 m0, s48
	s_nop 0
	buffer_load_dwordx4 v137, s[20:23], s81 offen lds
	s_add_i32 s81, s80, 0x100000
	s_mov_b32 m0, s49
	s_nop 0
	buffer_load_dwordx4 v137, s[20:23], s81 offen lds
	s_add_i32 s81, s80, 0x180000
	s_mov_b32 m0, s50
	s_nop 0
	buffer_load_dwordx4 v137, s[20:23], s81 offen lds
	s_mov_b32 m0, s30
	s_add_i32 s81, s78, 0x80000
	buffer_load_dwordx4 v136, s[16:19], s78 offen lds
	s_mov_b32 m0, s51
	s_nop 0
	buffer_load_dwordx4 v136, s[16:19], s81 offen lds
	s_waitcnt vmcnt(8)
	s_waitcnt lgkmcnt(0)
	s_setprio 1
	s_barrier
	v_mfma_f32_16x16x32_bf16 v[62:65], v[146:149], v[178:181], v[62:65]
	v_mfma_f32_16x16x32_bf16 v[62:65], v[150:153], v[182:185], v[62:65]
	v_mfma_f32_16x16x32_bf16 v[54:57], v[154:157], v[178:181], v[54:57]
	v_mfma_f32_16x16x32_bf16 v[54:57], v[158:161], v[182:185], v[54:57]
	v_mfma_f32_16x16x32_bf16 v[46:49], v[146:149], v[186:189], v[46:49]
	v_mfma_f32_16x16x32_bf16 v[46:49], v[150:153], v[190:193], v[46:49]
	v_mfma_f32_16x16x32_bf16 v[38:41], v[154:157], v[186:189], v[38:41]
	v_mfma_f32_16x16x32_bf16 v[38:41], v[158:161], v[190:193], v[38:41]
	v_mfma_f32_16x16x32_bf16 v[30:33], v[146:149], v[194:197], v[30:33]
	v_mfma_f32_16x16x32_bf16 v[30:33], v[150:153], v[198:201], v[30:33]
	v_mfma_f32_16x16x32_bf16 v[22:25], v[154:157], v[194:197], v[22:25]
	v_mfma_f32_16x16x32_bf16 v[22:25], v[158:161], v[198:201], v[22:25]
	v_mfma_f32_16x16x32_bf16 v[14:17], v[146:149], v[202:205], v[14:17]
	v_mfma_f32_16x16x32_bf16 v[14:17], v[150:153], v[206:209], v[14:17]
	v_mfma_f32_16x16x32_bf16 v[6:9], v[154:157], v[202:205], v[6:9]
	v_mfma_f32_16x16x32_bf16 v[6:9], v[158:161], v[206:209], v[6:9]
	v_mfma_f32_16x16x32_bf16 v[58:61], v[162:165], v[178:181], v[58:61]
	v_mfma_f32_16x16x32_bf16 v[58:61], v[166:169], v[182:185], v[58:61]
	v_mfma_f32_16x16x32_bf16 v[50:53], v[170:173], v[178:181], v[50:53]
	v_mfma_f32_16x16x32_bf16 v[50:53], v[174:177], v[182:185], v[50:53]
	v_mfma_f32_16x16x32_bf16 v[42:45], v[162:165], v[186:189], v[42:45]
	v_mfma_f32_16x16x32_bf16 v[42:45], v[166:169], v[190:193], v[42:45]
	v_mfma_f32_16x16x32_bf16 v[34:37], v[170:173], v[186:189], v[34:37]
	v_mfma_f32_16x16x32_bf16 v[34:37], v[174:177], v[190:193], v[34:37]
	v_mfma_f32_16x16x32_bf16 v[26:29], v[162:165], v[194:197], v[26:29]
	v_mfma_f32_16x16x32_bf16 v[26:29], v[166:169], v[198:201], v[26:29]
	v_mfma_f32_16x16x32_bf16 v[18:21], v[170:173], v[194:197], v[18:21]
	v_mfma_f32_16x16x32_bf16 v[18:21], v[174:177], v[198:201], v[18:21]
	v_mfma_f32_16x16x32_bf16 v[10:13], v[162:165], v[202:205], v[10:13]
	v_mfma_f32_16x16x32_bf16 v[10:13], v[166:169], v[206:209], v[10:13]
	v_mfma_f32_16x16x32_bf16 v[2:5], v[170:173], v[202:205], v[2:5]
	v_mfma_f32_16x16x32_bf16 v[2:5], v[174:177], v[206:209], v[2:5]
	s_setprio 0
	s_barrier
	ds_read_b128 v[146:149], v141
	ds_read_b128 v[150:153], v141 offset:1024
	ds_read_b128 v[154:157], v141 offset:2048
	ds_read_b128 v[158:161], v141 offset:3072
	ds_read_b128 v[162:165], v142
	ds_read_b128 v[166:169], v142 offset:1024
	ds_read_b128 v[170:173], v142 offset:2048
	ds_read_b128 v[174:177], v142 offset:3072
	s_mov_b32 m0, s52
	s_add_i32 s81, s78, 0x100000
	ds_read_b128 v[178:181], v140 offset:32768
	ds_read_b128 v[182:185], v140 offset:33792
	ds_read_b128 v[186:189], v140 offset:34816
	ds_read_b128 v[190:193], v140 offset:35840
	ds_read_b128 v[194:197], v140 offset:36864
	ds_read_b128 v[198:201], v140 offset:37888
	ds_read_b128 v[202:205], v140 offset:38912
	ds_read_b128 v[206:209], v140 offset:39936
	buffer_load_dwordx4 v136, s[16:19], s81 offen lds
	s_add_i32 s81, s78, 0x180000
	s_mov_b32 m0, s53
	s_nop 0
	buffer_load_dwordx4 v136, s[16:19], s81 offen lds
	s_waitcnt vmcnt(8)
	s_waitcnt lgkmcnt(0)
	s_setprio 1
	s_barrier
	v_mfma_f32_16x16x32_bf16 v[118:121], v[146:149], v[178:181], v[118:121]
	v_mfma_f32_16x16x32_bf16 v[118:121], v[150:153], v[182:185], v[118:121]
	v_mfma_f32_16x16x32_bf16 v[114:117], v[154:157], v[178:181], v[114:117]
	v_mfma_f32_16x16x32_bf16 v[114:117], v[158:161], v[182:185], v[114:117]
	v_mfma_f32_16x16x32_bf16 v[110:113], v[146:149], v[186:189], v[110:113]
	v_mfma_f32_16x16x32_bf16 v[110:113], v[150:153], v[190:193], v[110:113]
	v_mfma_f32_16x16x32_bf16 v[102:105], v[154:157], v[186:189], v[102:105]
	v_mfma_f32_16x16x32_bf16 v[102:105], v[158:161], v[190:193], v[102:105]
	v_mfma_f32_16x16x32_bf16 v[94:97], v[146:149], v[194:197], v[94:97]
	v_mfma_f32_16x16x32_bf16 v[94:97], v[150:153], v[198:201], v[94:97]
	v_mfma_f32_16x16x32_bf16 v[86:89], v[154:157], v[194:197], v[86:89]
	v_mfma_f32_16x16x32_bf16 v[86:89], v[158:161], v[198:201], v[86:89]
	v_mfma_f32_16x16x32_bf16 v[78:81], v[146:149], v[202:205], v[78:81]
	v_mfma_f32_16x16x32_bf16 v[78:81], v[150:153], v[206:209], v[78:81]
	v_mfma_f32_16x16x32_bf16 v[66:69], v[154:157], v[202:205], v[66:69]
	v_mfma_f32_16x16x32_bf16 v[66:69], v[158:161], v[206:209], v[66:69]
	v_mfma_f32_16x16x32_bf16 v[126:129], v[162:165], v[178:181], v[126:129]
	v_mfma_f32_16x16x32_bf16 v[126:129], v[166:169], v[182:185], v[126:129]
	v_mfma_f32_16x16x32_bf16 v[122:125], v[170:173], v[178:181], v[122:125]
	v_mfma_f32_16x16x32_bf16 v[122:125], v[174:177], v[182:185], v[122:125]
	v_mfma_f32_16x16x32_bf16 v[106:109], v[162:165], v[186:189], v[106:109]
	v_mfma_f32_16x16x32_bf16 v[106:109], v[166:169], v[190:193], v[106:109]
	v_mfma_f32_16x16x32_bf16 v[98:101], v[170:173], v[186:189], v[98:101]
	v_mfma_f32_16x16x32_bf16 v[98:101], v[174:177], v[190:193], v[98:101]
	v_mfma_f32_16x16x32_bf16 v[90:93], v[162:165], v[194:197], v[90:93]
	v_mfma_f32_16x16x32_bf16 v[90:93], v[166:169], v[198:201], v[90:93]
	v_mfma_f32_16x16x32_bf16 v[82:85], v[170:173], v[194:197], v[82:85]
	v_mfma_f32_16x16x32_bf16 v[82:85], v[174:177], v[198:201], v[82:85]
	v_mfma_f32_16x16x32_bf16 v[74:77], v[162:165], v[202:205], v[74:77]
	v_mfma_f32_16x16x32_bf16 v[74:77], v[166:169], v[206:209], v[74:77]
	v_mfma_f32_16x16x32_bf16 v[70:73], v[170:173], v[202:205], v[70:73]
	v_mfma_f32_16x16x32_bf16 v[70:73], v[174:177], v[206:209], v[70:73]
	s_setprio 0
	s_barrier
	s_mov_b32 m0, s54
	s_or_b32 s81, s80, 0x80
	ds_read_b128 v[178:181], v140 offset:49152
	ds_read_b128 v[182:185], v140 offset:50176
	ds_read_b128 v[186:189], v140 offset:51200
	ds_read_b128 v[190:193], v140 offset:52224
	ds_read_b128 v[194:197], v140 offset:53248
	ds_read_b128 v[198:201], v140 offset:54272
	ds_read_b128 v[202:205], v140 offset:55296
	ds_read_b128 v[206:209], v140 offset:56320
	buffer_load_dwordx4 v137, s[20:23], s81 offen lds
	s_add_i32 s81, s80, 0x80080
	s_mov_b32 m0, s55
	s_add_i32 s78, s78, 0x80080
	buffer_load_dwordx4 v137, s[20:23], s81 offen lds
	s_add_i32 s81, s80, 0x100080
	s_mov_b32 m0, s58
	s_add_i32 s80, s80, 0x180080
	buffer_load_dwordx4 v137, s[20:23], s81 offen lds
	s_mov_b32 m0, s59
	s_nop 0
	buffer_load_dwordx4 v137, s[20:23], s80 offen lds
	s_mov_b32 m0, s56
	s_nop 0
	buffer_load_dwordx4 v136, s[16:19], s79 offen lds
	s_mov_b32 m0, s57
	s_nop 0
	buffer_load_dwordx4 v136, s[16:19], s78 offen lds
	s_waitcnt vmcnt(8)
	s_waitcnt lgkmcnt(0)
	s_setprio 1
	s_barrier
	v_mfma_f32_16x16x32_bf16 v[62:65], v[146:149], v[178:181], v[62:65]
	v_mfma_f32_16x16x32_bf16 v[62:65], v[150:153], v[182:185], v[62:65]
	v_mfma_f32_16x16x32_bf16 v[54:57], v[154:157], v[178:181], v[54:57]
	v_mfma_f32_16x16x32_bf16 v[54:57], v[158:161], v[182:185], v[54:57]
	v_mfma_f32_16x16x32_bf16 v[46:49], v[146:149], v[186:189], v[46:49]
	v_mfma_f32_16x16x32_bf16 v[46:49], v[150:153], v[190:193], v[46:49]
	v_mfma_f32_16x16x32_bf16 v[38:41], v[154:157], v[186:189], v[38:41]
	v_mfma_f32_16x16x32_bf16 v[38:41], v[158:161], v[190:193], v[38:41]
	v_mfma_f32_16x16x32_bf16 v[30:33], v[146:149], v[194:197], v[30:33]
	v_mfma_f32_16x16x32_bf16 v[30:33], v[150:153], v[198:201], v[30:33]
	v_mfma_f32_16x16x32_bf16 v[22:25], v[154:157], v[194:197], v[22:25]
	v_mfma_f32_16x16x32_bf16 v[22:25], v[158:161], v[198:201], v[22:25]
	v_mfma_f32_16x16x32_bf16 v[14:17], v[146:149], v[202:205], v[14:17]
	v_mfma_f32_16x16x32_bf16 v[14:17], v[150:153], v[206:209], v[14:17]
	v_mfma_f32_16x16x32_bf16 v[6:9], v[154:157], v[202:205], v[6:9]
	v_mfma_f32_16x16x32_bf16 v[6:9], v[158:161], v[206:209], v[6:9]
	v_mfma_f32_16x16x32_bf16 v[58:61], v[162:165], v[178:181], v[58:61]
	v_mfma_f32_16x16x32_bf16 v[58:61], v[166:169], v[182:185], v[58:61]
	v_mfma_f32_16x16x32_bf16 v[50:53], v[170:173], v[178:181], v[50:53]
	v_mfma_f32_16x16x32_bf16 v[50:53], v[174:177], v[182:185], v[50:53]
	v_mfma_f32_16x16x32_bf16 v[42:45], v[162:165], v[186:189], v[42:45]
	v_mfma_f32_16x16x32_bf16 v[42:45], v[166:169], v[190:193], v[42:45]
	v_mfma_f32_16x16x32_bf16 v[34:37], v[170:173], v[186:189], v[34:37]
	v_mfma_f32_16x16x32_bf16 v[34:37], v[174:177], v[190:193], v[34:37]
	v_mfma_f32_16x16x32_bf16 v[26:29], v[162:165], v[194:197], v[26:29]
	v_mfma_f32_16x16x32_bf16 v[26:29], v[166:169], v[198:201], v[26:29]
	v_mfma_f32_16x16x32_bf16 v[18:21], v[170:173], v[194:197], v[18:21]
	v_mfma_f32_16x16x32_bf16 v[18:21], v[174:177], v[198:201], v[18:21]
	v_mfma_f32_16x16x32_bf16 v[10:13], v[162:165], v[202:205], v[10:13]
	v_mfma_f32_16x16x32_bf16 v[10:13], v[166:169], v[206:209], v[10:13]
	v_mfma_f32_16x16x32_bf16 v[2:5], v[170:173], v[202:205], v[2:5]
	v_mfma_f32_16x16x32_bf16 v[2:5], v[174:177], v[206:209], v[2:5]
	s_setprio 0
	s_barrier
	s_add_i32 s77, s77, 2
	s_addk_i32 s75, 0x100
	s_addk_i32 s76, 0x100
	s_cmp_ge_i32 s77, s13
	s_cbranch_scc0 .LBB0_1402
	s_and_b64 vcc, exec, s[46:47]
	s_cbranch_vccz .LBB0_1405

.LBB0_1519:
	ds_read_b128 v[134:137], v208
	ds_read_b128 v[138:141], v208 offset:1024
	ds_read_b128 v[142:145], v208 offset:2048
	ds_read_b128 v[146:149], v208 offset:3072
	ds_read_b128 v[150:153], v209
	ds_read_b128 v[154:157], v209 offset:1024
	ds_read_b128 v[158:161], v209 offset:2048
	ds_read_b128 v[162:165], v209 offset:3072
	s_add_i32 s18, s80, 0xffbf8080
	s_cmp_eq_u32 s65, s82
	s_cselect_b32 s83, s6, s18
	s_cselect_b32 s85, s7, s81
	s_or_b32 s84, s83, 0x80
	s_add_i32 s18, s80, 0xffea8000
	s_mov_b32 m0, s66
	ds_read_b128 v[166:169], v210
	ds_read_b128 v[170:173], v210 offset:1024
	ds_read_b128 v[174:177], v210 offset:2048
	ds_read_b128 v[178:181], v210 offset:3072
	ds_read_b128 v[182:185], v210 offset:4096
	ds_read_b128 v[186:189], v210 offset:5120
	ds_read_b128 v[190:193], v210 offset:6144
	ds_read_b128 v[194:197], v210 offset:7168
	buffer_load_dwordx4 v206, s[12:15], s18 offen lds
	s_mov_b32 m0, s69
	s_nop 0
	buffer_load_dwordx4 v206, s[12:15], s80 offen lds
	s_waitcnt vmcnt(8)
	s_waitcnt lgkmcnt(0)
	s_setprio 1
	s_barrier
	v_mfma_f32_16x16x32_bf16 v[126:129], v[134:137], v[166:169], v[126:129]
	v_mfma_f32_16x16x32_bf16 v[126:129], v[138:141], v[170:173], v[126:129]
	v_mfma_f32_16x16x32_bf16 v[122:125], v[142:145], v[166:169], v[122:125]
	v_mfma_f32_16x16x32_bf16 v[122:125], v[146:149], v[170:173], v[122:125]
	v_mfma_f32_16x16x32_bf16 v[118:121], v[134:137], v[174:177], v[118:121]
	v_mfma_f32_16x16x32_bf16 v[118:121], v[138:141], v[178:181], v[118:121]
	v_mfma_f32_16x16x32_bf16 v[114:117], v[142:145], v[174:177], v[114:117]
	v_mfma_f32_16x16x32_bf16 v[114:117], v[146:149], v[178:181], v[114:117]
	v_mfma_f32_16x16x32_bf16 v[106:109], v[134:137], v[182:185], v[106:109]
	v_mfma_f32_16x16x32_bf16 v[106:109], v[138:141], v[186:189], v[106:109]
	v_mfma_f32_16x16x32_bf16 v[98:101], v[142:145], v[182:185], v[98:101]
	v_mfma_f32_16x16x32_bf16 v[98:101], v[146:149], v[186:189], v[98:101]
	v_mfma_f32_16x16x32_bf16 v[90:93], v[134:137], v[190:193], v[90:93]
	v_mfma_f32_16x16x32_bf16 v[90:93], v[138:141], v[194:197], v[90:93]
	v_mfma_f32_16x16x32_bf16 v[82:85], v[142:145], v[190:193], v[82:85]
	v_mfma_f32_16x16x32_bf16 v[82:85], v[146:149], v[194:197], v[82:85]
	v_mfma_f32_16x16x32_bf16 v[110:113], v[150:153], v[166:169], v[110:113]
	v_mfma_f32_16x16x32_bf16 v[110:113], v[154:157], v[170:173], v[110:113]
	v_mfma_f32_16x16x32_bf16 v[102:105], v[158:161], v[166:169], v[102:105]
	v_mfma_f32_16x16x32_bf16 v[102:105], v[162:165], v[170:173], v[102:105]
	v_mfma_f32_16x16x32_bf16 v[94:97], v[150:153], v[174:177], v[94:97]
	v_mfma_f32_16x16x32_bf16 v[94:97], v[154:157], v[178:181], v[94:97]
	v_mfma_f32_16x16x32_bf16 v[86:89], v[158:161], v[174:177], v[86:89]
	v_mfma_f32_16x16x32_bf16 v[86:89], v[162:165], v[178:181], v[86:89]
	v_mfma_f32_16x16x32_bf16 v[78:81], v[150:153], v[182:185], v[78:81]
	v_mfma_f32_16x16x32_bf16 v[78:81], v[154:157], v[186:189], v[78:81]
	v_mfma_f32_16x16x32_bf16 v[74:77], v[158:161], v[182:185], v[74:77]
	v_mfma_f32_16x16x32_bf16 v[74:77], v[162:165], v[186:189], v[74:77]
	v_mfma_f32_16x16x32_bf16 v[70:73], v[150:153], v[190:193], v[70:73]
	v_mfma_f32_16x16x32_bf16 v[70:73], v[154:157], v[194:197], v[70:73]
	v_mfma_f32_16x16x32_bf16 v[66:69], v[158:161], v[190:193], v[66:69]
	v_mfma_f32_16x16x32_bf16 v[66:69], v[162:165], v[194:197], v[66:69]
	s_setprio 0
	s_barrier
	s_mov_b32 m0, s27
	s_mov_b32 s18, s14
	s_mov_b32 s19, s15
	ds_read_b128 v[166:169], v210 offset:16384
	ds_read_b128 v[170:173], v210 offset:17408
	ds_read_b128 v[174:177], v210 offset:18432
	ds_read_b128 v[178:181], v210 offset:19456
	ds_read_b128 v[182:185], v210 offset:20480
	ds_read_b128 v[186:189], v210 offset:21504
	ds_read_b128 v[190:193], v210 offset:22528
	ds_read_b128 v[194:197], v210 offset:23552
	buffer_load_dwordx4 v207, s[16:19], s85 offen lds
	s_add_i32 s86, s85, 0x158000
	s_mov_b32 m0, s30
	s_nop 0
	buffer_load_dwordx4 v207, s[16:19], s86 offen lds
	s_add_i32 s86, s85, 0x2b0000
	s_mov_b32 m0, s31
	s_nop 0
	buffer_load_dwordx4 v207, s[16:19], s86 offen lds
	s_add_i32 s86, s85, 0x408000
	s_mov_b32 m0, s50
	s_nop 0
	buffer_load_dwordx4 v207, s[16:19], s86 offen lds
	s_mov_b32 m0, s25
	s_add_i32 s86, s83, 0x158000
	buffer_load_dwordx4 v206, s[12:15], s83 offen lds
	s_mov_b32 m0, s51
	s_nop 0
	buffer_load_dwordx4 v206, s[12:15], s86 offen lds
	s_waitcnt vmcnt(8)
	s_waitcnt lgkmcnt(0)
	s_setprio 1
	s_barrier
	v_mfma_f32_16x16x32_bf16 v[62:65], v[134:137], v[166:169], v[62:65]
	v_mfma_f32_16x16x32_bf16 v[62:65], v[138:141], v[170:173], v[62:65]
	v_mfma_f32_16x16x32_bf16 v[58:61], v[142:145], v[166:169], v[58:61]
	v_mfma_f32_16x16x32_bf16 v[58:61], v[146:149], v[170:173], v[58:61]
	v_mfma_f32_16x16x32_bf16 v[54:57], v[134:137], v[174:177], v[54:57]
	v_mfma_f32_16x16x32_bf16 v[54:57], v[138:141], v[178:181], v[54:57]
	v_mfma_f32_16x16x32_bf16 v[50:53], v[142:145], v[174:177], v[50:53]
	v_mfma_f32_16x16x32_bf16 v[50:53], v[146:149], v[178:181], v[50:53]
	v_mfma_f32_16x16x32_bf16 v[42:45], v[134:137], v[182:185], v[42:45]
	v_mfma_f32_16x16x32_bf16 v[42:45], v[138:141], v[186:189], v[42:45]
	v_mfma_f32_16x16x32_bf16 v[34:37], v[142:145], v[182:185], v[34:37]
	v_mfma_f32_16x16x32_bf16 v[34:37], v[146:149], v[186:189], v[34:37]
	v_mfma_f32_16x16x32_bf16 v[26:29], v[134:137], v[190:193], v[26:29]
	v_mfma_f32_16x16x32_bf16 v[26:29], v[138:141], v[194:197], v[26:29]
	v_mfma_f32_16x16x32_bf16 v[18:21], v[142:145], v[190:193], v[18:21]
	v_mfma_f32_16x16x32_bf16 v[18:21], v[146:149], v[194:197], v[18:21]
	v_mfma_f32_16x16x32_bf16 v[46:49], v[150:153], v[166:169], v[46:49]
	v_mfma_f32_16x16x32_bf16 v[46:49], v[154:157], v[170:173], v[46:49]
	v_mfma_f32_16x16x32_bf16 v[38:41], v[158:161], v[166:169], v[38:41]
	v_mfma_f32_16x16x32_bf16 v[38:41], v[162:165], v[170:173], v[38:41]
	v_mfma_f32_16x16x32_bf16 v[30:33], v[150:153], v[174:177], v[30:33]
	v_mfma_f32_16x16x32_bf16 v[30:33], v[154:157], v[178:181], v[30:33]
	v_mfma_f32_16x16x32_bf16 v[22:25], v[158:161], v[174:177], v[22:25]
	v_mfma_f32_16x16x32_bf16 v[22:25], v[162:165], v[178:181], v[22:25]
	v_mfma_f32_16x16x32_bf16 v[14:17], v[150:153], v[182:185], v[14:17]
	v_mfma_f32_16x16x32_bf16 v[14:17], v[154:157], v[186:189], v[14:17]
	v_mfma_f32_16x16x32_bf16 v[10:13], v[158:161], v[182:185], v[10:13]
	v_mfma_f32_16x16x32_bf16 v[10:13], v[162:165], v[186:189], v[10:13]
	v_mfma_f32_16x16x32_bf16 v[6:9], v[150:153], v[190:193], v[6:9]
	v_mfma_f32_16x16x32_bf16 v[6:9], v[154:157], v[194:197], v[6:9]
	v_mfma_f32_16x16x32_bf16 v[2:5], v[158:161], v[190:193], v[2:5]
	v_mfma_f32_16x16x32_bf16 v[2:5], v[162:165], v[194:197], v[2:5]
	s_setprio 0
	s_barrier
	ds_read_b128 v[134:137], v211
	ds_read_b128 v[138:141], v211 offset:1024
	ds_read_b128 v[142:145], v211 offset:2048
	ds_read_b128 v[146:149], v211 offset:3072
	ds_read_b128 v[150:153], v212
	ds_read_b128 v[154:157], v212 offset:1024
	ds_read_b128 v[158:161], v212 offset:2048
	ds_read_b128 v[162:165], v212 offset:3072
	s_mov_b32 m0, s52
	s_add_i32 s86, s83, 0x2b0000
	ds_read_b128 v[166:169], v210 offset:32768
	ds_read_b128 v[170:173], v210 offset:33792
	ds_read_b128 v[174:177], v210 offset:34816
	ds_read_b128 v[178:181], v210 offset:35840
	ds_read_b128 v[182:185], v210 offset:36864
	ds_read_b128 v[186:189], v210 offset:37888
	ds_read_b128 v[190:193], v210 offset:38912
	ds_read_b128 v[194:197], v210 offset:39936
	buffer_load_dwordx4 v206, s[12:15], s86 offen lds
	s_add_i32 s86, s83, 0x408000
	s_mov_b32 m0, s53
	s_nop 0
	buffer_load_dwordx4 v206, s[12:15], s86 offen lds
	s_waitcnt vmcnt(8)
	s_waitcnt lgkmcnt(0)
	s_setprio 1
	s_barrier
	v_mfma_f32_16x16x32_bf16 v[126:129], v[134:137], v[166:169], v[126:129]
	v_mfma_f32_16x16x32_bf16 v[126:129], v[138:141], v[170:173], v[126:129]
	v_mfma_f32_16x16x32_bf16 v[122:125], v[142:145], v[166:169], v[122:125]
	v_mfma_f32_16x16x32_bf16 v[122:125], v[146:149], v[170:173], v[122:125]
	v_mfma_f32_16x16x32_bf16 v[118:121], v[134:137], v[174:177], v[118:121]
	v_mfma_f32_16x16x32_bf16 v[118:121], v[138:141], v[178:181], v[118:121]
	v_mfma_f32_16x16x32_bf16 v[114:117], v[142:145], v[174:177], v[114:117]
	v_mfma_f32_16x16x32_bf16 v[114:117], v[146:149], v[178:181], v[114:117]
	v_mfma_f32_16x16x32_bf16 v[106:109], v[134:137], v[182:185], v[106:109]
	v_mfma_f32_16x16x32_bf16 v[106:109], v[138:141], v[186:189], v[106:109]
	v_mfma_f32_16x16x32_bf16 v[98:101], v[142:145], v[182:185], v[98:101]
	v_mfma_f32_16x16x32_bf16 v[98:101], v[146:149], v[186:189], v[98:101]
	v_mfma_f32_16x16x32_bf16 v[90:93], v[134:137], v[190:193], v[90:93]
	v_mfma_f32_16x16x32_bf16 v[90:93], v[138:141], v[194:197], v[90:93]
	v_mfma_f32_16x16x32_bf16 v[82:85], v[142:145], v[190:193], v[82:85]
	v_mfma_f32_16x16x32_bf16 v[82:85], v[146:149], v[194:197], v[82:85]
	v_mfma_f32_16x16x32_bf16 v[110:113], v[150:153], v[166:169], v[110:113]
	v_mfma_f32_16x16x32_bf16 v[110:113], v[154:157], v[170:173], v[110:113]
	v_mfma_f32_16x16x32_bf16 v[102:105], v[158:161], v[166:169], v[102:105]
	v_mfma_f32_16x16x32_bf16 v[102:105], v[162:165], v[170:173], v[102:105]
	v_mfma_f32_16x16x32_bf16 v[94:97], v[150:153], v[174:177], v[94:97]
	v_mfma_f32_16x16x32_bf16 v[94:97], v[154:157], v[178:181], v[94:97]
	v_mfma_f32_16x16x32_bf16 v[86:89], v[158:161], v[174:177], v[86:89]
	v_mfma_f32_16x16x32_bf16 v[86:89], v[162:165], v[178:181], v[86:89]
	v_mfma_f32_16x16x32_bf16 v[78:81], v[150:153], v[182:185], v[78:81]
	v_mfma_f32_16x16x32_bf16 v[78:81], v[154:157], v[186:189], v[78:81]
	v_mfma_f32_16x16x32_bf16 v[74:77], v[158:161], v[182:185], v[74:77]
	v_mfma_f32_16x16x32_bf16 v[74:77], v[162:165], v[186:189], v[74:77]
	v_mfma_f32_16x16x32_bf16 v[70:73], v[150:153], v[190:193], v[70:73]
	v_mfma_f32_16x16x32_bf16 v[70:73], v[154:157], v[194:197], v[70:73]
	v_mfma_f32_16x16x32_bf16 v[66:69], v[158:161], v[190:193], v[66:69]
	v_mfma_f32_16x16x32_bf16 v[66:69], v[162:165], v[194:197], v[66:69]
	s_setprio 0
	s_barrier
	s_mov_b32 m0, s57
	s_or_b32 s86, s85, 0x80
	ds_read_b128 v[166:169], v210 offset:49152
	ds_read_b128 v[170:173], v210 offset:50176
	ds_read_b128 v[174:177], v210 offset:51200
	ds_read_b128 v[178:181], v210 offset:52224
	ds_read_b128 v[182:185], v210 offset:53248
	ds_read_b128 v[186:189], v210 offset:54272
	ds_read_b128 v[190:193], v210 offset:55296
	ds_read_b128 v[194:197], v210 offset:56320
	buffer_load_dwordx4 v207, s[16:19], s86 offen lds
	s_add_i32 s86, s85, 0x158080
	s_mov_b32 m0, s58
	s_add_i32 s83, s83, 0x158080
	buffer_load_dwordx4 v207, s[16:19], s86 offen lds
	s_add_i32 s86, s85, 0x2b0080
	s_mov_b32 m0, s61
	s_add_i32 s85, s85, 0x408080
	buffer_load_dwordx4 v207, s[16:19], s86 offen lds
	s_mov_b32 m0, s62
	s_nop 0
	buffer_load_dwordx4 v207, s[16:19], s85 offen lds
	s_mov_b32 m0, s59
	s_nop 0
	buffer_load_dwordx4 v206, s[12:15], s84 offen lds
	s_mov_b32 m0, s60
	s_nop 0
	buffer_load_dwordx4 v206, s[12:15], s83 offen lds
	s_waitcnt vmcnt(8)
	s_waitcnt lgkmcnt(0)
	s_setprio 1
	s_barrier
	v_mfma_f32_16x16x32_bf16 v[62:65], v[134:137], v[166:169], v[62:65]
	v_mfma_f32_16x16x32_bf16 v[62:65], v[138:141], v[170:173], v[62:65]
	v_mfma_f32_16x16x32_bf16 v[58:61], v[142:145], v[166:169], v[58:61]
	v_mfma_f32_16x16x32_bf16 v[58:61], v[146:149], v[170:173], v[58:61]
	v_mfma_f32_16x16x32_bf16 v[54:57], v[134:137], v[174:177], v[54:57]
	v_mfma_f32_16x16x32_bf16 v[54:57], v[138:141], v[178:181], v[54:57]
	v_mfma_f32_16x16x32_bf16 v[50:53], v[142:145], v[174:177], v[50:53]
	v_mfma_f32_16x16x32_bf16 v[50:53], v[146:149], v[178:181], v[50:53]
	v_mfma_f32_16x16x32_bf16 v[42:45], v[134:137], v[182:185], v[42:45]
	v_mfma_f32_16x16x32_bf16 v[42:45], v[138:141], v[186:189], v[42:45]
	v_mfma_f32_16x16x32_bf16 v[34:37], v[142:145], v[182:185], v[34:37]
	v_mfma_f32_16x16x32_bf16 v[34:37], v[146:149], v[186:189], v[34:37]
	v_mfma_f32_16x16x32_bf16 v[26:29], v[134:137], v[190:193], v[26:29]
	v_mfma_f32_16x16x32_bf16 v[26:29], v[138:141], v[194:197], v[26:29]
	v_mfma_f32_16x16x32_bf16 v[18:21], v[142:145], v[190:193], v[18:21]
	v_mfma_f32_16x16x32_bf16 v[18:21], v[146:149], v[194:197], v[18:21]
	v_mfma_f32_16x16x32_bf16 v[46:49], v[150:153], v[166:169], v[46:49]
	v_mfma_f32_16x16x32_bf16 v[46:49], v[154:157], v[170:173], v[46:49]
	v_mfma_f32_16x16x32_bf16 v[38:41], v[158:161], v[166:169], v[38:41]
	v_mfma_f32_16x16x32_bf16 v[38:41], v[162:165], v[170:173], v[38:41]
	v_mfma_f32_16x16x32_bf16 v[30:33], v[150:153], v[174:177], v[30:33]
	v_mfma_f32_16x16x32_bf16 v[30:33], v[154:157], v[178:181], v[30:33]
	v_mfma_f32_16x16x32_bf16 v[22:25], v[158:161], v[174:177], v[22:25]
	v_mfma_f32_16x16x32_bf16 v[22:25], v[162:165], v[178:181], v[22:25]
	v_mfma_f32_16x16x32_bf16 v[14:17], v[150:153], v[182:185], v[14:17]
	v_mfma_f32_16x16x32_bf16 v[14:17], v[154:157], v[186:189], v[14:17]
	v_mfma_f32_16x16x32_bf16 v[10:13], v[158:161], v[182:185], v[10:13]
	v_mfma_f32_16x16x32_bf16 v[10:13], v[162:165], v[186:189], v[10:13]
	v_mfma_f32_16x16x32_bf16 v[6:9], v[150:153], v[190:193], v[6:9]
	v_mfma_f32_16x16x32_bf16 v[6:9], v[154:157], v[194:197], v[6:9]
	v_mfma_f32_16x16x32_bf16 v[2:5], v[158:161], v[190:193], v[2:5]
	v_mfma_f32_16x16x32_bf16 v[2:5], v[162:165], v[194:197], v[2:5]
	s_setprio 0
	s_barrier
	s_add_i32 s82, s82, 2
	s_addk_i32 s80, 0x100
	s_addk_i32 s81, 0x100
	s_cmp_ge_i32 s82, s3
	s_cbranch_scc0 .LBB0_1519
	v_pk_mul_f32 v[182:183], v[128:129], 0.5 op_sel_hi:[1,0]
	v_pk_mul_f32 v[184:185], v[126:127], 0.5 op_sel_hi:[1,0]
	v_pk_mul_f32 v[186:187], v[124:125], 0.5 op_sel_hi:[1,0]
	v_pk_mul_f32 v[188:189], v[122:123], 0.5 op_sel_hi:[1,0]
	v_pk_mul_f32 v[196:197], v[112:113], 0.5 op_sel_hi:[1,0]
	v_pk_mul_f32 v[194:195], v[110:111], 0.5 op_sel_hi:[1,0]
	v_pk_mul_f32 v[192:193], v[104:105], 0.5 op_sel_hi:[1,0]
	v_pk_mul_f32 v[190:191], v[102:103], 0.5 op_sel_hi:[1,0]
	v_pk_mul_f32 v[180:181], v[120:121], 0.5 op_sel_hi:[1,0]
	v_pk_mul_f32 v[178:179], v[118:119], 0.5 op_sel_hi:[1,0]
	v_pk_mul_f32 v[176:177], v[116:117], 0.5 op_sel_hi:[1,0]
	v_pk_mul_f32 v[174:175], v[114:115], 0.5 op_sel_hi:[1,0]
	v_pk_mul_f32 v[170:171], v[96:97], 0.5 op_sel_hi:[1,0]
	v_pk_mul_f32 v[168:169], v[94:95], 0.5 op_sel_hi:[1,0]
	v_pk_mul_f32 v[166:167], v[88:89], 0.5 op_sel_hi:[1,0]
	v_pk_mul_f32 v[164:165], v[86:87], 0.5 op_sel_hi:[1,0]
	v_pk_mul_f32 v[162:163], v[108:109], 0.5 op_sel_hi:[1,0]
	v_pk_mul_f32 v[160:161], v[106:107], 0.5 op_sel_hi:[1,0]
	v_pk_mul_f32 v[158:159], v[100:101], 0.5 op_sel_hi:[1,0]
	v_pk_mul_f32 v[156:157], v[98:99], 0.5 op_sel_hi:[1,0]
	v_pk_mul_f32 v[154:155], v[80:81], 0.5 op_sel_hi:[1,0]
	v_pk_mul_f32 v[152:153], v[78:79], 0.5 op_sel_hi:[1,0]
	v_pk_mul_f32 v[150:151], v[76:77], 0.5 op_sel_hi:[1,0]
	v_pk_mul_f32 v[148:149], v[74:75], 0.5 op_sel_hi:[1,0]
	v_pk_mul_f32 v[144:145], v[92:93], 0.5 op_sel_hi:[1,0]
	v_pk_mul_f32 v[142:143], v[90:91], 0.5 op_sel_hi:[1,0]
	v_pk_mul_f32 v[140:141], v[84:85], 0.5 op_sel_hi:[1,0]
	v_pk_mul_f32 v[138:139], v[82:83], 0.5 op_sel_hi:[1,0]
	v_pk_mul_f32 v[136:137], v[72:73], 0.5 op_sel_hi:[1,0]
	v_pk_mul_f32 v[134:135], v[70:71], 0.5 op_sel_hi:[1,0]
	v_pk_mul_f32 v[128:129], v[68:69], 0.5 op_sel_hi:[1,0]
	v_pk_mul_f32 v[126:127], v[66:67], 0.5 op_sel_hi:[1,0]
	v_pk_mul_f32 v[122:123], v[64:65], 0.5 op_sel_hi:[1,0]
	v_pk_mul_f32 v[120:121], v[62:63], 0.5 op_sel_hi:[1,0]
	v_pk_mul_f32 v[118:119], v[60:61], 0.5 op_sel_hi:[1,0]
	v_pk_mul_f32 v[116:117], v[58:59], 0.5 op_sel_hi:[1,0]
	v_pk_mul_f32 v[112:113], v[48:49], 0.5 op_sel_hi:[1,0]
	v_pk_mul_f32 v[110:111], v[46:47], 0.5 op_sel_hi:[1,0]
	v_pk_mul_f32 v[108:109], v[40:41], 0.5 op_sel_hi:[1,0]
	v_pk_mul_f32 v[106:107], v[38:39], 0.5 op_sel_hi:[1,0]
	v_pk_mul_f32 v[104:105], v[56:57], 0.5 op_sel_hi:[1,0]
	v_pk_mul_f32 v[102:103], v[54:55], 0.5 op_sel_hi:[1,0]
	v_pk_mul_f32 v[100:101], v[52:53], 0.5 op_sel_hi:[1,0]
	v_pk_mul_f32 v[98:99], v[50:51], 0.5 op_sel_hi:[1,0]
	v_pk_mul_f32 v[96:97], v[32:33], 0.5 op_sel_hi:[1,0]
	v_pk_mul_f32 v[94:95], v[30:31], 0.5 op_sel_hi:[1,0]
	v_pk_mul_f32 v[92:93], v[24:25], 0.5 op_sel_hi:[1,0]
	v_pk_mul_f32 v[90:91], v[22:23], 0.5 op_sel_hi:[1,0]
	v_pk_mul_f32 v[88:89], v[44:45], 0.5 op_sel_hi:[1,0]
	v_pk_mul_f32 v[86:87], v[42:43], 0.5 op_sel_hi:[1,0]
	v_pk_mul_f32 v[84:85], v[36:37], 0.5 op_sel_hi:[1,0]
	v_pk_mul_f32 v[82:83], v[34:35], 0.5 op_sel_hi:[1,0]
	v_pk_mul_f32 v[80:81], v[16:17], 0.5 op_sel_hi:[1,0]
	v_pk_mul_f32 v[78:79], v[14:15], 0.5 op_sel_hi:[1,0]
	v_pk_mul_f32 v[76:77], v[12:13], 0.5 op_sel_hi:[1,0]
	v_pk_mul_f32 v[74:75], v[10:11], 0.5 op_sel_hi:[1,0]
	v_pk_mul_f32 v[72:73], v[28:29], 0.5 op_sel_hi:[1,0]
	v_pk_mul_f32 v[70:71], v[26:27], 0.5 op_sel_hi:[1,0]
	v_pk_mul_f32 v[68:69], v[20:21], 0.5 op_sel_hi:[1,0]
	v_pk_mul_f32 v[66:67], v[18:19], 0.5 op_sel_hi:[1,0]
	v_pk_mul_f32 v[64:65], v[8:9], 0.5 op_sel_hi:[1,0]
	v_pk_mul_f32 v[62:63], v[6:7], 0.5 op_sel_hi:[1,0]
	v_pk_mul_f32 v[60:61], v[4:5], 0.5 op_sel_hi:[1,0]
	v_pk_mul_f32 v[58:59], v[2:3], 0.5 op_sel_hi:[1,0]
	s_and_b64 vcc, exec, s[40:41]
	s_cbranch_vccz .LBB0_1522
